# K-loops: the back-to-back s_setprio 0 / s_setprio 1 pair in the middle of each 32-MFMA block deleted (priority stays raised through the block)
# baseline (speedup 1.0000x reference)
; #define PG8_STAGE(bufoff, gbase, voff) do { _Pragma("unroll") for (int _i = 0; _i < 2; ++_i) \
;         __builtin_amdgcn_global_load_lds((const unsigned*)((const char*)(gbase) + (voff)[_i]), (LAS unsigned*)(lds + (bufoff) + ldsw + _i * 8192), 16, 0, 0); } while (0)
; #define PG8_LDA(dst, b, h) do { _Pragma("unroll") for (int m = 0; m < 4; ++m) _Pragma("unroll") for (int k = 0; k < 2; ++k) dst[m][k] = *(const LAS bf16x8*)(lds + PG8_SA(b, h) + aoff + m * 2048 + k * 1024); } while (0)
; #define PG8_LDB(dst, b, h) do { _Pragma("unroll") for (int n = 0; n < 2; ++n) _Pragma("unroll") for (int k = 0; k < 2; ++k) dst[n][k] = *(const LAS bf16x8*)(lds + PG8_SB(b, h) + boff + n * 2048 + k * 1024); } while (0)
; #define PG8_MMA(ai, bj, At, Bt) do { __builtin_amdgcn_s_setprio(1); _Pragma("unroll") for (int m = 0; m < 4; ++m) _Pragma("unroll") for (int n = 0; n < 2; ++n) _Pragma("unroll") for (int k = 0; k < 2; ++k) \
;         acc[ai][bj][m][n] = __builtin_amdgcn_mfma_f32_16x16x32_bf16(Bt[n][k], At[m][k], acc[ai][bj][m][n], 0, 0, 0); __builtin_amdgcn_s_setprio(0); } while (0)
; #define PG8_WAIT_V(n) asm volatile("s_waitcnt vmcnt(" #n ")" ::: "memory")
; #define PG8_WAIT_L(n) asm volatile("s_waitcnt lgkmcnt(" #n ")" ::: "memory")
; #define PG8_BAR __builtin_amdgcn_s_barrier()
; #define PG8_SCHED __builtin_amdgcn_sched_barrier(0)
;     ...
;             PG8_LDB(B0, 0, 0); PG8_LDB(B1, 0, 1); PG8_SCHED; PG8_LDA(At, 0, 0); PG8_STAGE(PG8_SA(1, 1), a1 + hstepA, voffA);
;             PG8_WAIT_V(8); PG8_WAIT_L(0); PG8_BAR; PG8_MMA(0, 0, At, B0); PG8_MMA(0, 1, At, B1); PG8_BAR; PG8_SCHED;
;             PG8_LDA(At, 0, 1); PG8_STAGE(PG8_SB(0, 0), b2, voffB); PG8_STAGE(PG8_SB(0, 1), b2 + hstepB, voffB); PG8_STAGE(PG8_SA(0, 0), a2, voffA);
;             PG8_WAIT_V(8); PG8_WAIT_L(0); PG8_BAR; PG8_MMA(1, 0, At, B0); PG8_MMA(1, 1, At, B1); PG8_BAR; PG8_SCHED;
.LBB0_84:
	s_add_i32 s52, s8, 2
	s_add_u32 s4, s0, 0x100
	s_addc_u32 s5, s1, 0
	s_add_i32 s53, 0, 0x10000
	s_cmp_eq_u32 s44, s8
	s_cselect_b32 s9, s7, s5
	s_cselect_b32 s8, s6, s4
	v_add_u32_e32 v142, s53, v158
	s_cselect_b32 s55, s3, s15
	s_cselect_b32 s54, s2, s14
	s_add_i32 s56, 0, 0x14000
	ds_read_b128 v[160:163], v142
	ds_read_b128 v[164:167], v142 offset:1024
	ds_read_b128 v[168:171], v142 offset:2048
	ds_read_b128 v[172:175], v142 offset:3072
	v_add_u32_e32 v142, s56, v158
	ds_read_b128 v[176:179], v142
	ds_read_b128 v[180:183], v142 offset:1024
	ds_read_b128 v[184:187], v142 offset:2048
	ds_read_b128 v[188:191], v142 offset:3072
	v_lshl_add_u64 v[142:143], s[0:1], 0, v[138:139]
	s_add_i32 m0, s29, 0xc000
	ds_read_b128 v[192:195], v159
	ds_read_b128 v[196:199], v159 offset:1024
	ds_read_b128 v[200:203], v159 offset:2048
	ds_read_b128 v[204:207], v159 offset:3072
	ds_read_b128 v[208:211], v159 offset:4096
	ds_read_b128 v[212:215], v159 offset:5120
	ds_read_b128 v[216:219], v159 offset:6144
	ds_read_b128 v[228:231], v159 offset:7168
	global_load_lds_dwordx4 v[142:143], off
	v_lshl_add_u64 v[142:143], s[0:1], 0, v[140:141]
	s_add_i32 m0, s29, 0xe000
	s_nop 0
	global_load_lds_dwordx4 v[142:143], off
	s_waitcnt vmcnt(8)
	s_waitcnt lgkmcnt(0)
	s_barrier
	s_setprio 1
	s_waitcnt lgkmcnt(0)
	v_mfma_f32_16x16x32_bf16 v[124:127], v[160:163], v[192:195], v[124:127]
	v_mfma_f32_16x16x32_bf16 v[120:123], v[168:171], v[192:195], v[120:123]
	v_mfma_f32_16x16x32_bf16 v[108:111], v[160:163], v[200:203], v[108:111]
	v_mfma_f32_16x16x32_bf16 v[104:107], v[168:171], v[200:203], v[104:107]
	v_mfma_f32_16x16x32_bf16 v[92:95], v[160:163], v[208:211], v[92:95]
	v_mfma_f32_16x16x32_bf16 v[88:91], v[168:171], v[208:211], v[88:91]
	v_mfma_f32_16x16x32_bf16 v[76:79], v[160:163], v[216:219], v[76:79]
	v_mfma_f32_16x16x32_bf16 v[72:75], v[168:171], v[216:219], v[72:75]
	v_mfma_f32_16x16x32_bf16 v[124:127], v[164:167], v[196:199], v[124:127]
	v_mfma_f32_16x16x32_bf16 v[120:123], v[172:175], v[196:199], v[120:123]
	v_mfma_f32_16x16x32_bf16 v[108:111], v[164:167], v[204:207], v[108:111]
	v_mfma_f32_16x16x32_bf16 v[104:107], v[172:175], v[204:207], v[104:107]
	v_mfma_f32_16x16x32_bf16 v[92:95], v[164:167], v[212:215], v[92:95]
	v_mfma_f32_16x16x32_bf16 v[88:91], v[172:175], v[212:215], v[88:91]
	v_mfma_f32_16x16x32_bf16 v[76:79], v[164:167], v[228:231], v[76:79]
	v_mfma_f32_16x16x32_bf16 v[72:75], v[172:175], v[228:231], v[72:75]
	v_mfma_f32_16x16x32_bf16 v[116:119], v[176:179], v[192:195], v[116:119]
	v_mfma_f32_16x16x32_bf16 v[112:115], v[184:187], v[192:195], v[112:115]
	v_mfma_f32_16x16x32_bf16 v[100:103], v[176:179], v[200:203], v[100:103]
	v_mfma_f32_16x16x32_bf16 v[96:99], v[184:187], v[200:203], v[96:99]
	v_mfma_f32_16x16x32_bf16 v[84:87], v[176:179], v[208:211], v[84:87]
	v_mfma_f32_16x16x32_bf16 v[80:83], v[184:187], v[208:211], v[80:83]
	v_mfma_f32_16x16x32_bf16 v[68:71], v[176:179], v[216:219], v[68:71]
	v_mfma_f32_16x16x32_bf16 v[64:67], v[184:187], v[216:219], v[64:67]
	v_mfma_f32_16x16x32_bf16 v[116:119], v[180:183], v[196:199], v[116:119]
	v_mfma_f32_16x16x32_bf16 v[112:115], v[188:191], v[196:199], v[112:115]
	v_mfma_f32_16x16x32_bf16 v[100:103], v[180:183], v[204:207], v[100:103]
	v_mfma_f32_16x16x32_bf16 v[96:99], v[188:191], v[204:207], v[96:99]
	v_mfma_f32_16x16x32_bf16 v[84:87], v[180:183], v[212:215], v[84:87]
	v_mfma_f32_16x16x32_bf16 v[80:83], v[188:191], v[212:215], v[80:83]
	v_mfma_f32_16x16x32_bf16 v[68:71], v[180:183], v[228:231], v[68:71]
	v_mfma_f32_16x16x32_bf16 v[64:67], v[188:191], v[228:231], v[64:67]
	s_setprio 0
	s_barrier
	s_add_i32 s0, s53, s28
	v_lshl_add_u64 v[142:143], s[54:55], 0, v[130:131]
	s_mov_b32 m0, s0
	ds_read_b128 v[192:195], v159 offset:16384
	ds_read_b128 v[196:199], v159 offset:17408
	ds_read_b128 v[200:203], v159 offset:18432
	ds_read_b128 v[204:207], v159 offset:19456
	ds_read_b128 v[208:211], v159 offset:20480
	ds_read_b128 v[212:215], v159 offset:21504
	ds_read_b128 v[216:219], v159 offset:22528
	ds_read_b128 v[228:231], v159 offset:23552
	global_load_lds_dwordx4 v[142:143], off
	s_add_i32 m0, s0, 0x2000
	s_add_u32 s0, s54, s16
	v_lshl_add_u64 v[152:153], s[54:55], 0, v[134:135]
	s_addc_u32 s1, s55, s17
	s_add_i32 s53, s56, s28
	global_load_lds_dwordx4 v[152:153], off
	v_lshl_add_u64 v[156:157], s[0:1], 0, v[130:131]
	s_mov_b32 m0, s53
	v_lshl_add_u64 v[232:233], s[0:1], 0, v[134:135]
	global_load_lds_dwordx4 v[156:157], off
	s_add_i32 m0, s53, 0x2000
	v_lshl_add_u64 v[234:235], s[8:9], 0, v[128:129]
	global_load_lds_dwordx4 v[232:233], off
	s_mov_b32 m0, s29
	v_lshl_add_u64 v[236:237], s[8:9], 0, v[132:133]
	global_load_lds_dwordx4 v[234:235], off
	s_mov_b32 m0, s30
	s_nop 0
	global_load_lds_dwordx4 v[236:237], off
	s_waitcnt vmcnt(8)
	s_waitcnt lgkmcnt(0)
	s_barrier
; #define PG8_STAGE(bufoff, gbase, voff) do { _Pragma("unroll") for (int _i = 0; _i < 2; ++_i) \
;         __builtin_amdgcn_global_load_lds((const unsigned*)((const char*)(gbase) + (voff)[_i]), (LAS unsigned*)(lds + (bufoff) + ldsw + _i * 8192), 16, 0, 0); } while (0)
; #define PG8_LDA(dst, b, h) do { _Pragma("unroll") for (int m = 0; m < 4; ++m) _Pragma("unroll") for (int k = 0; k < 2; ++k) dst[m][k] = *(const LAS bf16x8*)(lds + PG8_SA(b, h) + aoff + m * 2048 + k * 1024); } while (0)
; #define PG8_LDB(dst, b, h) do { _Pragma("unroll") for (int n = 0; n < 2; ++n) _Pragma("unroll") for (int k = 0; k < 2; ++k) dst[n][k] = *(const LAS bf16x8*)(lds + PG8_SB(b, h) + boff + n * 2048 + k * 1024); } while (0)
; #define PG8_MMA(ai, bj, At, Bt) do { __builtin_amdgcn_s_setprio(1); _Pragma("unroll") for (int m = 0; m < 4; ++m) _Pragma("unroll") for (int n = 0; n < 2; ++n) _Pragma("unroll") for (int k = 0; k < 2; ++k) \
;         acc[ai][bj][m][n] = __builtin_amdgcn_mfma_f32_16x16x32_bf16(Bt[n][k], At[m][k], acc[ai][bj][m][n], 0, 0, 0); __builtin_amdgcn_s_setprio(0); } while (0)
; #define PG8_WAIT_V(n) asm volatile("s_waitcnt vmcnt(" #n ")" ::: "memory")
; #define PG8_WAIT_L(n) asm volatile("s_waitcnt lgkmcnt(" #n ")" ::: "memory")
; #define PG8_BAR __builtin_amdgcn_s_barrier()
; #define PG8_SCHED __builtin_amdgcn_sched_barrier(0)
;     ...
;             PG8_WAIT_V(8); PG8_WAIT_L(0); PG8_BAR; PG8_MMA(1, 0, At, B0); PG8_MMA(1, 1, At, B1); PG8_BAR; PG8_SCHED;
;             PG8_LDB(B0, 1, 0); PG8_LDB(B1, 1, 1); PG8_SCHED; PG8_LDA(At, 1, 0); PG8_STAGE(PG8_SA(0, 1), a2 + hstepA, voffA);
;             PG8_WAIT_V(8); PG8_WAIT_L(0); PG8_BAR; PG8_MMA(0, 0, At, B0); PG8_MMA(0, 1, At, B1); PG8_BAR; PG8_SCHED;
	s_setprio 1
	s_waitcnt lgkmcnt(0)
	v_mfma_f32_16x16x32_bf16 v[60:63], v[160:163], v[192:195], v[60:63]
	v_mfma_f32_16x16x32_bf16 v[56:59], v[168:171], v[192:195], v[56:59]
	v_mfma_f32_16x16x32_bf16 v[44:47], v[160:163], v[200:203], v[44:47]
	v_mfma_f32_16x16x32_bf16 v[40:43], v[168:171], v[200:203], v[40:43]
	v_mfma_f32_16x16x32_bf16 v[28:31], v[160:163], v[208:211], v[28:31]
	v_mfma_f32_16x16x32_bf16 v[24:27], v[168:171], v[208:211], v[24:27]
	v_mfma_f32_16x16x32_bf16 v[12:15], v[160:163], v[216:219], v[12:15]
	v_mfma_f32_16x16x32_bf16 v[8:11], v[168:171], v[216:219], v[8:11]
	v_mfma_f32_16x16x32_bf16 v[60:63], v[164:167], v[196:199], v[60:63]
	v_mfma_f32_16x16x32_bf16 v[56:59], v[172:175], v[196:199], v[56:59]
	v_mfma_f32_16x16x32_bf16 v[44:47], v[164:167], v[204:207], v[44:47]
	v_mfma_f32_16x16x32_bf16 v[40:43], v[172:175], v[204:207], v[40:43]
	v_mfma_f32_16x16x32_bf16 v[28:31], v[164:167], v[212:215], v[28:31]
	v_mfma_f32_16x16x32_bf16 v[24:27], v[172:175], v[212:215], v[24:27]
	v_mfma_f32_16x16x32_bf16 v[12:15], v[164:167], v[228:231], v[12:15]
	v_mfma_f32_16x16x32_bf16 v[8:11], v[172:175], v[228:231], v[8:11]
	v_mfma_f32_16x16x32_bf16 v[52:55], v[176:179], v[192:195], v[52:55]
	v_mfma_f32_16x16x32_bf16 v[48:51], v[184:187], v[192:195], v[48:51]
	v_mfma_f32_16x16x32_bf16 v[36:39], v[176:179], v[200:203], v[36:39]
	v_mfma_f32_16x16x32_bf16 v[32:35], v[184:187], v[200:203], v[32:35]
	v_mfma_f32_16x16x32_bf16 v[20:23], v[176:179], v[208:211], v[20:23]
	v_mfma_f32_16x16x32_bf16 v[16:19], v[184:187], v[208:211], v[16:19]
	v_mfma_f32_16x16x32_bf16 v[4:7], v[176:179], v[216:219], v[4:7]
	v_mfma_f32_16x16x32_bf16 v[0:3], v[184:187], v[216:219], v[0:3]
	v_mfma_f32_16x16x32_bf16 v[52:55], v[180:183], v[196:199], v[52:55]
	v_mfma_f32_16x16x32_bf16 v[48:51], v[188:191], v[196:199], v[48:51]
	v_mfma_f32_16x16x32_bf16 v[36:39], v[180:183], v[204:207], v[36:39]
	v_mfma_f32_16x16x32_bf16 v[32:35], v[188:191], v[204:207], v[32:35]
	v_mfma_f32_16x16x32_bf16 v[20:23], v[180:183], v[212:215], v[20:23]
	v_mfma_f32_16x16x32_bf16 v[16:19], v[188:191], v[212:215], v[16:19]
	v_mfma_f32_16x16x32_bf16 v[4:7], v[180:183], v[228:231], v[4:7]
	v_mfma_f32_16x16x32_bf16 v[0:3], v[188:191], v[228:231], v[0:3]
	s_setprio 0
	s_barrier
	s_add_i32 s53, 0, 0x18000
	v_add_u32_e32 v146, s53, v158
	s_add_i32 s54, 0, 0x1c000
	ds_read_b128 v[160:163], v146
	ds_read_b128 v[164:167], v146 offset:1024
	ds_read_b128 v[168:171], v146 offset:2048
	ds_read_b128 v[172:175], v146 offset:3072
	v_add_u32_e32 v146, s54, v158
	ds_read_b128 v[176:179], v146
	ds_read_b128 v[180:183], v146 offset:1024
	ds_read_b128 v[184:187], v146 offset:2048
	ds_read_b128 v[188:191], v146 offset:3072
	s_add_u32 s0, s8, 0xb0000
	s_addc_u32 s1, s9, 0
	s_mov_b32 m0, s31
	v_lshl_add_u64 v[238:239], s[0:1], 0, v[128:129]
	ds_read_b128 v[192:195], v159 offset:32768
	ds_read_b128 v[196:199], v159 offset:33792
	ds_read_b128 v[200:203], v159 offset:34816
	ds_read_b128 v[204:207], v159 offset:35840
	ds_read_b128 v[208:211], v159 offset:36864
	ds_read_b128 v[212:215], v159 offset:37888
	ds_read_b128 v[216:219], v159 offset:38912
	ds_read_b128 v[228:231], v159 offset:39936
	global_load_lds_dwordx4 v[238:239], off
	v_lshl_add_u64 v[238:239], s[0:1], 0, v[132:133]
	s_mov_b32 m0, s34
	s_nop 0
	global_load_lds_dwordx4 v[238:239], off
	s_waitcnt vmcnt(8)
	s_waitcnt lgkmcnt(0)
	s_barrier
	s_setprio 1
	s_waitcnt lgkmcnt(0)
	v_mfma_f32_16x16x32_bf16 v[124:127], v[160:163], v[192:195], v[124:127]
	v_mfma_f32_16x16x32_bf16 v[120:123], v[168:171], v[192:195], v[120:123]
	v_mfma_f32_16x16x32_bf16 v[108:111], v[160:163], v[200:203], v[108:111]
	v_mfma_f32_16x16x32_bf16 v[104:107], v[168:171], v[200:203], v[104:107]
	v_mfma_f32_16x16x32_bf16 v[92:95], v[160:163], v[208:211], v[92:95]
	v_mfma_f32_16x16x32_bf16 v[88:91], v[168:171], v[208:211], v[88:91]
	v_mfma_f32_16x16x32_bf16 v[76:79], v[160:163], v[216:219], v[76:79]
	v_mfma_f32_16x16x32_bf16 v[72:75], v[168:171], v[216:219], v[72:75]
	v_mfma_f32_16x16x32_bf16 v[124:127], v[164:167], v[196:199], v[124:127]
	v_mfma_f32_16x16x32_bf16 v[120:123], v[172:175], v[196:199], v[120:123]
	v_mfma_f32_16x16x32_bf16 v[108:111], v[164:167], v[204:207], v[108:111]
	v_mfma_f32_16x16x32_bf16 v[104:107], v[172:175], v[204:207], v[104:107]
	v_mfma_f32_16x16x32_bf16 v[92:95], v[164:167], v[212:215], v[92:95]
	v_mfma_f32_16x16x32_bf16 v[88:91], v[172:175], v[212:215], v[88:91]
	v_mfma_f32_16x16x32_bf16 v[76:79], v[164:167], v[228:231], v[76:79]
	v_mfma_f32_16x16x32_bf16 v[72:75], v[172:175], v[228:231], v[72:75]
	v_mfma_f32_16x16x32_bf16 v[116:119], v[176:179], v[192:195], v[116:119]
	v_mfma_f32_16x16x32_bf16 v[112:115], v[184:187], v[192:195], v[112:115]
	v_mfma_f32_16x16x32_bf16 v[100:103], v[176:179], v[200:203], v[100:103]
	v_mfma_f32_16x16x32_bf16 v[96:99], v[184:187], v[200:203], v[96:99]
	v_mfma_f32_16x16x32_bf16 v[84:87], v[176:179], v[208:211], v[84:87]
	v_mfma_f32_16x16x32_bf16 v[80:83], v[184:187], v[208:211], v[80:83]
	v_mfma_f32_16x16x32_bf16 v[68:71], v[176:179], v[216:219], v[68:71]
	v_mfma_f32_16x16x32_bf16 v[64:67], v[184:187], v[216:219], v[64:67]
	v_mfma_f32_16x16x32_bf16 v[116:119], v[180:183], v[196:199], v[116:119]
	v_mfma_f32_16x16x32_bf16 v[112:115], v[188:191], v[196:199], v[112:115]
	v_mfma_f32_16x16x32_bf16 v[100:103], v[180:183], v[204:207], v[100:103]
	v_mfma_f32_16x16x32_bf16 v[96:99], v[188:191], v[204:207], v[96:99]
	v_mfma_f32_16x16x32_bf16 v[84:87], v[180:183], v[212:215], v[84:87]
	v_mfma_f32_16x16x32_bf16 v[80:83], v[188:191], v[212:215], v[80:83]
	v_mfma_f32_16x16x32_bf16 v[68:71], v[180:183], v[228:231], v[68:71]
	v_mfma_f32_16x16x32_bf16 v[64:67], v[188:191], v[228:231], v[64:67]
	s_setprio 0
	s_barrier
; #define PG8_STAGE(bufoff, gbase, voff) do { _Pragma("unroll") for (int _i = 0; _i < 2; ++_i) \
;         __builtin_amdgcn_global_load_lds((const unsigned*)((const char*)(gbase) + (voff)[_i]), (LAS unsigned*)(lds + (bufoff) + ldsw + _i * 8192), 16, 0, 0); } while (0)
; #define PG8_LDA(dst, b, h) do { _Pragma("unroll") for (int m = 0; m < 4; ++m) _Pragma("unroll") for (int k = 0; k < 2; ++k) dst[m][k] = *(const LAS bf16x8*)(lds + PG8_SA(b, h) + aoff + m * 2048 + k * 1024); } while (0)
; #define PG8_MMA(ai, bj, At, Bt) do { __builtin_amdgcn_s_setprio(1); _Pragma("unroll") for (int m = 0; m < 4; ++m) _Pragma("unroll") for (int n = 0; n < 2; ++n) _Pragma("unroll") for (int k = 0; k < 2; ++k) \
;         acc[ai][bj][m][n] = __builtin_amdgcn_mfma_f32_16x16x32_bf16(Bt[n][k], At[m][k], acc[ai][bj][m][n], 0, 0, 0); __builtin_amdgcn_s_setprio(0); } while (0)
; #define PG8_WAIT_V(n) asm volatile("s_waitcnt vmcnt(" #n ")" ::: "memory")
; #define PG8_WAIT_L(n) asm volatile("s_waitcnt lgkmcnt(" #n ")" ::: "memory")
; #define PG8_BAR __builtin_amdgcn_s_barrier()
; #define PG8_SCHED __builtin_amdgcn_sched_barrier(0)
;     ...
;         for (int t = 0; t < nt; t += 2) {
;     ...
;             PG8_LDA(At, 1, 1); PG8_STAGE(PG8_SB(1, 0), b3, voffB); PG8_STAGE(PG8_SB(1, 1), b3 + hstepB, voffB); PG8_STAGE(PG8_SA(1, 0), a3, voffA);
;             PG8_WAIT_V(8); PG8_WAIT_L(0); PG8_BAR; PG8_MMA(1, 0, At, B0); PG8_MMA(1, 1, At, B1); PG8_BAR; PG8_SCHED;
	s_add_i32 s0, s53, s28
	v_lshl_add_u64 v[142:143], v[142:143], 0, s[58:59]
	s_mov_b32 m0, s0
	ds_read_b128 v[192:195], v159 offset:49152
	ds_read_b128 v[196:199], v159 offset:50176
	ds_read_b128 v[200:203], v159 offset:51200
	ds_read_b128 v[204:207], v159 offset:52224
	ds_read_b128 v[208:211], v159 offset:53248
	ds_read_b128 v[212:215], v159 offset:54272
	ds_read_b128 v[216:219], v159 offset:55296
	ds_read_b128 v[228:231], v159 offset:56320
	global_load_lds_dwordx4 v[142:143], off
	v_lshl_add_u64 v[142:143], v[152:153], 0, s[58:59]
	s_add_i32 m0, s0, 0x2000
	s_add_i32 s0, s54, s28
	global_load_lds_dwordx4 v[142:143], off
	v_lshl_add_u64 v[142:143], v[156:157], 0, s[58:59]
	s_mov_b32 m0, s0
	s_nop 0
	global_load_lds_dwordx4 v[142:143], off
	v_lshl_add_u64 v[142:143], v[232:233], 0, s[58:59]
	s_add_i32 m0, s0, 0x2000
	s_nop 0
	global_load_lds_dwordx4 v[142:143], off
	v_lshl_add_u64 v[142:143], v[234:235], 0, s[58:59]
	s_mov_b32 m0, s35
	s_nop 0
	global_load_lds_dwordx4 v[142:143], off
	v_lshl_add_u64 v[142:143], v[236:237], 0, s[58:59]
	s_mov_b32 m0, s40
	s_nop 0
	global_load_lds_dwordx4 v[142:143], off
	s_waitcnt vmcnt(8)
	s_waitcnt lgkmcnt(0)
	s_barrier
	s_setprio 1
	s_waitcnt lgkmcnt(0)
	v_mfma_f32_16x16x32_bf16 v[60:63], v[160:163], v[192:195], v[60:63]
	v_mfma_f32_16x16x32_bf16 v[56:59], v[168:171], v[192:195], v[56:59]
	v_mfma_f32_16x16x32_bf16 v[44:47], v[160:163], v[200:203], v[44:47]
	v_mfma_f32_16x16x32_bf16 v[40:43], v[168:171], v[200:203], v[40:43]
	v_mfma_f32_16x16x32_bf16 v[28:31], v[160:163], v[208:211], v[28:31]
	v_mfma_f32_16x16x32_bf16 v[24:27], v[168:171], v[208:211], v[24:27]
	v_mfma_f32_16x16x32_bf16 v[12:15], v[160:163], v[216:219], v[12:15]
	v_mfma_f32_16x16x32_bf16 v[8:11], v[168:171], v[216:219], v[8:11]
	v_mfma_f32_16x16x32_bf16 v[60:63], v[164:167], v[196:199], v[60:63]
	v_mfma_f32_16x16x32_bf16 v[56:59], v[172:175], v[196:199], v[56:59]
	v_mfma_f32_16x16x32_bf16 v[44:47], v[164:167], v[204:207], v[44:47]
	v_mfma_f32_16x16x32_bf16 v[40:43], v[172:175], v[204:207], v[40:43]
	v_mfma_f32_16x16x32_bf16 v[28:31], v[164:167], v[212:215], v[28:31]
	v_mfma_f32_16x16x32_bf16 v[24:27], v[172:175], v[212:215], v[24:27]
	v_mfma_f32_16x16x32_bf16 v[12:15], v[164:167], v[228:231], v[12:15]
	v_mfma_f32_16x16x32_bf16 v[8:11], v[172:175], v[228:231], v[8:11]
	v_mfma_f32_16x16x32_bf16 v[52:55], v[176:179], v[192:195], v[52:55]
	v_mfma_f32_16x16x32_bf16 v[48:51], v[184:187], v[192:195], v[48:51]
	v_mfma_f32_16x16x32_bf16 v[36:39], v[176:179], v[200:203], v[36:39]
	v_mfma_f32_16x16x32_bf16 v[32:35], v[184:187], v[200:203], v[32:35]
	v_mfma_f32_16x16x32_bf16 v[20:23], v[176:179], v[208:211], v[20:23]
	v_mfma_f32_16x16x32_bf16 v[16:19], v[184:187], v[208:211], v[16:19]
	v_mfma_f32_16x16x32_bf16 v[4:7], v[176:179], v[216:219], v[4:7]
	v_mfma_f32_16x16x32_bf16 v[0:3], v[184:187], v[216:219], v[0:3]
	v_mfma_f32_16x16x32_bf16 v[52:55], v[180:183], v[196:199], v[52:55]
	v_mfma_f32_16x16x32_bf16 v[48:51], v[188:191], v[196:199], v[48:51]
	v_mfma_f32_16x16x32_bf16 v[36:39], v[180:183], v[204:207], v[36:39]
	v_mfma_f32_16x16x32_bf16 v[32:35], v[188:191], v[204:207], v[32:35]
	v_mfma_f32_16x16x32_bf16 v[20:23], v[180:183], v[212:215], v[20:23]
	v_mfma_f32_16x16x32_bf16 v[16:19], v[188:191], v[212:215], v[16:19]
	v_mfma_f32_16x16x32_bf16 v[4:7], v[180:183], v[228:231], v[4:7]
	v_mfma_f32_16x16x32_bf16 v[0:3], v[188:191], v[228:231], v[0:3]
	s_setprio 0
	s_barrier
	s_add_u32 s14, s14, 0x100
	s_addc_u32 s15, s15, 0
	s_cmp_ge_i32 s52, s42
	s_mov_b64 s[0:1], s[4:5]
	s_mov_b32 s8, s52
	s_cbranch_scc0 .LBB0_84

; #define PG8_STAGE(bufoff, gbase, voff) do { _Pragma("unroll") for (int _i = 0; _i < 2; ++_i) \
;         __builtin_amdgcn_global_load_lds((const unsigned*)((const char*)(gbase) + (voff)[_i]), (LAS unsigned*)(lds + (bufoff) + ldsw + _i * 8192), 16, 0, 0); } while (0)
; #define PG8_LDA(dst, b, h) do { _Pragma("unroll") for (int m = 0; m < 4; ++m) _Pragma("unroll") for (int k = 0; k < 2; ++k) dst[m][k] = *(const LAS bf16x8*)(lds + PG8_SA(b, h) + aoff + m * 2048 + k * 1024); } while (0)
; #define PG8_LDB(dst, b, h) do { _Pragma("unroll") for (int n = 0; n < 2; ++n) _Pragma("unroll") for (int k = 0; k < 2; ++k) dst[n][k] = *(const LAS bf16x8*)(lds + PG8_SB(b, h) + boff + n * 2048 + k * 1024); } while (0)
; #define PG8_MMA(ai, bj, At, Bt) do { __builtin_amdgcn_s_setprio(1); _Pragma("unroll") for (int m = 0; m < 4; ++m) _Pragma("unroll") for (int n = 0; n < 2; ++n) _Pragma("unroll") for (int k = 0; k < 2; ++k) \
;         acc[ai][bj][m][n] = __builtin_amdgcn_mfma_f32_16x16x32_bf16(Bt[n][k], At[m][k], acc[ai][bj][m][n], 0, 0, 0); __builtin_amdgcn_s_setprio(0); } while (0)
; #define PG8_WAIT_V(n) asm volatile("s_waitcnt vmcnt(" #n ")" ::: "memory")
; #define PG8_WAIT_L(n) asm volatile("s_waitcnt lgkmcnt(" #n ")" ::: "memory")
; #define PG8_BAR __builtin_amdgcn_s_barrier()
; #define PG8_SCHED __builtin_amdgcn_sched_barrier(0)
;     ...
;             PG8_LDB(B0, 0, 0); PG8_LDB(B1, 0, 1); PG8_SCHED; PG8_LDA(At, 0, 0); PG8_STAGE(PG8_SA(1, 1), a1 + hstepA, voffA);
;             PG8_WAIT_V(8); PG8_WAIT_L(0); PG8_BAR; PG8_MMA(0, 0, At, B0); PG8_MMA(0, 1, At, B1); PG8_BAR; PG8_SCHED;
;             PG8_LDA(At, 0, 1); PG8_STAGE(PG8_SB(0, 0), b2, voffB); PG8_STAGE(PG8_SB(0, 1), b2 + hstepB, voffB); PG8_STAGE(PG8_SA(0, 0), a2, voffA);
;             PG8_WAIT_V(8); PG8_WAIT_L(0); PG8_BAR; PG8_MMA(1, 0, At, B0); PG8_MMA(1, 1, At, B1); PG8_BAR; PG8_SCHED;
.LBB0_133:
	s_add_i32 s9, s4, 2
	s_add_u32 s2, s0, 0x100
	s_addc_u32 s3, s1, 0
	s_add_i32 s18, 0, 0x10000
	s_cmp_eq_u32 s48, s4
	s_cselect_b32 s5, s15, s3
	s_cselect_b32 s4, s14, s2
	s_cselect_b32 s17, s35, s8
	s_cselect_b32 s16, s34, s7
	s_add_i32 s19, 0, 0x14000
	v_add_u32_e32 v140, s18, v208
	v_add_u32_e32 v152, s19, v208
	ds_read_b128 v[128:131], v140
	ds_read_b128 v[132:135], v140 offset:1024
	ds_read_b128 v[136:139], v140 offset:2048
	ds_read_b128 v[140:143], v140 offset:3072
	ds_read_b128 v[172:175], v152
	ds_read_b128 v[176:179], v152 offset:1024
	ds_read_b128 v[180:183], v152 offset:2048
	ds_read_b128 v[184:187], v152 offset:3072
	v_lshl_add_u64 v[204:205], s[0:1], 0, v[168:169]
	s_add_i32 m0, s41, 0xc000
	ds_read_b128 v[188:191], v210
	ds_read_b128 v[192:195], v210 offset:1024
	ds_read_b128 v[196:199], v210 offset:2048
	ds_read_b128 v[200:203], v210 offset:3072
	ds_read_b128 v[228:231], v210 offset:4096
	ds_read_b128 v[232:235], v210 offset:5120
	ds_read_b128 v[236:239], v210 offset:6144
	ds_read_b128 v[240:243], v210 offset:7168
	global_load_lds_dwordx4 v[204:205], off
	v_lshl_add_u64 v[204:205], s[0:1], 0, v[170:171]
	s_add_i32 m0, s41, 0xe000
	s_nop 0
	global_load_lds_dwordx4 v[204:205], off
	s_waitcnt vmcnt(8)
	s_waitcnt lgkmcnt(0)
	s_barrier
	s_setprio 1
	s_waitcnt lgkmcnt(0)
	v_mfma_f32_16x16x32_bf16 v[124:127], v[128:131], v[188:191], v[124:127]
	v_mfma_f32_16x16x32_bf16 v[120:123], v[136:139], v[188:191], v[120:123]
	v_mfma_f32_16x16x32_bf16 v[108:111], v[128:131], v[196:199], v[108:111]
	v_mfma_f32_16x16x32_bf16 v[104:107], v[136:139], v[196:199], v[104:107]
	v_mfma_f32_16x16x32_bf16 v[92:95], v[128:131], v[228:231], v[92:95]
	v_mfma_f32_16x16x32_bf16 v[88:91], v[136:139], v[228:231], v[88:91]
	v_mfma_f32_16x16x32_bf16 v[76:79], v[128:131], v[236:239], v[76:79]
	v_mfma_f32_16x16x32_bf16 v[72:75], v[136:139], v[236:239], v[72:75]
	v_mfma_f32_16x16x32_bf16 v[124:127], v[132:135], v[192:195], v[124:127]
	v_mfma_f32_16x16x32_bf16 v[120:123], v[140:143], v[192:195], v[120:123]
	v_mfma_f32_16x16x32_bf16 v[108:111], v[132:135], v[200:203], v[108:111]
	v_mfma_f32_16x16x32_bf16 v[104:107], v[140:143], v[200:203], v[104:107]
	v_mfma_f32_16x16x32_bf16 v[92:95], v[132:135], v[232:235], v[92:95]
	v_mfma_f32_16x16x32_bf16 v[88:91], v[140:143], v[232:235], v[88:91]
	v_mfma_f32_16x16x32_bf16 v[76:79], v[132:135], v[240:243], v[76:79]
	v_mfma_f32_16x16x32_bf16 v[72:75], v[140:143], v[240:243], v[72:75]
	v_mfma_f32_16x16x32_bf16 v[116:119], v[172:175], v[188:191], v[116:119]
	v_mfma_f32_16x16x32_bf16 v[112:115], v[180:183], v[188:191], v[112:115]
	v_mfma_f32_16x16x32_bf16 v[100:103], v[172:175], v[196:199], v[100:103]
	v_mfma_f32_16x16x32_bf16 v[96:99], v[180:183], v[196:199], v[96:99]
	v_mfma_f32_16x16x32_bf16 v[84:87], v[172:175], v[228:231], v[84:87]
	v_mfma_f32_16x16x32_bf16 v[80:83], v[180:183], v[228:231], v[80:83]
	v_mfma_f32_16x16x32_bf16 v[68:71], v[172:175], v[236:239], v[68:71]
	v_mfma_f32_16x16x32_bf16 v[64:67], v[180:183], v[236:239], v[64:67]
	v_mfma_f32_16x16x32_bf16 v[116:119], v[176:179], v[192:195], v[116:119]
	v_mfma_f32_16x16x32_bf16 v[112:115], v[184:187], v[192:195], v[112:115]
	v_mfma_f32_16x16x32_bf16 v[100:103], v[176:179], v[200:203], v[100:103]
	v_mfma_f32_16x16x32_bf16 v[96:99], v[184:187], v[200:203], v[96:99]
	v_mfma_f32_16x16x32_bf16 v[84:87], v[176:179], v[232:235], v[84:87]
	v_mfma_f32_16x16x32_bf16 v[80:83], v[184:187], v[232:235], v[80:83]
	v_mfma_f32_16x16x32_bf16 v[68:71], v[176:179], v[240:243], v[68:71]
	v_mfma_f32_16x16x32_bf16 v[64:67], v[184:187], v[240:243], v[64:67]
	s_setprio 0
	s_barrier
	s_add_i32 s0, s18, s40
	v_lshl_add_u64 v[204:205], s[16:17], 0, v[158:159]
	s_mov_b32 m0, s0
	ds_read_b128 v[188:191], v210 offset:16384
	ds_read_b128 v[192:195], v210 offset:17408
	ds_read_b128 v[196:199], v210 offset:18432
	ds_read_b128 v[200:203], v210 offset:19456
	ds_read_b128 v[228:231], v210 offset:20480
	ds_read_b128 v[232:235], v210 offset:21504
	ds_read_b128 v[236:239], v210 offset:22528
	ds_read_b128 v[240:243], v210 offset:23552
	global_load_lds_dwordx4 v[204:205], off
	s_add_i32 m0, s0, 0x2000
	s_add_u32 s0, s16, s22
	v_lshl_add_u64 v[244:245], s[16:17], 0, v[162:163]
	s_addc_u32 s1, s17, s23
	s_add_i32 s16, s19, s40
	global_load_lds_dwordx4 v[244:245], off
	v_lshl_add_u64 v[246:247], s[0:1], 0, v[158:159]
	s_mov_b32 m0, s16
	v_lshl_add_u64 v[248:249], s[0:1], 0, v[162:163]
	global_load_lds_dwordx4 v[246:247], off
	s_add_i32 m0, s16, 0x2000
	v_lshl_add_u64 v[250:251], s[4:5], 0, v[156:157]
	global_load_lds_dwordx4 v[248:249], off
	s_mov_b32 m0, s41
	v_lshl_add_u64 v[252:253], s[4:5], 0, v[160:161]
	global_load_lds_dwordx4 v[250:251], off
	s_mov_b32 m0, s42
	s_nop 0
	global_load_lds_dwordx4 v[252:253], off
	s_waitcnt vmcnt(8)
	s_waitcnt lgkmcnt(0)
	s_barrier
; #define PG8_STAGE(bufoff, gbase, voff) do { _Pragma("unroll") for (int _i = 0; _i < 2; ++_i) \
;         __builtin_amdgcn_global_load_lds((const unsigned*)((const char*)(gbase) + (voff)[_i]), (LAS unsigned*)(lds + (bufoff) + ldsw + _i * 8192), 16, 0, 0); } while (0)
; #define PG8_LDA(dst, b, h) do { _Pragma("unroll") for (int m = 0; m < 4; ++m) _Pragma("unroll") for (int k = 0; k < 2; ++k) dst[m][k] = *(const LAS bf16x8*)(lds + PG8_SA(b, h) + aoff + m * 2048 + k * 1024); } while (0)
; #define PG8_LDB(dst, b, h) do { _Pragma("unroll") for (int n = 0; n < 2; ++n) _Pragma("unroll") for (int k = 0; k < 2; ++k) dst[n][k] = *(const LAS bf16x8*)(lds + PG8_SB(b, h) + boff + n * 2048 + k * 1024); } while (0)
; #define PG8_MMA(ai, bj, At, Bt) do { __builtin_amdgcn_s_setprio(1); _Pragma("unroll") for (int m = 0; m < 4; ++m) _Pragma("unroll") for (int n = 0; n < 2; ++n) _Pragma("unroll") for (int k = 0; k < 2; ++k) \
;         acc[ai][bj][m][n] = __builtin_amdgcn_mfma_f32_16x16x32_bf16(Bt[n][k], At[m][k], acc[ai][bj][m][n], 0, 0, 0); __builtin_amdgcn_s_setprio(0); } while (0)
; #define PG8_WAIT_V(n) asm volatile("s_waitcnt vmcnt(" #n ")" ::: "memory")
; #define PG8_WAIT_L(n) asm volatile("s_waitcnt lgkmcnt(" #n ")" ::: "memory")
; #define PG8_BAR __builtin_amdgcn_s_barrier()
; #define PG8_SCHED __builtin_amdgcn_sched_barrier(0)
;     ...
;             PG8_WAIT_V(8); PG8_WAIT_L(0); PG8_BAR; PG8_MMA(1, 0, At, B0); PG8_MMA(1, 1, At, B1); PG8_BAR; PG8_SCHED;
;             PG8_LDB(B0, 1, 0); PG8_LDB(B1, 1, 1); PG8_SCHED; PG8_LDA(At, 1, 0); PG8_STAGE(PG8_SA(0, 1), a2 + hstepA, voffA);
;             PG8_WAIT_V(8); PG8_WAIT_L(0); PG8_BAR; PG8_MMA(0, 0, At, B0); PG8_MMA(0, 1, At, B1); PG8_BAR; PG8_SCHED;
	s_setprio 1
	s_waitcnt lgkmcnt(0)
	v_mfma_f32_16x16x32_bf16 v[60:63], v[128:131], v[188:191], v[60:63]
	v_mfma_f32_16x16x32_bf16 v[56:59], v[136:139], v[188:191], v[56:59]
	v_mfma_f32_16x16x32_bf16 v[44:47], v[128:131], v[196:199], v[44:47]
	v_mfma_f32_16x16x32_bf16 v[40:43], v[136:139], v[196:199], v[40:43]
	v_mfma_f32_16x16x32_bf16 v[28:31], v[128:131], v[228:231], v[28:31]
	v_mfma_f32_16x16x32_bf16 v[24:27], v[136:139], v[228:231], v[24:27]
	v_mfma_f32_16x16x32_bf16 v[12:15], v[128:131], v[236:239], v[12:15]
	v_mfma_f32_16x16x32_bf16 v[8:11], v[136:139], v[236:239], v[8:11]
	v_mfma_f32_16x16x32_bf16 v[60:63], v[132:135], v[192:195], v[60:63]
	v_mfma_f32_16x16x32_bf16 v[56:59], v[140:143], v[192:195], v[56:59]
	v_mfma_f32_16x16x32_bf16 v[44:47], v[132:135], v[200:203], v[44:47]
	v_mfma_f32_16x16x32_bf16 v[40:43], v[140:143], v[200:203], v[40:43]
	v_mfma_f32_16x16x32_bf16 v[28:31], v[132:135], v[232:235], v[28:31]
	v_mfma_f32_16x16x32_bf16 v[24:27], v[140:143], v[232:235], v[24:27]
	v_mfma_f32_16x16x32_bf16 v[12:15], v[132:135], v[240:243], v[12:15]
	v_mfma_f32_16x16x32_bf16 v[8:11], v[140:143], v[240:243], v[8:11]
	v_mfma_f32_16x16x32_bf16 v[52:55], v[172:175], v[188:191], v[52:55]
	v_mfma_f32_16x16x32_bf16 v[48:51], v[180:183], v[188:191], v[48:51]
	v_mfma_f32_16x16x32_bf16 v[36:39], v[172:175], v[196:199], v[36:39]
	v_mfma_f32_16x16x32_bf16 v[32:35], v[180:183], v[196:199], v[32:35]
	v_mfma_f32_16x16x32_bf16 v[20:23], v[172:175], v[228:231], v[20:23]
	v_mfma_f32_16x16x32_bf16 v[16:19], v[180:183], v[228:231], v[16:19]
	v_mfma_f32_16x16x32_bf16 v[4:7], v[172:175], v[236:239], v[4:7]
	v_mfma_f32_16x16x32_bf16 v[0:3], v[180:183], v[236:239], v[0:3]
	v_mfma_f32_16x16x32_bf16 v[52:55], v[176:179], v[192:195], v[52:55]
	v_mfma_f32_16x16x32_bf16 v[48:51], v[184:187], v[192:195], v[48:51]
	v_mfma_f32_16x16x32_bf16 v[36:39], v[176:179], v[200:203], v[36:39]
	v_mfma_f32_16x16x32_bf16 v[32:35], v[184:187], v[200:203], v[32:35]
	v_mfma_f32_16x16x32_bf16 v[20:23], v[176:179], v[232:235], v[20:23]
	v_mfma_f32_16x16x32_bf16 v[16:19], v[184:187], v[232:235], v[16:19]
	v_mfma_f32_16x16x32_bf16 v[4:7], v[176:179], v[240:243], v[4:7]
	v_mfma_f32_16x16x32_bf16 v[0:3], v[184:187], v[240:243], v[0:3]
	s_setprio 0
	s_barrier
	s_add_i32 s16, 0, 0x18000
	s_add_i32 s17, 0, 0x1c000
	v_add_u32_e32 v140, s16, v208
	v_add_u32_e32 v152, s17, v208
	ds_read_b128 v[128:131], v140
	ds_read_b128 v[132:135], v140 offset:1024
	ds_read_b128 v[136:139], v140 offset:2048
	ds_read_b128 v[140:143], v140 offset:3072
	ds_read_b128 v[172:175], v152
	ds_read_b128 v[176:179], v152 offset:1024
	ds_read_b128 v[180:183], v152 offset:2048
	ds_read_b128 v[184:187], v152 offset:3072
	s_add_u32 s0, s4, 0xb0000
	s_addc_u32 s1, s5, 0
	s_mov_b32 m0, s43
	v_lshl_add_u64 v[152:153], s[0:1], 0, v[156:157]
	ds_read_b128 v[188:191], v210 offset:32768
	ds_read_b128 v[192:195], v210 offset:33792
	ds_read_b128 v[196:199], v210 offset:34816
	ds_read_b128 v[200:203], v210 offset:35840
	ds_read_b128 v[228:231], v210 offset:36864
	ds_read_b128 v[232:235], v210 offset:37888
	ds_read_b128 v[236:239], v210 offset:38912
	ds_read_b128 v[240:243], v210 offset:39936
	global_load_lds_dwordx4 v[152:153], off
	v_lshl_add_u64 v[152:153], s[0:1], 0, v[160:161]
	s_mov_b32 m0, s44
	s_nop 0
	global_load_lds_dwordx4 v[152:153], off
	s_waitcnt vmcnt(8)
	s_waitcnt lgkmcnt(0)
	s_barrier
	s_setprio 1
	s_waitcnt lgkmcnt(0)
	v_mfma_f32_16x16x32_bf16 v[124:127], v[128:131], v[188:191], v[124:127]
	v_mfma_f32_16x16x32_bf16 v[120:123], v[136:139], v[188:191], v[120:123]
	v_mfma_f32_16x16x32_bf16 v[108:111], v[128:131], v[196:199], v[108:111]
	v_mfma_f32_16x16x32_bf16 v[104:107], v[136:139], v[196:199], v[104:107]
	v_mfma_f32_16x16x32_bf16 v[92:95], v[128:131], v[228:231], v[92:95]
	v_mfma_f32_16x16x32_bf16 v[88:91], v[136:139], v[228:231], v[88:91]
	v_mfma_f32_16x16x32_bf16 v[76:79], v[128:131], v[236:239], v[76:79]
	v_mfma_f32_16x16x32_bf16 v[72:75], v[136:139], v[236:239], v[72:75]
	v_mfma_f32_16x16x32_bf16 v[124:127], v[132:135], v[192:195], v[124:127]
	v_mfma_f32_16x16x32_bf16 v[120:123], v[140:143], v[192:195], v[120:123]
	v_mfma_f32_16x16x32_bf16 v[108:111], v[132:135], v[200:203], v[108:111]
	v_mfma_f32_16x16x32_bf16 v[104:107], v[140:143], v[200:203], v[104:107]
	v_mfma_f32_16x16x32_bf16 v[92:95], v[132:135], v[232:235], v[92:95]
	v_mfma_f32_16x16x32_bf16 v[88:91], v[140:143], v[232:235], v[88:91]
	v_mfma_f32_16x16x32_bf16 v[76:79], v[132:135], v[240:243], v[76:79]
	v_mfma_f32_16x16x32_bf16 v[72:75], v[140:143], v[240:243], v[72:75]
	v_mfma_f32_16x16x32_bf16 v[116:119], v[172:175], v[188:191], v[116:119]
	v_mfma_f32_16x16x32_bf16 v[112:115], v[180:183], v[188:191], v[112:115]
	v_mfma_f32_16x16x32_bf16 v[100:103], v[172:175], v[196:199], v[100:103]
	v_mfma_f32_16x16x32_bf16 v[96:99], v[180:183], v[196:199], v[96:99]
	v_mfma_f32_16x16x32_bf16 v[84:87], v[172:175], v[228:231], v[84:87]
	v_mfma_f32_16x16x32_bf16 v[80:83], v[180:183], v[228:231], v[80:83]
	v_mfma_f32_16x16x32_bf16 v[68:71], v[172:175], v[236:239], v[68:71]
	v_mfma_f32_16x16x32_bf16 v[64:67], v[180:183], v[236:239], v[64:67]
	v_mfma_f32_16x16x32_bf16 v[116:119], v[176:179], v[192:195], v[116:119]
	v_mfma_f32_16x16x32_bf16 v[112:115], v[184:187], v[192:195], v[112:115]
	v_mfma_f32_16x16x32_bf16 v[100:103], v[176:179], v[200:203], v[100:103]
	v_mfma_f32_16x16x32_bf16 v[96:99], v[184:187], v[200:203], v[96:99]
	v_mfma_f32_16x16x32_bf16 v[84:87], v[176:179], v[232:235], v[84:87]
	v_mfma_f32_16x16x32_bf16 v[80:83], v[184:187], v[232:235], v[80:83]
	v_mfma_f32_16x16x32_bf16 v[68:71], v[176:179], v[240:243], v[68:71]
	v_mfma_f32_16x16x32_bf16 v[64:67], v[184:187], v[240:243], v[64:67]
	s_setprio 0
	s_barrier
; #define PG8_STAGE(bufoff, gbase, voff) do { _Pragma("unroll") for (int _i = 0; _i < 2; ++_i) \
;         __builtin_amdgcn_global_load_lds((const unsigned*)((const char*)(gbase) + (voff)[_i]), (LAS unsigned*)(lds + (bufoff) + ldsw + _i * 8192), 16, 0, 0); } while (0)
; #define PG8_LDA(dst, b, h) do { _Pragma("unroll") for (int m = 0; m < 4; ++m) _Pragma("unroll") for (int k = 0; k < 2; ++k) dst[m][k] = *(const LAS bf16x8*)(lds + PG8_SA(b, h) + aoff + m * 2048 + k * 1024); } while (0)
; #define PG8_MMA(ai, bj, At, Bt) do { __builtin_amdgcn_s_setprio(1); _Pragma("unroll") for (int m = 0; m < 4; ++m) _Pragma("unroll") for (int n = 0; n < 2; ++n) _Pragma("unroll") for (int k = 0; k < 2; ++k) \
;         acc[ai][bj][m][n] = __builtin_amdgcn_mfma_f32_16x16x32_bf16(Bt[n][k], At[m][k], acc[ai][bj][m][n], 0, 0, 0); __builtin_amdgcn_s_setprio(0); } while (0)
; #define PG8_WAIT_V(n) asm volatile("s_waitcnt vmcnt(" #n ")" ::: "memory")
; #define PG8_WAIT_L(n) asm volatile("s_waitcnt lgkmcnt(" #n ")" ::: "memory")
; #define PG8_BAR __builtin_amdgcn_s_barrier()
; #define PG8_SCHED __builtin_amdgcn_sched_barrier(0)
;     ...
;         for (int t = 0; t < nt; t += 2) {
;     ...
;             PG8_LDA(At, 1, 1); PG8_STAGE(PG8_SB(1, 0), b3, voffB); PG8_STAGE(PG8_SB(1, 1), b3 + hstepB, voffB); PG8_STAGE(PG8_SA(1, 0), a3, voffA);
;             PG8_WAIT_V(8); PG8_WAIT_L(0); PG8_BAR; PG8_MMA(1, 0, At, B0); PG8_MMA(1, 1, At, B1); PG8_BAR; PG8_SCHED;
	s_add_i32 s0, s16, s40
	v_lshl_add_u64 v[152:153], v[204:205], 0, s[58:59]
	s_mov_b32 m0, s0
	ds_read_b128 v[188:191], v210 offset:49152
	ds_read_b128 v[192:195], v210 offset:50176
	ds_read_b128 v[196:199], v210 offset:51200
	ds_read_b128 v[200:203], v210 offset:52224
	ds_read_b128 v[228:231], v210 offset:53248
	ds_read_b128 v[232:235], v210 offset:54272
	ds_read_b128 v[236:239], v210 offset:55296
	ds_read_b128 v[240:243], v210 offset:56320
	global_load_lds_dwordx4 v[152:153], off
	v_lshl_add_u64 v[152:153], v[244:245], 0, s[58:59]
	s_add_i32 m0, s0, 0x2000
	s_add_i32 s0, s17, s40
	global_load_lds_dwordx4 v[152:153], off
	v_lshl_add_u64 v[152:153], v[246:247], 0, s[58:59]
	s_mov_b32 m0, s0
	s_nop 0
	global_load_lds_dwordx4 v[152:153], off
	v_lshl_add_u64 v[152:153], v[248:249], 0, s[58:59]
	s_add_i32 m0, s0, 0x2000
	s_nop 0
	global_load_lds_dwordx4 v[152:153], off
	v_lshl_add_u64 v[152:153], v[250:251], 0, s[58:59]
	s_mov_b32 m0, s45
	s_nop 0
	global_load_lds_dwordx4 v[152:153], off
	v_lshl_add_u64 v[152:153], v[252:253], 0, s[58:59]
	s_mov_b32 m0, s46
	s_nop 0
	global_load_lds_dwordx4 v[152:153], off
	s_waitcnt vmcnt(8)
	s_waitcnt lgkmcnt(0)
	s_barrier
	s_setprio 1
	s_waitcnt lgkmcnt(0)
	v_mfma_f32_16x16x32_bf16 v[60:63], v[128:131], v[188:191], v[60:63]
	v_mfma_f32_16x16x32_bf16 v[56:59], v[136:139], v[188:191], v[56:59]
	v_mfma_f32_16x16x32_bf16 v[44:47], v[128:131], v[196:199], v[44:47]
	v_mfma_f32_16x16x32_bf16 v[40:43], v[136:139], v[196:199], v[40:43]
	v_mfma_f32_16x16x32_bf16 v[28:31], v[128:131], v[228:231], v[28:31]
	v_mfma_f32_16x16x32_bf16 v[24:27], v[136:139], v[228:231], v[24:27]
	v_mfma_f32_16x16x32_bf16 v[12:15], v[128:131], v[236:239], v[12:15]
	v_mfma_f32_16x16x32_bf16 v[8:11], v[136:139], v[236:239], v[8:11]
	v_mfma_f32_16x16x32_bf16 v[60:63], v[132:135], v[192:195], v[60:63]
	v_mfma_f32_16x16x32_bf16 v[56:59], v[140:143], v[192:195], v[56:59]
	v_mfma_f32_16x16x32_bf16 v[44:47], v[132:135], v[200:203], v[44:47]
	v_mfma_f32_16x16x32_bf16 v[40:43], v[140:143], v[200:203], v[40:43]
	v_mfma_f32_16x16x32_bf16 v[28:31], v[132:135], v[232:235], v[28:31]
	v_mfma_f32_16x16x32_bf16 v[24:27], v[140:143], v[232:235], v[24:27]
	v_mfma_f32_16x16x32_bf16 v[12:15], v[132:135], v[240:243], v[12:15]
	v_mfma_f32_16x16x32_bf16 v[8:11], v[140:143], v[240:243], v[8:11]
	v_mfma_f32_16x16x32_bf16 v[52:55], v[172:175], v[188:191], v[52:55]
	v_mfma_f32_16x16x32_bf16 v[48:51], v[180:183], v[188:191], v[48:51]
	v_mfma_f32_16x16x32_bf16 v[36:39], v[172:175], v[196:199], v[36:39]
	v_mfma_f32_16x16x32_bf16 v[32:35], v[180:183], v[196:199], v[32:35]
	v_mfma_f32_16x16x32_bf16 v[20:23], v[172:175], v[228:231], v[20:23]
	v_mfma_f32_16x16x32_bf16 v[16:19], v[180:183], v[228:231], v[16:19]
	v_mfma_f32_16x16x32_bf16 v[4:7], v[172:175], v[236:239], v[4:7]
	v_mfma_f32_16x16x32_bf16 v[0:3], v[180:183], v[236:239], v[0:3]
	v_mfma_f32_16x16x32_bf16 v[52:55], v[176:179], v[192:195], v[52:55]
	v_mfma_f32_16x16x32_bf16 v[48:51], v[184:187], v[192:195], v[48:51]
	v_mfma_f32_16x16x32_bf16 v[36:39], v[176:179], v[200:203], v[36:39]
	v_mfma_f32_16x16x32_bf16 v[32:35], v[184:187], v[200:203], v[32:35]
	v_mfma_f32_16x16x32_bf16 v[20:23], v[176:179], v[232:235], v[20:23]
	v_mfma_f32_16x16x32_bf16 v[16:19], v[184:187], v[232:235], v[16:19]
	v_mfma_f32_16x16x32_bf16 v[4:7], v[176:179], v[240:243], v[4:7]
	v_mfma_f32_16x16x32_bf16 v[0:3], v[184:187], v[240:243], v[0:3]
	s_setprio 0
	s_barrier
	s_add_u32 s7, s7, 0x100
	s_addc_u32 s8, s8, 0
	s_cmp_ge_i32 s9, s47
	s_mov_b64 s[0:1], s[2:3]
	s_mov_b32 s4, s9
	s_cbranch_scc0 .LBB0_133
	v_mov_b64_e32 v[248:249], v[154:155]
	v_mov_b64_e32 v[154:155], v[212:213]

; #define PG8_STAGE(bufoff, gbase, voff) do { _Pragma("unroll") for (int _i = 0; _i < 2; ++_i) \
;         __builtin_amdgcn_global_load_lds((const unsigned*)((const char*)(gbase) + (voff)[_i]), (LAS unsigned*)(lds + (bufoff) + ldsw + _i * 8192), 16, 0, 0); } while (0)
; #define PG8_LDA(dst, b, h) do { _Pragma("unroll") for (int m = 0; m < 4; ++m) _Pragma("unroll") for (int k = 0; k < 2; ++k) dst[m][k] = *(const LAS bf16x8*)(lds + PG8_SA(b, h) + aoff + m * 2048 + k * 1024); } while (0)
; #define PG8_LDB(dst, b, h) do { _Pragma("unroll") for (int n = 0; n < 2; ++n) _Pragma("unroll") for (int k = 0; k < 2; ++k) dst[n][k] = *(const LAS bf16x8*)(lds + PG8_SB(b, h) + boff + n * 2048 + k * 1024); } while (0)
; #define PG8_MMA(ai, bj, At, Bt) do { __builtin_amdgcn_s_setprio(1); _Pragma("unroll") for (int m = 0; m < 4; ++m) _Pragma("unroll") for (int n = 0; n < 2; ++n) _Pragma("unroll") for (int k = 0; k < 2; ++k) \
;         acc[ai][bj][m][n] = __builtin_amdgcn_mfma_f32_16x16x32_bf16(Bt[n][k], At[m][k], acc[ai][bj][m][n], 0, 0, 0); __builtin_amdgcn_s_setprio(0); } while (0)
; #define PG8_WAIT_V(n) asm volatile("s_waitcnt vmcnt(" #n ")" ::: "memory")
; #define PG8_WAIT_L(n) asm volatile("s_waitcnt lgkmcnt(" #n ")" ::: "memory")
; #define PG8_BAR __builtin_amdgcn_s_barrier()
; #define PG8_SCHED __builtin_amdgcn_sched_barrier(0)
;     ...
;             PG8_LDB(B0, 0, 0); PG8_LDB(B1, 0, 1); PG8_SCHED; PG8_LDA(At, 0, 0); PG8_STAGE(PG8_SA(1, 1), a1 + hstepA, voffA);
;             PG8_WAIT_V(8); PG8_WAIT_L(0); PG8_BAR; PG8_MMA(0, 0, At, B0); PG8_MMA(0, 1, At, B1); PG8_BAR; PG8_SCHED;
;             PG8_LDA(At, 0, 1); PG8_STAGE(PG8_SB(0, 0), b2, voffB); PG8_STAGE(PG8_SB(0, 1), b2 + hstepB, voffB); PG8_STAGE(PG8_SA(0, 0), a2, voffA);
;             PG8_WAIT_V(8); PG8_WAIT_L(0); PG8_BAR; PG8_MMA(1, 0, At, B0); PG8_MMA(1, 1, At, B1); PG8_BAR; PG8_SCHED;
.LBB0_206:
	s_add_i32 s53, s26, 2
	s_add_u32 s54, s12, 0xfffc0080
	s_addc_u32 s27, s13, -1
	s_add_i32 s56, 0, 0x10000
	s_cmp_eq_u32 s46, s26
	s_cselect_b32 s27, s17, s27
	s_cselect_b32 s26, s52, s54
	v_add_u32_e32 v152, s56, v143
	s_cselect_b32 s55, s19, s29
	s_cselect_b32 s54, s18, s28
	s_add_i32 s57, 0, 0x14000
	ds_read_b128 v[158:161], v152
	ds_read_b128 v[162:165], v152 offset:1024
	ds_read_b128 v[166:169], v152 offset:2048
	ds_read_b128 v[170:173], v152 offset:3072
	v_add_u32_e32 v152, s57, v143
	ds_read_b128 v[174:177], v152
	ds_read_b128 v[178:181], v152 offset:1024
	ds_read_b128 v[182:185], v152 offset:2048
	ds_read_b128 v[186:189], v152 offset:3072
	v_lshl_add_u64 v[218:219], s[12:13], 0, v[138:139]
	s_add_i32 m0, s25, 0xc000
	ds_read_b128 v[190:193], v157
	ds_read_b128 v[194:197], v157 offset:1024
	ds_read_b128 v[198:201], v157 offset:2048
	ds_read_b128 v[202:205], v157 offset:3072
	ds_read_b128 v[206:209], v157 offset:4096
	ds_read_b128 v[210:213], v157 offset:5120
	ds_read_b128 v[214:217], v157 offset:6144
	ds_read_b128 v[228:231], v157 offset:7168
	global_load_lds_dwordx4 v[218:219], off
	v_lshl_add_u64 v[218:219], s[12:13], 0, v[140:141]
	s_add_i32 m0, s25, 0xe000
	s_nop 0
	global_load_lds_dwordx4 v[218:219], off
	s_waitcnt vmcnt(8)
	s_waitcnt lgkmcnt(0)
	s_barrier
	s_setprio 1
	s_waitcnt lgkmcnt(0)
	v_mfma_f32_16x16x32_bf16 v[124:127], v[158:161], v[190:193], v[124:127]
	v_mfma_f32_16x16x32_bf16 v[116:119], v[166:169], v[190:193], v[116:119]
	v_mfma_f32_16x16x32_bf16 v[108:111], v[158:161], v[198:201], v[108:111]
	v_mfma_f32_16x16x32_bf16 v[100:103], v[166:169], v[198:201], v[100:103]
	v_mfma_f32_16x16x32_bf16 v[92:95], v[158:161], v[206:209], v[92:95]
	v_mfma_f32_16x16x32_bf16 v[84:87], v[166:169], v[206:209], v[84:87]
	v_mfma_f32_16x16x32_bf16 v[76:79], v[158:161], v[214:217], v[76:79]
	v_mfma_f32_16x16x32_bf16 v[68:71], v[166:169], v[214:217], v[68:71]
	v_mfma_f32_16x16x32_bf16 v[124:127], v[162:165], v[194:197], v[124:127]
	v_mfma_f32_16x16x32_bf16 v[116:119], v[170:173], v[194:197], v[116:119]
	v_mfma_f32_16x16x32_bf16 v[108:111], v[162:165], v[202:205], v[108:111]
	v_mfma_f32_16x16x32_bf16 v[100:103], v[170:173], v[202:205], v[100:103]
	v_mfma_f32_16x16x32_bf16 v[92:95], v[162:165], v[210:213], v[92:95]
	v_mfma_f32_16x16x32_bf16 v[84:87], v[170:173], v[210:213], v[84:87]
	v_mfma_f32_16x16x32_bf16 v[76:79], v[162:165], v[228:231], v[76:79]
	v_mfma_f32_16x16x32_bf16 v[68:71], v[170:173], v[228:231], v[68:71]
	v_mfma_f32_16x16x32_bf16 v[120:123], v[174:177], v[190:193], v[120:123]
	v_mfma_f32_16x16x32_bf16 v[112:115], v[182:185], v[190:193], v[112:115]
	v_mfma_f32_16x16x32_bf16 v[104:107], v[174:177], v[198:201], v[104:107]
	v_mfma_f32_16x16x32_bf16 v[96:99], v[182:185], v[198:201], v[96:99]
	v_mfma_f32_16x16x32_bf16 v[88:91], v[174:177], v[206:209], v[88:91]
	v_mfma_f32_16x16x32_bf16 v[80:83], v[182:185], v[206:209], v[80:83]
	v_mfma_f32_16x16x32_bf16 v[72:75], v[174:177], v[214:217], v[72:75]
	v_mfma_f32_16x16x32_bf16 v[64:67], v[182:185], v[214:217], v[64:67]
	v_mfma_f32_16x16x32_bf16 v[120:123], v[178:181], v[194:197], v[120:123]
	v_mfma_f32_16x16x32_bf16 v[112:115], v[186:189], v[194:197], v[112:115]
	v_mfma_f32_16x16x32_bf16 v[104:107], v[178:181], v[202:205], v[104:107]
	v_mfma_f32_16x16x32_bf16 v[96:99], v[186:189], v[202:205], v[96:99]
	v_mfma_f32_16x16x32_bf16 v[88:91], v[178:181], v[210:213], v[88:91]
	v_mfma_f32_16x16x32_bf16 v[80:83], v[186:189], v[210:213], v[80:83]
	v_mfma_f32_16x16x32_bf16 v[72:75], v[178:181], v[228:231], v[72:75]
	v_mfma_f32_16x16x32_bf16 v[64:67], v[186:189], v[228:231], v[64:67]
	s_setprio 0
	s_barrier
	s_add_i32 s56, s56, s37
	v_lshl_add_u64 v[218:219], s[54:55], 0, v[132:133]
	s_mov_b32 m0, s56
	ds_read_b128 v[190:193], v157 offset:16384
	ds_read_b128 v[194:197], v157 offset:17408
	ds_read_b128 v[198:201], v157 offset:18432
	ds_read_b128 v[202:205], v157 offset:19456
	ds_read_b128 v[206:209], v157 offset:20480
	ds_read_b128 v[210:213], v157 offset:21504
	ds_read_b128 v[214:217], v157 offset:22528
	ds_read_b128 v[228:231], v157 offset:23552
	global_load_lds_dwordx4 v[218:219], off
	s_add_i32 m0, s56, 0x2000
	v_lshl_add_u64 v[232:233], s[54:55], 0, v[128:129]
	s_add_u32 s54, s54, s0
	s_addc_u32 s55, s55, s1
	s_add_i32 s56, s57, s37
	global_load_lds_dwordx4 v[232:233], off
	v_lshl_add_u64 v[234:235], s[54:55], 0, v[132:133]
	s_mov_b32 m0, s56
	v_lshl_add_u64 v[236:237], s[54:55], 0, v[128:129]
	global_load_lds_dwordx4 v[234:235], off
	s_add_i32 m0, s56, 0x2000
	v_lshl_add_u64 v[238:239], s[26:27], 0, v[134:135]
	global_load_lds_dwordx4 v[236:237], off
	s_mov_b32 m0, s25
	v_lshl_add_u64 v[240:241], s[26:27], 0, v[130:131]
	global_load_lds_dwordx4 v[238:239], off
	s_mov_b32 m0, s39
	s_nop 0
	global_load_lds_dwordx4 v[240:241], off
	s_waitcnt vmcnt(8)
	s_waitcnt lgkmcnt(0)
	s_barrier
; #define PG8_STAGE(bufoff, gbase, voff) do { _Pragma("unroll") for (int _i = 0; _i < 2; ++_i) \
;         __builtin_amdgcn_global_load_lds((const unsigned*)((const char*)(gbase) + (voff)[_i]), (LAS unsigned*)(lds + (bufoff) + ldsw + _i * 8192), 16, 0, 0); } while (0)
; #define PG8_LDA(dst, b, h) do { _Pragma("unroll") for (int m = 0; m < 4; ++m) _Pragma("unroll") for (int k = 0; k < 2; ++k) dst[m][k] = *(const LAS bf16x8*)(lds + PG8_SA(b, h) + aoff + m * 2048 + k * 1024); } while (0)
; #define PG8_LDB(dst, b, h) do { _Pragma("unroll") for (int n = 0; n < 2; ++n) _Pragma("unroll") for (int k = 0; k < 2; ++k) dst[n][k] = *(const LAS bf16x8*)(lds + PG8_SB(b, h) + boff + n * 2048 + k * 1024); } while (0)
; #define PG8_MMA(ai, bj, At, Bt) do { __builtin_amdgcn_s_setprio(1); _Pragma("unroll") for (int m = 0; m < 4; ++m) _Pragma("unroll") for (int n = 0; n < 2; ++n) _Pragma("unroll") for (int k = 0; k < 2; ++k) \
;         acc[ai][bj][m][n] = __builtin_amdgcn_mfma_f32_16x16x32_bf16(Bt[n][k], At[m][k], acc[ai][bj][m][n], 0, 0, 0); __builtin_amdgcn_s_setprio(0); } while (0)
; #define PG8_WAIT_V(n) asm volatile("s_waitcnt vmcnt(" #n ")" ::: "memory")
; #define PG8_WAIT_L(n) asm volatile("s_waitcnt lgkmcnt(" #n ")" ::: "memory")
; #define PG8_BAR __builtin_amdgcn_s_barrier()
; #define PG8_SCHED __builtin_amdgcn_sched_barrier(0)
;     ...
;             PG8_WAIT_V(8); PG8_WAIT_L(0); PG8_BAR; PG8_MMA(1, 0, At, B0); PG8_MMA(1, 1, At, B1); PG8_BAR; PG8_SCHED;
;             PG8_LDB(B0, 1, 0); PG8_LDB(B1, 1, 1); PG8_SCHED; PG8_LDA(At, 1, 0); PG8_STAGE(PG8_SA(0, 1), a2 + hstepA, voffA);
;             PG8_WAIT_V(8); PG8_WAIT_L(0); PG8_BAR; PG8_MMA(0, 0, At, B0); PG8_MMA(0, 1, At, B1); PG8_BAR; PG8_SCHED;
	s_setprio 1
	s_waitcnt lgkmcnt(0)
	v_mfma_f32_16x16x32_bf16 v[60:63], v[158:161], v[190:193], v[60:63]
	v_mfma_f32_16x16x32_bf16 v[52:55], v[166:169], v[190:193], v[52:55]
	v_mfma_f32_16x16x32_bf16 v[44:47], v[158:161], v[198:201], v[44:47]
	v_mfma_f32_16x16x32_bf16 v[36:39], v[166:169], v[198:201], v[36:39]
	v_mfma_f32_16x16x32_bf16 v[28:31], v[158:161], v[206:209], v[28:31]
	v_mfma_f32_16x16x32_bf16 v[20:23], v[166:169], v[206:209], v[20:23]
	v_mfma_f32_16x16x32_bf16 v[12:15], v[158:161], v[214:217], v[12:15]
	v_mfma_f32_16x16x32_bf16 v[4:7], v[166:169], v[214:217], v[4:7]
	v_mfma_f32_16x16x32_bf16 v[60:63], v[162:165], v[194:197], v[60:63]
	v_mfma_f32_16x16x32_bf16 v[52:55], v[170:173], v[194:197], v[52:55]
	v_mfma_f32_16x16x32_bf16 v[44:47], v[162:165], v[202:205], v[44:47]
	v_mfma_f32_16x16x32_bf16 v[36:39], v[170:173], v[202:205], v[36:39]
	v_mfma_f32_16x16x32_bf16 v[28:31], v[162:165], v[210:213], v[28:31]
	v_mfma_f32_16x16x32_bf16 v[20:23], v[170:173], v[210:213], v[20:23]
	v_mfma_f32_16x16x32_bf16 v[12:15], v[162:165], v[228:231], v[12:15]
	v_mfma_f32_16x16x32_bf16 v[4:7], v[170:173], v[228:231], v[4:7]
	v_mfma_f32_16x16x32_bf16 v[56:59], v[174:177], v[190:193], v[56:59]
	v_mfma_f32_16x16x32_bf16 v[48:51], v[182:185], v[190:193], v[48:51]
	v_mfma_f32_16x16x32_bf16 v[40:43], v[174:177], v[198:201], v[40:43]
	v_mfma_f32_16x16x32_bf16 v[32:35], v[182:185], v[198:201], v[32:35]
	v_mfma_f32_16x16x32_bf16 v[24:27], v[174:177], v[206:209], v[24:27]
	v_mfma_f32_16x16x32_bf16 v[16:19], v[182:185], v[206:209], v[16:19]
	v_mfma_f32_16x16x32_bf16 v[8:11], v[174:177], v[214:217], v[8:11]
	v_mfma_f32_16x16x32_bf16 v[0:3], v[182:185], v[214:217], v[0:3]
	v_mfma_f32_16x16x32_bf16 v[56:59], v[178:181], v[194:197], v[56:59]
	v_mfma_f32_16x16x32_bf16 v[48:51], v[186:189], v[194:197], v[48:51]
	v_mfma_f32_16x16x32_bf16 v[40:43], v[178:181], v[202:205], v[40:43]
	v_mfma_f32_16x16x32_bf16 v[32:35], v[186:189], v[202:205], v[32:35]
	v_mfma_f32_16x16x32_bf16 v[24:27], v[178:181], v[210:213], v[24:27]
	v_mfma_f32_16x16x32_bf16 v[16:19], v[186:189], v[210:213], v[16:19]
	v_mfma_f32_16x16x32_bf16 v[8:11], v[178:181], v[228:231], v[8:11]
	v_mfma_f32_16x16x32_bf16 v[0:3], v[186:189], v[228:231], v[0:3]
	s_setprio 0
	s_barrier
	s_add_i32 s54, 0, 0x18000
	v_add_u32_e32 v152, s54, v143
	s_add_i32 s55, 0, 0x1c000
	ds_read_b128 v[158:161], v152
	ds_read_b128 v[162:165], v152 offset:1024
	ds_read_b128 v[166:169], v152 offset:2048
	ds_read_b128 v[170:173], v152 offset:3072
	v_add_u32_e32 v152, s55, v143
	ds_read_b128 v[174:177], v152
	ds_read_b128 v[178:181], v152 offset:1024
	ds_read_b128 v[182:185], v152 offset:2048
	ds_read_b128 v[186:189], v152 offset:3072
	s_add_u32 s26, s26, 0x40000
	s_addc_u32 s27, s27, 0
	s_mov_b32 m0, s40
	v_lshl_add_u64 v[242:243], s[26:27], 0, v[134:135]
	ds_read_b128 v[190:193], v157 offset:32768
	ds_read_b128 v[194:197], v157 offset:33792
	ds_read_b128 v[198:201], v157 offset:34816
	ds_read_b128 v[202:205], v157 offset:35840
	ds_read_b128 v[206:209], v157 offset:36864
	ds_read_b128 v[210:213], v157 offset:37888
	ds_read_b128 v[214:217], v157 offset:38912
	ds_read_b128 v[228:231], v157 offset:39936
	global_load_lds_dwordx4 v[242:243], off
	v_lshl_add_u64 v[242:243], s[26:27], 0, v[130:131]
	s_mov_b32 m0, s41
	s_nop 0
	global_load_lds_dwordx4 v[242:243], off
	s_waitcnt vmcnt(8)
	s_waitcnt lgkmcnt(0)
	s_barrier
	s_setprio 1
	s_waitcnt lgkmcnt(0)
	v_mfma_f32_16x16x32_bf16 v[124:127], v[158:161], v[190:193], v[124:127]
	v_mfma_f32_16x16x32_bf16 v[116:119], v[166:169], v[190:193], v[116:119]
	v_mfma_f32_16x16x32_bf16 v[108:111], v[158:161], v[198:201], v[108:111]
	v_mfma_f32_16x16x32_bf16 v[100:103], v[166:169], v[198:201], v[100:103]
	v_mfma_f32_16x16x32_bf16 v[92:95], v[158:161], v[206:209], v[92:95]
	v_mfma_f32_16x16x32_bf16 v[84:87], v[166:169], v[206:209], v[84:87]
	v_mfma_f32_16x16x32_bf16 v[76:79], v[158:161], v[214:217], v[76:79]
	v_mfma_f32_16x16x32_bf16 v[68:71], v[166:169], v[214:217], v[68:71]
	v_mfma_f32_16x16x32_bf16 v[124:127], v[162:165], v[194:197], v[124:127]
	v_mfma_f32_16x16x32_bf16 v[116:119], v[170:173], v[194:197], v[116:119]
	v_mfma_f32_16x16x32_bf16 v[108:111], v[162:165], v[202:205], v[108:111]
	v_mfma_f32_16x16x32_bf16 v[100:103], v[170:173], v[202:205], v[100:103]
	v_mfma_f32_16x16x32_bf16 v[92:95], v[162:165], v[210:213], v[92:95]
	v_mfma_f32_16x16x32_bf16 v[84:87], v[170:173], v[210:213], v[84:87]
	v_mfma_f32_16x16x32_bf16 v[76:79], v[162:165], v[228:231], v[76:79]
	v_mfma_f32_16x16x32_bf16 v[68:71], v[170:173], v[228:231], v[68:71]
	v_mfma_f32_16x16x32_bf16 v[120:123], v[174:177], v[190:193], v[120:123]
	v_mfma_f32_16x16x32_bf16 v[112:115], v[182:185], v[190:193], v[112:115]
	v_mfma_f32_16x16x32_bf16 v[104:107], v[174:177], v[198:201], v[104:107]
	v_mfma_f32_16x16x32_bf16 v[96:99], v[182:185], v[198:201], v[96:99]
	v_mfma_f32_16x16x32_bf16 v[88:91], v[174:177], v[206:209], v[88:91]
	v_mfma_f32_16x16x32_bf16 v[80:83], v[182:185], v[206:209], v[80:83]
	v_mfma_f32_16x16x32_bf16 v[72:75], v[174:177], v[214:217], v[72:75]
	v_mfma_f32_16x16x32_bf16 v[64:67], v[182:185], v[214:217], v[64:67]
	v_mfma_f32_16x16x32_bf16 v[120:123], v[178:181], v[194:197], v[120:123]
	v_mfma_f32_16x16x32_bf16 v[112:115], v[186:189], v[194:197], v[112:115]
	v_mfma_f32_16x16x32_bf16 v[104:107], v[178:181], v[202:205], v[104:107]
	v_mfma_f32_16x16x32_bf16 v[96:99], v[186:189], v[202:205], v[96:99]
	v_mfma_f32_16x16x32_bf16 v[88:91], v[178:181], v[210:213], v[88:91]
	v_mfma_f32_16x16x32_bf16 v[80:83], v[186:189], v[210:213], v[80:83]
	v_mfma_f32_16x16x32_bf16 v[72:75], v[178:181], v[228:231], v[72:75]
	v_mfma_f32_16x16x32_bf16 v[64:67], v[186:189], v[228:231], v[64:67]
	s_setprio 0
	s_barrier
; #define PG8_STAGE(bufoff, gbase, voff) do { _Pragma("unroll") for (int _i = 0; _i < 2; ++_i) \
;         __builtin_amdgcn_global_load_lds((const unsigned*)((const char*)(gbase) + (voff)[_i]), (LAS unsigned*)(lds + (bufoff) + ldsw + _i * 8192), 16, 0, 0); } while (0)
; #define PG8_LDA(dst, b, h) do { _Pragma("unroll") for (int m = 0; m < 4; ++m) _Pragma("unroll") for (int k = 0; k < 2; ++k) dst[m][k] = *(const LAS bf16x8*)(lds + PG8_SA(b, h) + aoff + m * 2048 + k * 1024); } while (0)
; #define PG8_MMA(ai, bj, At, Bt) do { __builtin_amdgcn_s_setprio(1); _Pragma("unroll") for (int m = 0; m < 4; ++m) _Pragma("unroll") for (int n = 0; n < 2; ++n) _Pragma("unroll") for (int k = 0; k < 2; ++k) \
;         acc[ai][bj][m][n] = __builtin_amdgcn_mfma_f32_16x16x32_bf16(Bt[n][k], At[m][k], acc[ai][bj][m][n], 0, 0, 0); __builtin_amdgcn_s_setprio(0); } while (0)
; #define PG8_WAIT_V(n) asm volatile("s_waitcnt vmcnt(" #n ")" ::: "memory")
; #define PG8_WAIT_L(n) asm volatile("s_waitcnt lgkmcnt(" #n ")" ::: "memory")
; #define PG8_BAR __builtin_amdgcn_s_barrier()
; #define PG8_SCHED __builtin_amdgcn_sched_barrier(0)
;     ...
;         for (int t = 0; t < nt; t += 2) {
;             const bool last = (t == nt - 2);
;             const char* a1 = cA + (size_t)(t + 1) * kstep;
;             const char* a2 = last ? nA : cA + (size_t)(t + 2) * kstep; const char* b2 = last ? nB : cB + (size_t)(t + 2) * kstep;
;     ...
;             PG8_LDA(At, 1, 1); PG8_STAGE(PG8_SB(1, 0), b3, voffB); PG8_STAGE(PG8_SB(1, 1), b3 + hstepB, voffB); PG8_STAGE(PG8_SA(1, 0), a3, voffA);
;             PG8_WAIT_V(8); PG8_WAIT_L(0); PG8_BAR; PG8_MMA(1, 0, At, B0); PG8_MMA(1, 1, At, B1); PG8_BAR; PG8_SCHED;
	s_add_i32 s26, s54, s37
	v_lshl_add_u64 v[218:219], v[218:219], 0, s[58:59]
	s_mov_b32 m0, s26
	ds_read_b128 v[190:193], v157 offset:49152
	ds_read_b128 v[194:197], v157 offset:50176
	ds_read_b128 v[198:201], v157 offset:51200
	ds_read_b128 v[202:205], v157 offset:52224
	ds_read_b128 v[206:209], v157 offset:53248
	ds_read_b128 v[210:213], v157 offset:54272
	ds_read_b128 v[214:217], v157 offset:55296
	ds_read_b128 v[228:231], v157 offset:56320
	global_load_lds_dwordx4 v[218:219], off
	v_lshl_add_u64 v[218:219], v[232:233], 0, s[58:59]
	s_add_i32 m0, s26, 0x2000
	s_add_i32 s26, s55, s37
	global_load_lds_dwordx4 v[218:219], off
	v_lshl_add_u64 v[218:219], v[234:235], 0, s[58:59]
	s_mov_b32 m0, s26
	s_nop 0
	global_load_lds_dwordx4 v[218:219], off
	v_lshl_add_u64 v[218:219], v[236:237], 0, s[58:59]
	s_add_i32 m0, s26, 0x2000
	s_nop 0
	global_load_lds_dwordx4 v[218:219], off
	v_lshl_add_u64 v[218:219], v[238:239], 0, s[58:59]
	s_mov_b32 m0, s42
	s_nop 0
	global_load_lds_dwordx4 v[218:219], off
	v_lshl_add_u64 v[218:219], v[240:241], 0, s[58:59]
	s_mov_b32 m0, s43
	s_nop 0
	global_load_lds_dwordx4 v[218:219], off
	s_waitcnt vmcnt(8)
	s_waitcnt lgkmcnt(0)
	s_barrier
	s_setprio 1
	s_waitcnt lgkmcnt(0)
	v_mfma_f32_16x16x32_bf16 v[60:63], v[158:161], v[190:193], v[60:63]
	v_mfma_f32_16x16x32_bf16 v[52:55], v[166:169], v[190:193], v[52:55]
	v_mfma_f32_16x16x32_bf16 v[44:47], v[158:161], v[198:201], v[44:47]
	v_mfma_f32_16x16x32_bf16 v[36:39], v[166:169], v[198:201], v[36:39]
	v_mfma_f32_16x16x32_bf16 v[28:31], v[158:161], v[206:209], v[28:31]
	v_mfma_f32_16x16x32_bf16 v[20:23], v[166:169], v[206:209], v[20:23]
	v_mfma_f32_16x16x32_bf16 v[12:15], v[158:161], v[214:217], v[12:15]
	v_mfma_f32_16x16x32_bf16 v[4:7], v[166:169], v[214:217], v[4:7]
	v_mfma_f32_16x16x32_bf16 v[60:63], v[162:165], v[194:197], v[60:63]
	v_mfma_f32_16x16x32_bf16 v[52:55], v[170:173], v[194:197], v[52:55]
	v_mfma_f32_16x16x32_bf16 v[44:47], v[162:165], v[202:205], v[44:47]
	v_mfma_f32_16x16x32_bf16 v[36:39], v[170:173], v[202:205], v[36:39]
	v_mfma_f32_16x16x32_bf16 v[28:31], v[162:165], v[210:213], v[28:31]
	v_mfma_f32_16x16x32_bf16 v[20:23], v[170:173], v[210:213], v[20:23]
	v_mfma_f32_16x16x32_bf16 v[12:15], v[162:165], v[228:231], v[12:15]
	v_mfma_f32_16x16x32_bf16 v[4:7], v[170:173], v[228:231], v[4:7]
	v_mfma_f32_16x16x32_bf16 v[56:59], v[174:177], v[190:193], v[56:59]
	v_mfma_f32_16x16x32_bf16 v[48:51], v[182:185], v[190:193], v[48:51]
	v_mfma_f32_16x16x32_bf16 v[40:43], v[174:177], v[198:201], v[40:43]
	v_mfma_f32_16x16x32_bf16 v[32:35], v[182:185], v[198:201], v[32:35]
	v_mfma_f32_16x16x32_bf16 v[24:27], v[174:177], v[206:209], v[24:27]
	v_mfma_f32_16x16x32_bf16 v[16:19], v[182:185], v[206:209], v[16:19]
	v_mfma_f32_16x16x32_bf16 v[8:11], v[174:177], v[214:217], v[8:11]
	v_mfma_f32_16x16x32_bf16 v[0:3], v[182:185], v[214:217], v[0:3]
	v_mfma_f32_16x16x32_bf16 v[56:59], v[178:181], v[194:197], v[56:59]
	v_mfma_f32_16x16x32_bf16 v[48:51], v[186:189], v[194:197], v[48:51]
	v_mfma_f32_16x16x32_bf16 v[40:43], v[178:181], v[202:205], v[40:43]
	v_mfma_f32_16x16x32_bf16 v[32:35], v[186:189], v[202:205], v[32:35]
	v_mfma_f32_16x16x32_bf16 v[24:27], v[178:181], v[210:213], v[24:27]
	v_mfma_f32_16x16x32_bf16 v[16:19], v[186:189], v[210:213], v[16:19]
	v_mfma_f32_16x16x32_bf16 v[8:11], v[178:181], v[228:231], v[8:11]
	v_mfma_f32_16x16x32_bf16 v[0:3], v[186:189], v[228:231], v[0:3]
	s_setprio 0
	s_barrier
	s_add_u32 s12, s12, 0x100
	s_addc_u32 s13, s13, 0
	s_add_u32 s28, s28, 0x100
	s_addc_u32 s29, s29, 0
	s_cmp_ge_i32 s53, s44
	s_mov_b32 s26, s53
	s_cbranch_scc0 .LBB0_206

; #define PG8_STAGE(bufoff, gbase, voff) do { _Pragma("unroll") for (int _i = 0; _i < 2; ++_i) \
;         __builtin_amdgcn_global_load_lds((const unsigned*)((const char*)(gbase) + (voff)[_i]), (LAS unsigned*)(lds + (bufoff) + ldsw + _i * 8192), 16, 0, 0); } while (0)
; #define PG8_LDA(dst, b, h) do { _Pragma("unroll") for (int m = 0; m < 4; ++m) _Pragma("unroll") for (int k = 0; k < 2; ++k) dst[m][k] = *(const LAS bf16x8*)(lds + PG8_SA(b, h) + aoff + m * 2048 + k * 1024); } while (0)
; #define PG8_LDB(dst, b, h) do { _Pragma("unroll") for (int n = 0; n < 2; ++n) _Pragma("unroll") for (int k = 0; k < 2; ++k) dst[n][k] = *(const LAS bf16x8*)(lds + PG8_SB(b, h) + boff + n * 2048 + k * 1024); } while (0)
; #define PG8_MMA(ai, bj, At, Bt) do { __builtin_amdgcn_s_setprio(1); _Pragma("unroll") for (int m = 0; m < 4; ++m) _Pragma("unroll") for (int n = 0; n < 2; ++n) _Pragma("unroll") for (int k = 0; k < 2; ++k) \
;         acc[ai][bj][m][n] = __builtin_amdgcn_mfma_f32_16x16x32_bf16(Bt[n][k], At[m][k], acc[ai][bj][m][n], 0, 0, 0); __builtin_amdgcn_s_setprio(0); } while (0)
; #define PG8_WAIT_V(n) asm volatile("s_waitcnt vmcnt(" #n ")" ::: "memory")
; #define PG8_WAIT_L(n) asm volatile("s_waitcnt lgkmcnt(" #n ")" ::: "memory")
; #define PG8_BAR __builtin_amdgcn_s_barrier()
; #define PG8_SCHED __builtin_amdgcn_sched_barrier(0)
;     ...
;             const bool last = (t == nt - 2);
;             const char* a1 = cA + (size_t)(t + 1) * kstep;
;             const char* a2 = last ? nA : cA + (size_t)(t + 2) * kstep; const char* b2 = last ? nB : cB + (size_t)(t + 2) * kstep;
;             const char* a3 = a2 + kstep; const char* b3 = b2 + kstep;
;             if constexpr (SP2) {
;             PG8_LDB(B0, 0, 0); PG8_LDB(B1, 0, 1); PG8_SCHED; PG8_LDA(At, 0, 0); PG8_STAGE(PG8_SA(1, 1), a1 + hstepA, voffA);
;             PG8_WAIT_V(8); PG8_WAIT_L(0); PG8_BAR; PG8_MMA(0, 0, At, B0); PG8_MMA(0, 1, At, B1); PG8_BAR; PG8_SCHED;
;             PG8_LDA(At, 0, 1); PG8_STAGE(PG8_SB(0, 0), b2, voffB); PG8_STAGE(PG8_SB(0, 1), b2 + hstepB, voffB); PG8_STAGE(PG8_SA(0, 0), a2, voffA);
;             PG8_WAIT_V(8); PG8_WAIT_L(0); PG8_BAR; PG8_MMA(1, 0, At, B0); PG8_MMA(1, 1, At, B1); PG8_BAR; PG8_SCHED;
.LBB0_239:
	s_add_i32 s52, s8, 2
	s_add_u32 s4, s0, 0x100
	s_addc_u32 s5, s1, 0
	s_add_i32 s53, 0, 0x10000
	s_cmp_eq_u32 s44, s8
	s_cselect_b32 s9, s7, s5
	s_cselect_b32 s8, s6, s4
	v_add_u32_e32 v142, s53, v158
	s_cselect_b32 s55, s3, s15
	s_cselect_b32 s54, s2, s14
	s_add_i32 s56, 0, 0x14000
	ds_read_b128 v[160:163], v142
	ds_read_b128 v[164:167], v142 offset:1024
	ds_read_b128 v[168:171], v142 offset:2048
	ds_read_b128 v[172:175], v142 offset:3072
	v_add_u32_e32 v142, s56, v158
	ds_read_b128 v[176:179], v142
	ds_read_b128 v[180:183], v142 offset:1024
	ds_read_b128 v[184:187], v142 offset:2048
	ds_read_b128 v[188:191], v142 offset:3072
	v_lshl_add_u64 v[142:143], s[0:1], 0, v[138:139]
	s_add_i32 m0, s35, 0xc000
	ds_read_b128 v[192:195], v159
	ds_read_b128 v[196:199], v159 offset:1024
	ds_read_b128 v[200:203], v159 offset:2048
	ds_read_b128 v[204:207], v159 offset:3072
	ds_read_b128 v[208:211], v159 offset:4096
	ds_read_b128 v[212:215], v159 offset:5120
	ds_read_b128 v[216:219], v159 offset:6144
	ds_read_b128 v[228:231], v159 offset:7168
	global_load_lds_dwordx4 v[142:143], off
	v_lshl_add_u64 v[142:143], s[0:1], 0, v[140:141]
	s_add_i32 m0, s35, 0xe000
	s_nop 0
	global_load_lds_dwordx4 v[142:143], off
	s_waitcnt vmcnt(8)
	s_waitcnt lgkmcnt(0)
	s_barrier
	s_setprio 1
	s_waitcnt lgkmcnt(0)
	v_mfma_f32_16x16x32_bf16 v[124:127], v[160:163], v[192:195], v[124:127]
	v_mfma_f32_16x16x32_bf16 v[120:123], v[168:171], v[192:195], v[120:123]
	v_mfma_f32_16x16x32_bf16 v[108:111], v[160:163], v[200:203], v[108:111]
	v_mfma_f32_16x16x32_bf16 v[104:107], v[168:171], v[200:203], v[104:107]
	v_mfma_f32_16x16x32_bf16 v[92:95], v[160:163], v[208:211], v[92:95]
	v_mfma_f32_16x16x32_bf16 v[88:91], v[168:171], v[208:211], v[88:91]
	v_mfma_f32_16x16x32_bf16 v[76:79], v[160:163], v[216:219], v[76:79]
	v_mfma_f32_16x16x32_bf16 v[72:75], v[168:171], v[216:219], v[72:75]
	v_mfma_f32_16x16x32_bf16 v[124:127], v[164:167], v[196:199], v[124:127]
	v_mfma_f32_16x16x32_bf16 v[120:123], v[172:175], v[196:199], v[120:123]
	v_mfma_f32_16x16x32_bf16 v[108:111], v[164:167], v[204:207], v[108:111]
	v_mfma_f32_16x16x32_bf16 v[104:107], v[172:175], v[204:207], v[104:107]
	v_mfma_f32_16x16x32_bf16 v[92:95], v[164:167], v[212:215], v[92:95]
	v_mfma_f32_16x16x32_bf16 v[88:91], v[172:175], v[212:215], v[88:91]
	v_mfma_f32_16x16x32_bf16 v[76:79], v[164:167], v[228:231], v[76:79]
	v_mfma_f32_16x16x32_bf16 v[72:75], v[172:175], v[228:231], v[72:75]
	v_mfma_f32_16x16x32_bf16 v[116:119], v[176:179], v[192:195], v[116:119]
	v_mfma_f32_16x16x32_bf16 v[112:115], v[184:187], v[192:195], v[112:115]
	v_mfma_f32_16x16x32_bf16 v[100:103], v[176:179], v[200:203], v[100:103]
	v_mfma_f32_16x16x32_bf16 v[96:99], v[184:187], v[200:203], v[96:99]
	v_mfma_f32_16x16x32_bf16 v[84:87], v[176:179], v[208:211], v[84:87]
	v_mfma_f32_16x16x32_bf16 v[80:83], v[184:187], v[208:211], v[80:83]
	v_mfma_f32_16x16x32_bf16 v[68:71], v[176:179], v[216:219], v[68:71]
	v_mfma_f32_16x16x32_bf16 v[64:67], v[184:187], v[216:219], v[64:67]
	v_mfma_f32_16x16x32_bf16 v[116:119], v[180:183], v[196:199], v[116:119]
	v_mfma_f32_16x16x32_bf16 v[112:115], v[188:191], v[196:199], v[112:115]
	v_mfma_f32_16x16x32_bf16 v[100:103], v[180:183], v[204:207], v[100:103]
	v_mfma_f32_16x16x32_bf16 v[96:99], v[188:191], v[204:207], v[96:99]
	v_mfma_f32_16x16x32_bf16 v[84:87], v[180:183], v[212:215], v[84:87]
	v_mfma_f32_16x16x32_bf16 v[80:83], v[188:191], v[212:215], v[80:83]
	v_mfma_f32_16x16x32_bf16 v[68:71], v[180:183], v[228:231], v[68:71]
	v_mfma_f32_16x16x32_bf16 v[64:67], v[188:191], v[228:231], v[64:67]
	s_setprio 0
	s_barrier
	s_add_i32 s0, s53, s34
	v_lshl_add_u64 v[142:143], s[54:55], 0, v[130:131]
	s_mov_b32 m0, s0
	ds_read_b128 v[192:195], v159 offset:16384
	ds_read_b128 v[196:199], v159 offset:17408
	ds_read_b128 v[200:203], v159 offset:18432
	ds_read_b128 v[204:207], v159 offset:19456
	ds_read_b128 v[208:211], v159 offset:20480
	ds_read_b128 v[212:215], v159 offset:21504
	ds_read_b128 v[216:219], v159 offset:22528
	ds_read_b128 v[228:231], v159 offset:23552
	global_load_lds_dwordx4 v[142:143], off
	s_add_i32 m0, s0, 0x2000
	s_add_u32 s0, s54, s16
	v_lshl_add_u64 v[156:157], s[54:55], 0, v[134:135]
	s_addc_u32 s1, s55, s17
	s_add_i32 s53, s56, s34
	global_load_lds_dwordx4 v[156:157], off
	v_lshl_add_u64 v[232:233], s[0:1], 0, v[130:131]
	s_mov_b32 m0, s53
	v_lshl_add_u64 v[234:235], s[0:1], 0, v[134:135]
	global_load_lds_dwordx4 v[232:233], off
	s_add_i32 m0, s53, 0x2000
	v_lshl_add_u64 v[236:237], s[8:9], 0, v[128:129]
	global_load_lds_dwordx4 v[234:235], off
	s_mov_b32 m0, s35
	v_lshl_add_u64 v[238:239], s[8:9], 0, v[132:133]
	global_load_lds_dwordx4 v[236:237], off
	s_mov_b32 m0, s36
	s_nop 0
	global_load_lds_dwordx4 v[238:239], off
	s_waitcnt vmcnt(8)
	s_waitcnt lgkmcnt(0)
	s_barrier
; #define PG8_STAGE(bufoff, gbase, voff) do { _Pragma("unroll") for (int _i = 0; _i < 2; ++_i) \
;         __builtin_amdgcn_global_load_lds((const unsigned*)((const char*)(gbase) + (voff)[_i]), (LAS unsigned*)(lds + (bufoff) + ldsw + _i * 8192), 16, 0, 0); } while (0)
; #define PG8_LDA(dst, b, h) do { _Pragma("unroll") for (int m = 0; m < 4; ++m) _Pragma("unroll") for (int k = 0; k < 2; ++k) dst[m][k] = *(const LAS bf16x8*)(lds + PG8_SA(b, h) + aoff + m * 2048 + k * 1024); } while (0)
; #define PG8_LDB(dst, b, h) do { _Pragma("unroll") for (int n = 0; n < 2; ++n) _Pragma("unroll") for (int k = 0; k < 2; ++k) dst[n][k] = *(const LAS bf16x8*)(lds + PG8_SB(b, h) + boff + n * 2048 + k * 1024); } while (0)
; #define PG8_MMA(ai, bj, At, Bt) do { __builtin_amdgcn_s_setprio(1); _Pragma("unroll") for (int m = 0; m < 4; ++m) _Pragma("unroll") for (int n = 0; n < 2; ++n) _Pragma("unroll") for (int k = 0; k < 2; ++k) \
;         acc[ai][bj][m][n] = __builtin_amdgcn_mfma_f32_16x16x32_bf16(Bt[n][k], At[m][k], acc[ai][bj][m][n], 0, 0, 0); __builtin_amdgcn_s_setprio(0); } while (0)
; #define PG8_WAIT_V(n) asm volatile("s_waitcnt vmcnt(" #n ")" ::: "memory")
; #define PG8_WAIT_L(n) asm volatile("s_waitcnt lgkmcnt(" #n ")" ::: "memory")
; #define PG8_BAR __builtin_amdgcn_s_barrier()
; #define PG8_SCHED __builtin_amdgcn_sched_barrier(0)
;     ...
;             PG8_WAIT_V(8); PG8_WAIT_L(0); PG8_BAR; PG8_MMA(1, 0, At, B0); PG8_MMA(1, 1, At, B1); PG8_BAR; PG8_SCHED;
;             PG8_LDB(B0, 1, 0); PG8_LDB(B1, 1, 1); PG8_SCHED; PG8_LDA(At, 1, 0); PG8_STAGE(PG8_SA(0, 1), a2 + hstepA, voffA);
;             PG8_WAIT_V(8); PG8_WAIT_L(0); PG8_BAR; PG8_MMA(0, 0, At, B0); PG8_MMA(0, 1, At, B1); PG8_BAR; PG8_SCHED;
	s_setprio 1
	s_waitcnt lgkmcnt(0)
	v_mfma_f32_16x16x32_bf16 v[60:63], v[160:163], v[192:195], v[60:63]
	v_mfma_f32_16x16x32_bf16 v[56:59], v[168:171], v[192:195], v[56:59]
	v_mfma_f32_16x16x32_bf16 v[44:47], v[160:163], v[200:203], v[44:47]
	v_mfma_f32_16x16x32_bf16 v[40:43], v[168:171], v[200:203], v[40:43]
	v_mfma_f32_16x16x32_bf16 v[28:31], v[160:163], v[208:211], v[28:31]
	v_mfma_f32_16x16x32_bf16 v[24:27], v[168:171], v[208:211], v[24:27]
	v_mfma_f32_16x16x32_bf16 v[12:15], v[160:163], v[216:219], v[12:15]
	v_mfma_f32_16x16x32_bf16 v[8:11], v[168:171], v[216:219], v[8:11]
	v_mfma_f32_16x16x32_bf16 v[60:63], v[164:167], v[196:199], v[60:63]
	v_mfma_f32_16x16x32_bf16 v[56:59], v[172:175], v[196:199], v[56:59]
	v_mfma_f32_16x16x32_bf16 v[44:47], v[164:167], v[204:207], v[44:47]
	v_mfma_f32_16x16x32_bf16 v[40:43], v[172:175], v[204:207], v[40:43]
	v_mfma_f32_16x16x32_bf16 v[28:31], v[164:167], v[212:215], v[28:31]
	v_mfma_f32_16x16x32_bf16 v[24:27], v[172:175], v[212:215], v[24:27]
	v_mfma_f32_16x16x32_bf16 v[12:15], v[164:167], v[228:231], v[12:15]
	v_mfma_f32_16x16x32_bf16 v[8:11], v[172:175], v[228:231], v[8:11]
	v_mfma_f32_16x16x32_bf16 v[52:55], v[176:179], v[192:195], v[52:55]
	v_mfma_f32_16x16x32_bf16 v[48:51], v[184:187], v[192:195], v[48:51]
	v_mfma_f32_16x16x32_bf16 v[36:39], v[176:179], v[200:203], v[36:39]
	v_mfma_f32_16x16x32_bf16 v[32:35], v[184:187], v[200:203], v[32:35]
	v_mfma_f32_16x16x32_bf16 v[20:23], v[176:179], v[208:211], v[20:23]
	v_mfma_f32_16x16x32_bf16 v[16:19], v[184:187], v[208:211], v[16:19]
	v_mfma_f32_16x16x32_bf16 v[4:7], v[176:179], v[216:219], v[4:7]
	v_mfma_f32_16x16x32_bf16 v[0:3], v[184:187], v[216:219], v[0:3]
	v_mfma_f32_16x16x32_bf16 v[52:55], v[180:183], v[196:199], v[52:55]
	v_mfma_f32_16x16x32_bf16 v[48:51], v[188:191], v[196:199], v[48:51]
	v_mfma_f32_16x16x32_bf16 v[36:39], v[180:183], v[204:207], v[36:39]
	v_mfma_f32_16x16x32_bf16 v[32:35], v[188:191], v[204:207], v[32:35]
	v_mfma_f32_16x16x32_bf16 v[20:23], v[180:183], v[212:215], v[20:23]
	v_mfma_f32_16x16x32_bf16 v[16:19], v[188:191], v[212:215], v[16:19]
	v_mfma_f32_16x16x32_bf16 v[4:7], v[180:183], v[228:231], v[4:7]
	v_mfma_f32_16x16x32_bf16 v[0:3], v[188:191], v[228:231], v[0:3]
	s_setprio 0
	s_barrier
	s_add_i32 s53, 0, 0x18000
	v_add_u32_e32 v146, s53, v158
	s_add_i32 s54, 0, 0x1c000
	ds_read_b128 v[160:163], v146
	ds_read_b128 v[164:167], v146 offset:1024
	ds_read_b128 v[168:171], v146 offset:2048
	ds_read_b128 v[172:175], v146 offset:3072
	v_add_u32_e32 v146, s54, v158
	ds_read_b128 v[176:179], v146
	ds_read_b128 v[180:183], v146 offset:1024
	ds_read_b128 v[184:187], v146 offset:2048
	ds_read_b128 v[188:191], v146 offset:3072
	s_add_u32 s0, s8, 0xe0000
	s_addc_u32 s1, s9, 0
	s_mov_b32 m0, s37
	v_lshl_add_u64 v[240:241], s[0:1], 0, v[128:129]
	ds_read_b128 v[192:195], v159 offset:32768
	ds_read_b128 v[196:199], v159 offset:33792
	ds_read_b128 v[200:203], v159 offset:34816
	ds_read_b128 v[204:207], v159 offset:35840
	ds_read_b128 v[208:211], v159 offset:36864
	ds_read_b128 v[212:215], v159 offset:37888
	ds_read_b128 v[216:219], v159 offset:38912
	ds_read_b128 v[228:231], v159 offset:39936
	global_load_lds_dwordx4 v[240:241], off
	v_lshl_add_u64 v[240:241], s[0:1], 0, v[132:133]
	s_mov_b32 m0, s38
	s_nop 0
	global_load_lds_dwordx4 v[240:241], off
	s_waitcnt vmcnt(8)
	s_waitcnt lgkmcnt(0)
	s_barrier
	s_setprio 1
	s_waitcnt lgkmcnt(0)
	v_mfma_f32_16x16x32_bf16 v[124:127], v[160:163], v[192:195], v[124:127]
	v_mfma_f32_16x16x32_bf16 v[120:123], v[168:171], v[192:195], v[120:123]
	v_mfma_f32_16x16x32_bf16 v[108:111], v[160:163], v[200:203], v[108:111]
	v_mfma_f32_16x16x32_bf16 v[104:107], v[168:171], v[200:203], v[104:107]
	v_mfma_f32_16x16x32_bf16 v[92:95], v[160:163], v[208:211], v[92:95]
	v_mfma_f32_16x16x32_bf16 v[88:91], v[168:171], v[208:211], v[88:91]
	v_mfma_f32_16x16x32_bf16 v[76:79], v[160:163], v[216:219], v[76:79]
	v_mfma_f32_16x16x32_bf16 v[72:75], v[168:171], v[216:219], v[72:75]
	v_mfma_f32_16x16x32_bf16 v[124:127], v[164:167], v[196:199], v[124:127]
	v_mfma_f32_16x16x32_bf16 v[120:123], v[172:175], v[196:199], v[120:123]
	v_mfma_f32_16x16x32_bf16 v[108:111], v[164:167], v[204:207], v[108:111]
	v_mfma_f32_16x16x32_bf16 v[104:107], v[172:175], v[204:207], v[104:107]
	v_mfma_f32_16x16x32_bf16 v[92:95], v[164:167], v[212:215], v[92:95]
	v_mfma_f32_16x16x32_bf16 v[88:91], v[172:175], v[212:215], v[88:91]
	v_mfma_f32_16x16x32_bf16 v[76:79], v[164:167], v[228:231], v[76:79]
	v_mfma_f32_16x16x32_bf16 v[72:75], v[172:175], v[228:231], v[72:75]
	v_mfma_f32_16x16x32_bf16 v[116:119], v[176:179], v[192:195], v[116:119]
	v_mfma_f32_16x16x32_bf16 v[112:115], v[184:187], v[192:195], v[112:115]
	v_mfma_f32_16x16x32_bf16 v[100:103], v[176:179], v[200:203], v[100:103]
	v_mfma_f32_16x16x32_bf16 v[96:99], v[184:187], v[200:203], v[96:99]
	v_mfma_f32_16x16x32_bf16 v[84:87], v[176:179], v[208:211], v[84:87]
	v_mfma_f32_16x16x32_bf16 v[80:83], v[184:187], v[208:211], v[80:83]
	v_mfma_f32_16x16x32_bf16 v[68:71], v[176:179], v[216:219], v[68:71]
	v_mfma_f32_16x16x32_bf16 v[64:67], v[184:187], v[216:219], v[64:67]
	v_mfma_f32_16x16x32_bf16 v[116:119], v[180:183], v[196:199], v[116:119]
	v_mfma_f32_16x16x32_bf16 v[112:115], v[188:191], v[196:199], v[112:115]
	v_mfma_f32_16x16x32_bf16 v[100:103], v[180:183], v[204:207], v[100:103]
	v_mfma_f32_16x16x32_bf16 v[96:99], v[188:191], v[204:207], v[96:99]
	v_mfma_f32_16x16x32_bf16 v[84:87], v[180:183], v[212:215], v[84:87]
	v_mfma_f32_16x16x32_bf16 v[80:83], v[188:191], v[212:215], v[80:83]
	v_mfma_f32_16x16x32_bf16 v[68:71], v[180:183], v[228:231], v[68:71]
	v_mfma_f32_16x16x32_bf16 v[64:67], v[188:191], v[228:231], v[64:67]
	s_setprio 0
	s_barrier
; #define PG8_STAGE(bufoff, gbase, voff) do { _Pragma("unroll") for (int _i = 0; _i < 2; ++_i) \
;         __builtin_amdgcn_global_load_lds((const unsigned*)((const char*)(gbase) + (voff)[_i]), (LAS unsigned*)(lds + (bufoff) + ldsw + _i * 8192), 16, 0, 0); } while (0)
; #define PG8_LDA(dst, b, h) do { _Pragma("unroll") for (int m = 0; m < 4; ++m) _Pragma("unroll") for (int k = 0; k < 2; ++k) dst[m][k] = *(const LAS bf16x8*)(lds + PG8_SA(b, h) + aoff + m * 2048 + k * 1024); } while (0)
; #define PG8_MMA(ai, bj, At, Bt) do { __builtin_amdgcn_s_setprio(1); _Pragma("unroll") for (int m = 0; m < 4; ++m) _Pragma("unroll") for (int n = 0; n < 2; ++n) _Pragma("unroll") for (int k = 0; k < 2; ++k) \
;         acc[ai][bj][m][n] = __builtin_amdgcn_mfma_f32_16x16x32_bf16(Bt[n][k], At[m][k], acc[ai][bj][m][n], 0, 0, 0); __builtin_amdgcn_s_setprio(0); } while (0)
; #define PG8_WAIT_V(n) asm volatile("s_waitcnt vmcnt(" #n ")" ::: "memory")
; #define PG8_WAIT_L(n) asm volatile("s_waitcnt lgkmcnt(" #n ")" ::: "memory")
; #define PG8_BAR __builtin_amdgcn_s_barrier()
; #define PG8_SCHED __builtin_amdgcn_sched_barrier(0)
;     ...
;         for (int t = 0; t < nt; t += 2) {
;             const bool last = (t == nt - 2);
;             const char* a1 = cA + (size_t)(t + 1) * kstep;
;             const char* a2 = last ? nA : cA + (size_t)(t + 2) * kstep; const char* b2 = last ? nB : cB + (size_t)(t + 2) * kstep;
;     ...
;             PG8_LDA(At, 1, 1); PG8_STAGE(PG8_SB(1, 0), b3, voffB); PG8_STAGE(PG8_SB(1, 1), b3 + hstepB, voffB); PG8_STAGE(PG8_SA(1, 0), a3, voffA);
;             PG8_WAIT_V(8); PG8_WAIT_L(0); PG8_BAR; PG8_MMA(1, 0, At, B0); PG8_MMA(1, 1, At, B1); PG8_BAR; PG8_SCHED;
	s_add_i32 s0, s53, s34
	v_lshl_add_u64 v[142:143], v[142:143], 0, s[58:59]
	s_mov_b32 m0, s0
	ds_read_b128 v[192:195], v159 offset:49152
	ds_read_b128 v[196:199], v159 offset:50176
	ds_read_b128 v[200:203], v159 offset:51200
	ds_read_b128 v[204:207], v159 offset:52224
	ds_read_b128 v[208:211], v159 offset:53248
	ds_read_b128 v[212:215], v159 offset:54272
	ds_read_b128 v[216:219], v159 offset:55296
	ds_read_b128 v[228:231], v159 offset:56320
	global_load_lds_dwordx4 v[142:143], off
	v_lshl_add_u64 v[142:143], v[156:157], 0, s[58:59]
	s_add_i32 m0, s0, 0x2000
	s_add_i32 s0, s54, s34
	global_load_lds_dwordx4 v[142:143], off
	v_lshl_add_u64 v[142:143], v[232:233], 0, s[58:59]
	s_mov_b32 m0, s0
	s_nop 0
	global_load_lds_dwordx4 v[142:143], off
	v_lshl_add_u64 v[142:143], v[234:235], 0, s[58:59]
	s_add_i32 m0, s0, 0x2000
	s_nop 0
	global_load_lds_dwordx4 v[142:143], off
	v_lshl_add_u64 v[142:143], v[236:237], 0, s[58:59]
	s_mov_b32 m0, s39
	s_nop 0
	global_load_lds_dwordx4 v[142:143], off
	v_lshl_add_u64 v[142:143], v[238:239], 0, s[58:59]
	s_mov_b32 m0, s40
	s_nop 0
	global_load_lds_dwordx4 v[142:143], off
	s_waitcnt vmcnt(8)
	s_waitcnt lgkmcnt(0)
	s_barrier
	s_setprio 1
	s_waitcnt lgkmcnt(0)
	v_mfma_f32_16x16x32_bf16 v[60:63], v[160:163], v[192:195], v[60:63]
	v_mfma_f32_16x16x32_bf16 v[56:59], v[168:171], v[192:195], v[56:59]
	v_mfma_f32_16x16x32_bf16 v[44:47], v[160:163], v[200:203], v[44:47]
	v_mfma_f32_16x16x32_bf16 v[40:43], v[168:171], v[200:203], v[40:43]
	v_mfma_f32_16x16x32_bf16 v[28:31], v[160:163], v[208:211], v[28:31]
	v_mfma_f32_16x16x32_bf16 v[24:27], v[168:171], v[208:211], v[24:27]
	v_mfma_f32_16x16x32_bf16 v[12:15], v[160:163], v[216:219], v[12:15]
	v_mfma_f32_16x16x32_bf16 v[8:11], v[168:171], v[216:219], v[8:11]
	v_mfma_f32_16x16x32_bf16 v[60:63], v[164:167], v[196:199], v[60:63]
	v_mfma_f32_16x16x32_bf16 v[56:59], v[172:175], v[196:199], v[56:59]
	v_mfma_f32_16x16x32_bf16 v[44:47], v[164:167], v[204:207], v[44:47]
	v_mfma_f32_16x16x32_bf16 v[40:43], v[172:175], v[204:207], v[40:43]
	v_mfma_f32_16x16x32_bf16 v[28:31], v[164:167], v[212:215], v[28:31]
	v_mfma_f32_16x16x32_bf16 v[24:27], v[172:175], v[212:215], v[24:27]
	v_mfma_f32_16x16x32_bf16 v[12:15], v[164:167], v[228:231], v[12:15]
	v_mfma_f32_16x16x32_bf16 v[8:11], v[172:175], v[228:231], v[8:11]
	v_mfma_f32_16x16x32_bf16 v[52:55], v[176:179], v[192:195], v[52:55]
	v_mfma_f32_16x16x32_bf16 v[48:51], v[184:187], v[192:195], v[48:51]
	v_mfma_f32_16x16x32_bf16 v[36:39], v[176:179], v[200:203], v[36:39]
	v_mfma_f32_16x16x32_bf16 v[32:35], v[184:187], v[200:203], v[32:35]
	v_mfma_f32_16x16x32_bf16 v[20:23], v[176:179], v[208:211], v[20:23]
	v_mfma_f32_16x16x32_bf16 v[16:19], v[184:187], v[208:211], v[16:19]
	v_mfma_f32_16x16x32_bf16 v[4:7], v[176:179], v[216:219], v[4:7]
	v_mfma_f32_16x16x32_bf16 v[0:3], v[184:187], v[216:219], v[0:3]
	v_mfma_f32_16x16x32_bf16 v[52:55], v[180:183], v[196:199], v[52:55]
	v_mfma_f32_16x16x32_bf16 v[48:51], v[188:191], v[196:199], v[48:51]
	v_mfma_f32_16x16x32_bf16 v[36:39], v[180:183], v[204:207], v[36:39]
	v_mfma_f32_16x16x32_bf16 v[32:35], v[188:191], v[204:207], v[32:35]
	v_mfma_f32_16x16x32_bf16 v[20:23], v[180:183], v[212:215], v[20:23]
	v_mfma_f32_16x16x32_bf16 v[16:19], v[188:191], v[212:215], v[16:19]
	v_mfma_f32_16x16x32_bf16 v[4:7], v[180:183], v[228:231], v[4:7]
	v_mfma_f32_16x16x32_bf16 v[0:3], v[188:191], v[228:231], v[0:3]
	s_setprio 0
	s_barrier
	s_add_u32 s14, s14, 0x100
	s_addc_u32 s15, s15, 0
	s_cmp_ge_i32 s52, s42
	s_mov_b64 s[0:1], s[4:5]
	s_mov_b32 s8, s52
	s_cbranch_scc0 .LBB0_239

; #define PG8_STAGE(bufoff, gbase, voff) do { _Pragma("unroll") for (int _i = 0; _i < 2; ++_i) \
;         __builtin_amdgcn_global_load_lds((const unsigned*)((const char*)(gbase) + (voff)[_i]), (LAS unsigned*)(lds + (bufoff) + ldsw + _i * 8192), 16, 0, 0); } while (0)
; #define PG8_LDA(dst, b, h) do { _Pragma("unroll") for (int m = 0; m < 4; ++m) _Pragma("unroll") for (int k = 0; k < 2; ++k) dst[m][k] = *(const LAS bf16x8*)(lds + PG8_SA(b, h) + aoff + m * 2048 + k * 1024); } while (0)
; #define PG8_LDB(dst, b, h) do { _Pragma("unroll") for (int n = 0; n < 2; ++n) _Pragma("unroll") for (int k = 0; k < 2; ++k) dst[n][k] = *(const LAS bf16x8*)(lds + PG8_SB(b, h) + boff + n * 2048 + k * 1024); } while (0)
; #define PG8_MMA(ai, bj, At, Bt) do { __builtin_amdgcn_s_setprio(1); _Pragma("unroll") for (int m = 0; m < 4; ++m) _Pragma("unroll") for (int n = 0; n < 2; ++n) _Pragma("unroll") for (int k = 0; k < 2; ++k) \
;         acc[ai][bj][m][n] = __builtin_amdgcn_mfma_f32_16x16x32_bf16(Bt[n][k], At[m][k], acc[ai][bj][m][n], 0, 0, 0); __builtin_amdgcn_s_setprio(0); } while (0)
; #define PG8_WAIT_V(n) asm volatile("s_waitcnt vmcnt(" #n ")" ::: "memory")
; #define PG8_WAIT_L(n) asm volatile("s_waitcnt lgkmcnt(" #n ")" ::: "memory")
; #define PG8_BAR __builtin_amdgcn_s_barrier()
; #define PG8_SCHED __builtin_amdgcn_sched_barrier(0)
;     ...
;             const bool last = (t == nt - 2);
;             const char* a1 = cA + (size_t)(t + 1) * kstep;
;             const char* a2 = last ? nA : cA + (size_t)(t + 2) * kstep; const char* b2 = last ? nB : cB + (size_t)(t + 2) * kstep;
;             const char* a3 = a2 + kstep; const char* b3 = b2 + kstep;
;             if constexpr (SP2) {
;             PG8_LDB(B0, 0, 0); PG8_LDB(B1, 0, 1); PG8_SCHED; PG8_LDA(At, 0, 0); PG8_STAGE(PG8_SA(1, 1), a1 + hstepA, voffA);
;             PG8_WAIT_V(8); PG8_WAIT_L(0); PG8_BAR; PG8_MMA(0, 0, At, B0); PG8_MMA(0, 1, At, B1); PG8_BAR; PG8_SCHED;
;             PG8_LDA(At, 0, 1); PG8_STAGE(PG8_SB(0, 0), b2, voffB); PG8_STAGE(PG8_SB(0, 1), b2 + hstepB, voffB); PG8_STAGE(PG8_SA(0, 0), a2, voffA);
;             PG8_WAIT_V(8); PG8_WAIT_L(0); PG8_BAR; PG8_MMA(1, 0, At, B0); PG8_MMA(1, 1, At, B1); PG8_BAR; PG8_SCHED;
.LBB0_285:
	s_add_i32 s53, s28, 2
	s_add_u32 s54, s12, 0xfffe0080
	s_addc_u32 s29, s13, -1
	s_add_i32 s56, 0, 0x10000
	s_cmp_eq_u32 s49, s28
	s_cselect_b32 s29, s17, s29
	s_cselect_b32 s28, s19, s54
	v_add_u32_e32 v152, s56, v167
	s_cselect_b32 s55, s23, s31
	s_cselect_b32 s54, s22, s30
	s_add_i32 s57, 0, 0x14000
	ds_read_b128 v[112:115], v152
	ds_read_b128 v[116:119], v152 offset:1024
	ds_read_b128 v[158:161], v152 offset:2048
	ds_read_b128 v[162:165], v152 offset:3072
	v_add_u32_e32 v152, s57, v167
	ds_read_b128 v[170:173], v152
	ds_read_b128 v[174:177], v152 offset:1024
	ds_read_b128 v[178:181], v152 offset:2048
	ds_read_b128 v[182:185], v152 offset:3072
	v_lshl_add_u64 v[218:219], s[12:13], 0, v[142:143]
	s_add_i32 m0, s27, 0xc000
	ds_read_b128 v[186:189], v169
	ds_read_b128 v[190:193], v169 offset:1024
	ds_read_b128 v[194:197], v169 offset:2048
	ds_read_b128 v[198:201], v169 offset:3072
	ds_read_b128 v[202:205], v169 offset:4096
	ds_read_b128 v[206:209], v169 offset:5120
	ds_read_b128 v[210:213], v169 offset:6144
	ds_read_b128 v[214:217], v169 offset:7168
	global_load_lds_dwordx4 v[218:219], off
	v_lshl_add_u64 v[218:219], s[12:13], 0, v[156:157]
	s_add_i32 m0, s27, 0xe000
	s_nop 0
	global_load_lds_dwordx4 v[218:219], off
	s_waitcnt vmcnt(8)
	s_waitcnt lgkmcnt(0)
	s_barrier
	s_setprio 1
	s_waitcnt lgkmcnt(0)
	v_mfma_f32_16x16x32_bf16 v[128:131], v[112:115], v[186:189], v[128:131]
	v_mfma_f32_16x16x32_bf16 v[132:135], v[158:161], v[186:189], v[132:135]
	v_mfma_f32_16x16x32_bf16 v[124:127], v[112:115], v[194:197], v[124:127]
	v_mfma_f32_16x16x32_bf16 v[120:123], v[158:161], v[194:197], v[120:123]
	v_mfma_f32_16x16x32_bf16 v[108:111], v[112:115], v[202:205], v[108:111]
	v_mfma_f32_16x16x32_bf16 v[104:107], v[158:161], v[202:205], v[104:107]
	v_mfma_f32_16x16x32_bf16 v[100:103], v[112:115], v[210:213], v[100:103]
	v_mfma_f32_16x16x32_bf16 v[96:99], v[158:161], v[210:213], v[96:99]
	v_mfma_f32_16x16x32_bf16 v[128:131], v[116:119], v[190:193], v[128:131]
	v_mfma_f32_16x16x32_bf16 v[132:135], v[162:165], v[190:193], v[132:135]
	v_mfma_f32_16x16x32_bf16 v[124:127], v[116:119], v[198:201], v[124:127]
	v_mfma_f32_16x16x32_bf16 v[120:123], v[162:165], v[198:201], v[120:123]
	v_mfma_f32_16x16x32_bf16 v[108:111], v[116:119], v[206:209], v[108:111]
	v_mfma_f32_16x16x32_bf16 v[104:107], v[162:165], v[206:209], v[104:107]
	v_mfma_f32_16x16x32_bf16 v[100:103], v[116:119], v[214:217], v[100:103]
	v_mfma_f32_16x16x32_bf16 v[96:99], v[162:165], v[214:217], v[96:99]
	v_mfma_f32_16x16x32_bf16 v[60:63], v[170:173], v[186:189], v[60:63]
	v_mfma_f32_16x16x32_bf16 v[56:59], v[178:181], v[186:189], v[56:59]
	v_mfma_f32_16x16x32_bf16 v[52:55], v[170:173], v[194:197], v[52:55]
	v_mfma_f32_16x16x32_bf16 v[48:51], v[178:181], v[194:197], v[48:51]
	v_mfma_f32_16x16x32_bf16 v[44:47], v[170:173], v[202:205], v[44:47]
	v_mfma_f32_16x16x32_bf16 v[40:43], v[178:181], v[202:205], v[40:43]
	v_mfma_f32_16x16x32_bf16 v[36:39], v[170:173], v[210:213], v[36:39]
	v_mfma_f32_16x16x32_bf16 v[32:35], v[178:181], v[210:213], v[32:35]
	v_mfma_f32_16x16x32_bf16 v[60:63], v[174:177], v[190:193], v[60:63]
	v_mfma_f32_16x16x32_bf16 v[56:59], v[182:185], v[190:193], v[56:59]
	v_mfma_f32_16x16x32_bf16 v[52:55], v[174:177], v[198:201], v[52:55]
	v_mfma_f32_16x16x32_bf16 v[48:51], v[182:185], v[198:201], v[48:51]
	v_mfma_f32_16x16x32_bf16 v[44:47], v[174:177], v[206:209], v[44:47]
	v_mfma_f32_16x16x32_bf16 v[40:43], v[182:185], v[206:209], v[40:43]
	v_mfma_f32_16x16x32_bf16 v[36:39], v[174:177], v[214:217], v[36:39]
	v_mfma_f32_16x16x32_bf16 v[32:35], v[182:185], v[214:217], v[32:35]
	s_setprio 0
	s_barrier
	s_add_i32 s56, s56, s42
	v_lshl_add_u64 v[218:219], s[54:55], 0, v[146:147]
	s_mov_b32 m0, s56
	ds_read_b128 v[186:189], v169 offset:16384
	ds_read_b128 v[190:193], v169 offset:17408
	ds_read_b128 v[194:197], v169 offset:18432
	ds_read_b128 v[198:201], v169 offset:19456
	ds_read_b128 v[202:205], v169 offset:20480
	ds_read_b128 v[206:209], v169 offset:21504
	ds_read_b128 v[210:213], v169 offset:22528
	ds_read_b128 v[214:217], v169 offset:23552
	global_load_lds_dwordx4 v[218:219], off
	s_add_i32 m0, s56, 0x2000
	v_lshl_add_u64 v[228:229], s[54:55], 0, v[140:141]
	s_add_u32 s54, s54, s6
	s_addc_u32 s55, s55, s7
	s_add_i32 s56, s57, s42
	global_load_lds_dwordx4 v[228:229], off
	v_lshl_add_u64 v[230:231], s[54:55], 0, v[146:147]
	s_mov_b32 m0, s56
	v_lshl_add_u64 v[232:233], s[54:55], 0, v[140:141]
	global_load_lds_dwordx4 v[230:231], off
	s_add_i32 m0, s56, 0x2000
	v_lshl_add_u64 v[234:235], s[28:29], 0, v[136:137]
	global_load_lds_dwordx4 v[232:233], off
	s_mov_b32 m0, s27
	v_lshl_add_u64 v[236:237], s[28:29], 0, v[138:139]
	global_load_lds_dwordx4 v[234:235], off
	s_mov_b32 m0, s43
	s_nop 0
	global_load_lds_dwordx4 v[236:237], off
	s_waitcnt vmcnt(8)
	s_waitcnt lgkmcnt(0)
	s_barrier
; #define PG8_STAGE(bufoff, gbase, voff) do { _Pragma("unroll") for (int _i = 0; _i < 2; ++_i) \
;         __builtin_amdgcn_global_load_lds((const unsigned*)((const char*)(gbase) + (voff)[_i]), (LAS unsigned*)(lds + (bufoff) + ldsw + _i * 8192), 16, 0, 0); } while (0)
; #define PG8_LDA(dst, b, h) do { _Pragma("unroll") for (int m = 0; m < 4; ++m) _Pragma("unroll") for (int k = 0; k < 2; ++k) dst[m][k] = *(const LAS bf16x8*)(lds + PG8_SA(b, h) + aoff + m * 2048 + k * 1024); } while (0)
; #define PG8_LDB(dst, b, h) do { _Pragma("unroll") for (int n = 0; n < 2; ++n) _Pragma("unroll") for (int k = 0; k < 2; ++k) dst[n][k] = *(const LAS bf16x8*)(lds + PG8_SB(b, h) + boff + n * 2048 + k * 1024); } while (0)
; #define PG8_MMA(ai, bj, At, Bt) do { __builtin_amdgcn_s_setprio(1); _Pragma("unroll") for (int m = 0; m < 4; ++m) _Pragma("unroll") for (int n = 0; n < 2; ++n) _Pragma("unroll") for (int k = 0; k < 2; ++k) \
;         acc[ai][bj][m][n] = __builtin_amdgcn_mfma_f32_16x16x32_bf16(Bt[n][k], At[m][k], acc[ai][bj][m][n], 0, 0, 0); __builtin_amdgcn_s_setprio(0); } while (0)
; #define PG8_WAIT_V(n) asm volatile("s_waitcnt vmcnt(" #n ")" ::: "memory")
; #define PG8_WAIT_L(n) asm volatile("s_waitcnt lgkmcnt(" #n ")" ::: "memory")
; #define PG8_BAR __builtin_amdgcn_s_barrier()
; #define PG8_SCHED __builtin_amdgcn_sched_barrier(0)
;     ...
;             PG8_WAIT_V(8); PG8_WAIT_L(0); PG8_BAR; PG8_MMA(1, 0, At, B0); PG8_MMA(1, 1, At, B1); PG8_BAR; PG8_SCHED;
;             PG8_LDB(B0, 1, 0); PG8_LDB(B1, 1, 1); PG8_SCHED; PG8_LDA(At, 1, 0); PG8_STAGE(PG8_SA(0, 1), a2 + hstepA, voffA);
;             PG8_WAIT_V(8); PG8_WAIT_L(0); PG8_BAR; PG8_MMA(0, 0, At, B0); PG8_MMA(0, 1, At, B1); PG8_BAR; PG8_SCHED;
	s_setprio 1
	s_waitcnt lgkmcnt(0)
	v_mfma_f32_16x16x32_bf16 v[92:95], v[112:115], v[186:189], v[92:95]
	v_mfma_f32_16x16x32_bf16 v[88:91], v[158:161], v[186:189], v[88:91]
	v_mfma_f32_16x16x32_bf16 v[84:87], v[112:115], v[194:197], v[84:87]
	v_mfma_f32_16x16x32_bf16 v[80:83], v[158:161], v[194:197], v[80:83]
	v_mfma_f32_16x16x32_bf16 v[76:79], v[112:115], v[202:205], v[76:79]
	v_mfma_f32_16x16x32_bf16 v[72:75], v[158:161], v[202:205], v[72:75]
	v_mfma_f32_16x16x32_bf16 v[68:71], v[112:115], v[210:213], v[68:71]
	v_mfma_f32_16x16x32_bf16 v[64:67], v[158:161], v[210:213], v[64:67]
	v_mfma_f32_16x16x32_bf16 v[92:95], v[116:119], v[190:193], v[92:95]
	v_mfma_f32_16x16x32_bf16 v[88:91], v[162:165], v[190:193], v[88:91]
	v_mfma_f32_16x16x32_bf16 v[84:87], v[116:119], v[198:201], v[84:87]
	v_mfma_f32_16x16x32_bf16 v[80:83], v[162:165], v[198:201], v[80:83]
	v_mfma_f32_16x16x32_bf16 v[76:79], v[116:119], v[206:209], v[76:79]
	v_mfma_f32_16x16x32_bf16 v[72:75], v[162:165], v[206:209], v[72:75]
	v_mfma_f32_16x16x32_bf16 v[68:71], v[116:119], v[214:217], v[68:71]
	v_mfma_f32_16x16x32_bf16 v[64:67], v[162:165], v[214:217], v[64:67]
	v_mfma_f32_16x16x32_bf16 v[28:31], v[170:173], v[186:189], v[28:31]
	v_mfma_f32_16x16x32_bf16 v[24:27], v[178:181], v[186:189], v[24:27]
	v_mfma_f32_16x16x32_bf16 v[20:23], v[170:173], v[194:197], v[20:23]
	v_mfma_f32_16x16x32_bf16 v[16:19], v[178:181], v[194:197], v[16:19]
	v_mfma_f32_16x16x32_bf16 v[12:15], v[170:173], v[202:205], v[12:15]
	v_mfma_f32_16x16x32_bf16 v[8:11], v[178:181], v[202:205], v[8:11]
	v_mfma_f32_16x16x32_bf16 v[4:7], v[170:173], v[210:213], v[4:7]
	v_mfma_f32_16x16x32_bf16 v[0:3], v[178:181], v[210:213], v[0:3]
	v_mfma_f32_16x16x32_bf16 v[28:31], v[174:177], v[190:193], v[28:31]
	v_mfma_f32_16x16x32_bf16 v[24:27], v[182:185], v[190:193], v[24:27]
	v_mfma_f32_16x16x32_bf16 v[20:23], v[174:177], v[198:201], v[20:23]
	v_mfma_f32_16x16x32_bf16 v[16:19], v[182:185], v[198:201], v[16:19]
	v_mfma_f32_16x16x32_bf16 v[12:15], v[174:177], v[206:209], v[12:15]
	v_mfma_f32_16x16x32_bf16 v[8:11], v[182:185], v[206:209], v[8:11]
	v_mfma_f32_16x16x32_bf16 v[4:7], v[174:177], v[214:217], v[4:7]
	v_mfma_f32_16x16x32_bf16 v[0:3], v[182:185], v[214:217], v[0:3]
	s_setprio 0
	s_barrier
	s_add_i32 s54, 0, 0x18000
	v_add_u32_e32 v152, s54, v167
	s_add_i32 s55, 0, 0x1c000
	ds_read_b128 v[112:115], v152
	ds_read_b128 v[116:119], v152 offset:1024
	ds_read_b128 v[158:161], v152 offset:2048
	ds_read_b128 v[162:165], v152 offset:3072
	v_add_u32_e32 v152, s55, v167
	ds_read_b128 v[170:173], v152
	ds_read_b128 v[174:177], v152 offset:1024
	ds_read_b128 v[178:181], v152 offset:2048
	ds_read_b128 v[182:185], v152 offset:3072
	s_add_u32 s28, s28, 0x20000
	s_addc_u32 s29, s29, 0
	s_mov_b32 m0, s44
	v_lshl_add_u64 v[238:239], s[28:29], 0, v[136:137]
	ds_read_b128 v[186:189], v169 offset:32768
	ds_read_b128 v[190:193], v169 offset:33792
	ds_read_b128 v[194:197], v169 offset:34816
	ds_read_b128 v[198:201], v169 offset:35840
	ds_read_b128 v[202:205], v169 offset:36864
	ds_read_b128 v[206:209], v169 offset:37888
	ds_read_b128 v[210:213], v169 offset:38912
	ds_read_b128 v[214:217], v169 offset:39936
	global_load_lds_dwordx4 v[238:239], off
	v_lshl_add_u64 v[238:239], s[28:29], 0, v[138:139]
	s_mov_b32 m0, s45
	s_nop 0
	global_load_lds_dwordx4 v[238:239], off
	s_waitcnt vmcnt(8)
	s_waitcnt lgkmcnt(0)
	s_barrier
	s_setprio 1
	s_waitcnt lgkmcnt(0)
	v_mfma_f32_16x16x32_bf16 v[128:131], v[112:115], v[186:189], v[128:131]
	v_mfma_f32_16x16x32_bf16 v[132:135], v[158:161], v[186:189], v[132:135]
	v_mfma_f32_16x16x32_bf16 v[124:127], v[112:115], v[194:197], v[124:127]
	v_mfma_f32_16x16x32_bf16 v[120:123], v[158:161], v[194:197], v[120:123]
	v_mfma_f32_16x16x32_bf16 v[108:111], v[112:115], v[202:205], v[108:111]
	v_mfma_f32_16x16x32_bf16 v[104:107], v[158:161], v[202:205], v[104:107]
	v_mfma_f32_16x16x32_bf16 v[100:103], v[112:115], v[210:213], v[100:103]
	v_mfma_f32_16x16x32_bf16 v[96:99], v[158:161], v[210:213], v[96:99]
	v_mfma_f32_16x16x32_bf16 v[128:131], v[116:119], v[190:193], v[128:131]
	v_mfma_f32_16x16x32_bf16 v[132:135], v[162:165], v[190:193], v[132:135]
	v_mfma_f32_16x16x32_bf16 v[124:127], v[116:119], v[198:201], v[124:127]
	v_mfma_f32_16x16x32_bf16 v[120:123], v[162:165], v[198:201], v[120:123]
	v_mfma_f32_16x16x32_bf16 v[108:111], v[116:119], v[206:209], v[108:111]
	v_mfma_f32_16x16x32_bf16 v[104:107], v[162:165], v[206:209], v[104:107]
	v_mfma_f32_16x16x32_bf16 v[100:103], v[116:119], v[214:217], v[100:103]
	v_mfma_f32_16x16x32_bf16 v[96:99], v[162:165], v[214:217], v[96:99]
	v_mfma_f32_16x16x32_bf16 v[60:63], v[170:173], v[186:189], v[60:63]
	v_mfma_f32_16x16x32_bf16 v[56:59], v[178:181], v[186:189], v[56:59]
	v_mfma_f32_16x16x32_bf16 v[52:55], v[170:173], v[194:197], v[52:55]
	v_mfma_f32_16x16x32_bf16 v[48:51], v[178:181], v[194:197], v[48:51]
	v_mfma_f32_16x16x32_bf16 v[44:47], v[170:173], v[202:205], v[44:47]
	v_mfma_f32_16x16x32_bf16 v[40:43], v[178:181], v[202:205], v[40:43]
	v_mfma_f32_16x16x32_bf16 v[36:39], v[170:173], v[210:213], v[36:39]
	v_mfma_f32_16x16x32_bf16 v[32:35], v[178:181], v[210:213], v[32:35]
	v_mfma_f32_16x16x32_bf16 v[60:63], v[174:177], v[190:193], v[60:63]
	v_mfma_f32_16x16x32_bf16 v[56:59], v[182:185], v[190:193], v[56:59]
	v_mfma_f32_16x16x32_bf16 v[52:55], v[174:177], v[198:201], v[52:55]
	v_mfma_f32_16x16x32_bf16 v[48:51], v[182:185], v[198:201], v[48:51]
	v_mfma_f32_16x16x32_bf16 v[44:47], v[174:177], v[206:209], v[44:47]
	v_mfma_f32_16x16x32_bf16 v[40:43], v[182:185], v[206:209], v[40:43]
	v_mfma_f32_16x16x32_bf16 v[36:39], v[174:177], v[214:217], v[36:39]
	v_mfma_f32_16x16x32_bf16 v[32:35], v[182:185], v[214:217], v[32:35]
	s_setprio 0
	s_barrier
; #define PG8_STAGE(bufoff, gbase, voff) do { _Pragma("unroll") for (int _i = 0; _i < 2; ++_i) \
;         __builtin_amdgcn_global_load_lds((const unsigned*)((const char*)(gbase) + (voff)[_i]), (LAS unsigned*)(lds + (bufoff) + ldsw + _i * 8192), 16, 0, 0); } while (0)
; #define PG8_LDA(dst, b, h) do { _Pragma("unroll") for (int m = 0; m < 4; ++m) _Pragma("unroll") for (int k = 0; k < 2; ++k) dst[m][k] = *(const LAS bf16x8*)(lds + PG8_SA(b, h) + aoff + m * 2048 + k * 1024); } while (0)
; #define PG8_MMA(ai, bj, At, Bt) do { __builtin_amdgcn_s_setprio(1); _Pragma("unroll") for (int m = 0; m < 4; ++m) _Pragma("unroll") for (int n = 0; n < 2; ++n) _Pragma("unroll") for (int k = 0; k < 2; ++k) \
;         acc[ai][bj][m][n] = __builtin_amdgcn_mfma_f32_16x16x32_bf16(Bt[n][k], At[m][k], acc[ai][bj][m][n], 0, 0, 0); __builtin_amdgcn_s_setprio(0); } while (0)
; #define PG8_WAIT_V(n) asm volatile("s_waitcnt vmcnt(" #n ")" ::: "memory")
; #define PG8_WAIT_L(n) asm volatile("s_waitcnt lgkmcnt(" #n ")" ::: "memory")
; #define PG8_BAR __builtin_amdgcn_s_barrier()
; #define PG8_SCHED __builtin_amdgcn_sched_barrier(0)
;     ...
;         for (int t = 0; t < nt; t += 2) {
;             const bool last = (t == nt - 2);
;             const char* a1 = cA + (size_t)(t + 1) * kstep;
;             const char* a2 = last ? nA : cA + (size_t)(t + 2) * kstep; const char* b2 = last ? nB : cB + (size_t)(t + 2) * kstep;
;     ...
;             PG8_LDA(At, 1, 1); PG8_STAGE(PG8_SB(1, 0), b3, voffB); PG8_STAGE(PG8_SB(1, 1), b3 + hstepB, voffB); PG8_STAGE(PG8_SA(1, 0), a3, voffA);
;             PG8_WAIT_V(8); PG8_WAIT_L(0); PG8_BAR; PG8_MMA(1, 0, At, B0); PG8_MMA(1, 1, At, B1); PG8_BAR; PG8_SCHED;
	s_add_i32 s28, s54, s42
	v_lshl_add_u64 v[218:219], v[218:219], 0, s[58:59]
	s_mov_b32 m0, s28
	ds_read_b128 v[186:189], v169 offset:49152
	ds_read_b128 v[190:193], v169 offset:50176
	ds_read_b128 v[194:197], v169 offset:51200
	ds_read_b128 v[198:201], v169 offset:52224
	ds_read_b128 v[202:205], v169 offset:53248
	ds_read_b128 v[206:209], v169 offset:54272
	ds_read_b128 v[210:213], v169 offset:55296
	ds_read_b128 v[214:217], v169 offset:56320
	global_load_lds_dwordx4 v[218:219], off
	v_lshl_add_u64 v[218:219], v[228:229], 0, s[58:59]
	s_add_i32 m0, s28, 0x2000
	s_add_i32 s28, s55, s42
	global_load_lds_dwordx4 v[218:219], off
	v_lshl_add_u64 v[218:219], v[230:231], 0, s[58:59]
	s_mov_b32 m0, s28
	s_nop 0
	global_load_lds_dwordx4 v[218:219], off
	v_lshl_add_u64 v[218:219], v[232:233], 0, s[58:59]
	s_add_i32 m0, s28, 0x2000
	s_nop 0
	global_load_lds_dwordx4 v[218:219], off
	v_lshl_add_u64 v[218:219], v[234:235], 0, s[58:59]
	s_mov_b32 m0, s47
	s_nop 0
	global_load_lds_dwordx4 v[218:219], off
	v_lshl_add_u64 v[218:219], v[236:237], 0, s[58:59]
	s_mov_b32 m0, s48
	s_nop 0
	global_load_lds_dwordx4 v[218:219], off
	s_waitcnt vmcnt(8)
	s_waitcnt lgkmcnt(0)
	s_barrier
	s_setprio 1
	s_waitcnt lgkmcnt(0)
	v_mfma_f32_16x16x32_bf16 v[92:95], v[112:115], v[186:189], v[92:95]
	v_mfma_f32_16x16x32_bf16 v[88:91], v[158:161], v[186:189], v[88:91]
	v_mfma_f32_16x16x32_bf16 v[84:87], v[112:115], v[194:197], v[84:87]
	v_mfma_f32_16x16x32_bf16 v[80:83], v[158:161], v[194:197], v[80:83]
	v_mfma_f32_16x16x32_bf16 v[76:79], v[112:115], v[202:205], v[76:79]
	v_mfma_f32_16x16x32_bf16 v[72:75], v[158:161], v[202:205], v[72:75]
	v_mfma_f32_16x16x32_bf16 v[68:71], v[112:115], v[210:213], v[68:71]
	v_mfma_f32_16x16x32_bf16 v[64:67], v[158:161], v[210:213], v[64:67]
	v_mfma_f32_16x16x32_bf16 v[92:95], v[116:119], v[190:193], v[92:95]
	v_mfma_f32_16x16x32_bf16 v[88:91], v[162:165], v[190:193], v[88:91]
	v_mfma_f32_16x16x32_bf16 v[84:87], v[116:119], v[198:201], v[84:87]
	v_mfma_f32_16x16x32_bf16 v[80:83], v[162:165], v[198:201], v[80:83]
	v_mfma_f32_16x16x32_bf16 v[76:79], v[116:119], v[206:209], v[76:79]
	v_mfma_f32_16x16x32_bf16 v[72:75], v[162:165], v[206:209], v[72:75]
	v_mfma_f32_16x16x32_bf16 v[68:71], v[116:119], v[214:217], v[68:71]
	v_mfma_f32_16x16x32_bf16 v[64:67], v[162:165], v[214:217], v[64:67]
	v_mfma_f32_16x16x32_bf16 v[28:31], v[170:173], v[186:189], v[28:31]
	v_mfma_f32_16x16x32_bf16 v[24:27], v[178:181], v[186:189], v[24:27]
	v_mfma_f32_16x16x32_bf16 v[20:23], v[170:173], v[194:197], v[20:23]
	v_mfma_f32_16x16x32_bf16 v[16:19], v[178:181], v[194:197], v[16:19]
	v_mfma_f32_16x16x32_bf16 v[12:15], v[170:173], v[202:205], v[12:15]
	v_mfma_f32_16x16x32_bf16 v[8:11], v[178:181], v[202:205], v[8:11]
	v_mfma_f32_16x16x32_bf16 v[4:7], v[170:173], v[210:213], v[4:7]
	v_mfma_f32_16x16x32_bf16 v[0:3], v[178:181], v[210:213], v[0:3]
	v_mfma_f32_16x16x32_bf16 v[28:31], v[174:177], v[190:193], v[28:31]
	v_mfma_f32_16x16x32_bf16 v[24:27], v[182:185], v[190:193], v[24:27]
	v_mfma_f32_16x16x32_bf16 v[20:23], v[174:177], v[198:201], v[20:23]
	v_mfma_f32_16x16x32_bf16 v[16:19], v[182:185], v[198:201], v[16:19]
	v_mfma_f32_16x16x32_bf16 v[12:15], v[174:177], v[206:209], v[12:15]
	v_mfma_f32_16x16x32_bf16 v[8:11], v[182:185], v[206:209], v[8:11]
	v_mfma_f32_16x16x32_bf16 v[4:7], v[174:177], v[214:217], v[4:7]
	v_mfma_f32_16x16x32_bf16 v[0:3], v[182:185], v[214:217], v[0:3]
	s_setprio 0
	s_barrier
	s_add_u32 s12, s12, 0x100
	s_addc_u32 s13, s13, 0
	s_add_u32 s30, s30, 0x100
	s_addc_u32 s31, s31, 0
	s_cmp_ge_i32 s53, s46
	s_mov_b32 s28, s53
	s_cbranch_scc0 .LBB0_285

; #define PG8_STAGE(bufoff, gbase, voff) do { _Pragma("unroll") for (int _i = 0; _i < 2; ++_i) \
;         __builtin_amdgcn_global_load_lds((const unsigned*)((const char*)(gbase) + (voff)[_i]), (LAS unsigned*)(lds + (bufoff) + ldsw + _i * 8192), 16, 0, 0); } while (0)
; #define PG8_LDA(dst, b, h) do { _Pragma("unroll") for (int m = 0; m < 4; ++m) _Pragma("unroll") for (int k = 0; k < 2; ++k) dst[m][k] = *(const LAS bf16x8*)(lds + PG8_SA(b, h) + aoff + m * 2048 + k * 1024); } while (0)
; #define PG8_LDB(dst, b, h) do { _Pragma("unroll") for (int n = 0; n < 2; ++n) _Pragma("unroll") for (int k = 0; k < 2; ++k) dst[n][k] = *(const LAS bf16x8*)(lds + PG8_SB(b, h) + boff + n * 2048 + k * 1024); } while (0)
; #define PG8_MMA(ai, bj, At, Bt) do { __builtin_amdgcn_s_setprio(1); _Pragma("unroll") for (int m = 0; m < 4; ++m) _Pragma("unroll") for (int n = 0; n < 2; ++n) _Pragma("unroll") for (int k = 0; k < 2; ++k) \
;         acc[ai][bj][m][n] = __builtin_amdgcn_mfma_f32_16x16x32_bf16(Bt[n][k], At[m][k], acc[ai][bj][m][n], 0, 0, 0); __builtin_amdgcn_s_setprio(0); } while (0)
; #define PG8_WAIT_V(n) asm volatile("s_waitcnt vmcnt(" #n ")" ::: "memory")
; #define PG8_WAIT_L(n) asm volatile("s_waitcnt lgkmcnt(" #n ")" ::: "memory")
; #define PG8_BAR __builtin_amdgcn_s_barrier()
; #define PG8_SCHED __builtin_amdgcn_sched_barrier(0)
;     ...
;             const bool last = (t == nt - 2);
;             const char* a1 = cA + (size_t)(t + 1) * kstep;
;             const char* a2 = last ? nA : cA + (size_t)(t + 2) * kstep; const char* b2 = last ? nB : cB + (size_t)(t + 2) * kstep;
;             const char* a3 = a2 + kstep; const char* b3 = b2 + kstep;
;             if constexpr (SP2) {
;             PG8_LDB(B0, 0, 0); PG8_LDB(B1, 0, 1); PG8_SCHED; PG8_LDA(At, 0, 0); PG8_STAGE(PG8_SA(1, 1), a1 + hstepA, voffA);
;             PG8_WAIT_V(8); PG8_WAIT_L(0); PG8_BAR; PG8_MMA(0, 0, At, B0); PG8_MMA(0, 1, At, B1); PG8_BAR; PG8_SCHED;
;             PG8_LDA(At, 0, 1); PG8_STAGE(PG8_SB(0, 0), b2, voffB); PG8_STAGE(PG8_SB(0, 1), b2 + hstepB, voffB); PG8_STAGE(PG8_SA(0, 0), a2, voffA);
;             PG8_WAIT_V(8); PG8_WAIT_L(0); PG8_BAR; PG8_MMA(1, 0, At, B0); PG8_MMA(1, 1, At, B1); PG8_BAR; PG8_SCHED;
.LBB0_314:
	s_add_i32 s50, s4, 2
	s_add_u32 s2, s0, 0x100
	s_addc_u32 s3, s1, 0
	s_add_i32 s51, 0, 0x10000
	s_cmp_eq_u32 s41, s4
	s_cselect_b32 s5, s13, s3
	s_cselect_b32 s4, s12, s2
	v_add_u32_e32 v140, s51, v143
	s_cselect_b32 s53, s27, s49
	s_cselect_b32 s52, s26, s48
	s_add_i32 s54, 0, 0x14000
	ds_read_b128 v[158:161], v140
	ds_read_b128 v[162:165], v140 offset:1024
	ds_read_b128 v[166:169], v140 offset:2048
	ds_read_b128 v[170:173], v140 offset:3072
	v_add_u32_e32 v140, s54, v143
	ds_read_b128 v[174:177], v140
	ds_read_b128 v[178:181], v140 offset:1024
	ds_read_b128 v[182:185], v140 offset:2048
	ds_read_b128 v[186:189], v140 offset:3072
	v_lshl_add_u64 v[140:141], s[0:1], 0, v[136:137]
	s_add_i32 m0, s35, 0xc000
	ds_read_b128 v[190:193], v156
	ds_read_b128 v[194:197], v156 offset:1024
	ds_read_b128 v[198:201], v156 offset:2048
	ds_read_b128 v[202:205], v156 offset:3072
	ds_read_b128 v[206:209], v156 offset:4096
	ds_read_b128 v[210:213], v156 offset:5120
	ds_read_b128 v[214:217], v156 offset:6144
	ds_read_b128 v[228:231], v156 offset:7168
	global_load_lds_dwordx4 v[140:141], off
	v_lshl_add_u64 v[140:141], s[0:1], 0, v[138:139]
	s_add_i32 m0, s35, 0xe000
	s_nop 0
	global_load_lds_dwordx4 v[140:141], off
	s_waitcnt vmcnt(8)
	s_waitcnt lgkmcnt(0)
	s_barrier
	s_setprio 1
	s_waitcnt lgkmcnt(0)
	v_mfma_f32_16x16x32_bf16 v[124:127], v[158:161], v[190:193], v[124:127]
	v_mfma_f32_16x16x32_bf16 v[120:123], v[166:169], v[190:193], v[120:123]
	v_mfma_f32_16x16x32_bf16 v[108:111], v[158:161], v[198:201], v[108:111]
	v_mfma_f32_16x16x32_bf16 v[104:107], v[166:169], v[198:201], v[104:107]
	v_mfma_f32_16x16x32_bf16 v[92:95], v[158:161], v[206:209], v[92:95]
	v_mfma_f32_16x16x32_bf16 v[88:91], v[166:169], v[206:209], v[88:91]
	v_mfma_f32_16x16x32_bf16 v[76:79], v[158:161], v[214:217], v[76:79]
	v_mfma_f32_16x16x32_bf16 v[72:75], v[166:169], v[214:217], v[72:75]
	v_mfma_f32_16x16x32_bf16 v[124:127], v[162:165], v[194:197], v[124:127]
	v_mfma_f32_16x16x32_bf16 v[120:123], v[170:173], v[194:197], v[120:123]
	v_mfma_f32_16x16x32_bf16 v[108:111], v[162:165], v[202:205], v[108:111]
	v_mfma_f32_16x16x32_bf16 v[104:107], v[170:173], v[202:205], v[104:107]
	v_mfma_f32_16x16x32_bf16 v[92:95], v[162:165], v[210:213], v[92:95]
	v_mfma_f32_16x16x32_bf16 v[88:91], v[170:173], v[210:213], v[88:91]
	v_mfma_f32_16x16x32_bf16 v[76:79], v[162:165], v[228:231], v[76:79]
	v_mfma_f32_16x16x32_bf16 v[72:75], v[170:173], v[228:231], v[72:75]
	v_mfma_f32_16x16x32_bf16 v[116:119], v[174:177], v[190:193], v[116:119]
	v_mfma_f32_16x16x32_bf16 v[112:115], v[182:185], v[190:193], v[112:115]
	v_mfma_f32_16x16x32_bf16 v[100:103], v[174:177], v[198:201], v[100:103]
	v_mfma_f32_16x16x32_bf16 v[96:99], v[182:185], v[198:201], v[96:99]
	v_mfma_f32_16x16x32_bf16 v[84:87], v[174:177], v[206:209], v[84:87]
	v_mfma_f32_16x16x32_bf16 v[80:83], v[182:185], v[206:209], v[80:83]
	v_mfma_f32_16x16x32_bf16 v[68:71], v[174:177], v[214:217], v[68:71]
	v_mfma_f32_16x16x32_bf16 v[64:67], v[182:185], v[214:217], v[64:67]
	v_mfma_f32_16x16x32_bf16 v[116:119], v[178:181], v[194:197], v[116:119]
	v_mfma_f32_16x16x32_bf16 v[112:115], v[186:189], v[194:197], v[112:115]
	v_mfma_f32_16x16x32_bf16 v[100:103], v[178:181], v[202:205], v[100:103]
	v_mfma_f32_16x16x32_bf16 v[96:99], v[186:189], v[202:205], v[96:99]
	v_mfma_f32_16x16x32_bf16 v[84:87], v[178:181], v[210:213], v[84:87]
	v_mfma_f32_16x16x32_bf16 v[80:83], v[186:189], v[210:213], v[80:83]
	v_mfma_f32_16x16x32_bf16 v[68:71], v[178:181], v[228:231], v[68:71]
	v_mfma_f32_16x16x32_bf16 v[64:67], v[186:189], v[228:231], v[64:67]
	s_setprio 0
	s_barrier
	s_add_i32 s0, s51, s31
	v_lshl_add_u64 v[140:141], s[52:53], 0, v[130:131]
	s_mov_b32 m0, s0
	ds_read_b128 v[190:193], v156 offset:16384
	ds_read_b128 v[194:197], v156 offset:17408
	ds_read_b128 v[198:201], v156 offset:18432
	ds_read_b128 v[202:205], v156 offset:19456
	ds_read_b128 v[206:209], v156 offset:20480
	ds_read_b128 v[210:213], v156 offset:21504
	ds_read_b128 v[214:217], v156 offset:22528
	ds_read_b128 v[228:231], v156 offset:23552
	global_load_lds_dwordx4 v[140:141], off
	s_add_i32 m0, s0, 0x2000
	s_add_u32 s0, s52, s14
	v_lshl_add_u64 v[218:219], s[52:53], 0, v[134:135]
	s_addc_u32 s1, s53, s15
	s_add_i32 s51, s54, s31
	global_load_lds_dwordx4 v[218:219], off
	v_lshl_add_u64 v[232:233], s[0:1], 0, v[130:131]
	s_mov_b32 m0, s51
	v_lshl_add_u64 v[234:235], s[0:1], 0, v[134:135]
	global_load_lds_dwordx4 v[232:233], off
	s_add_i32 m0, s51, 0x2000
	v_lshl_add_u64 v[236:237], s[4:5], 0, v[128:129]
	global_load_lds_dwordx4 v[234:235], off
	s_mov_b32 m0, s35
	v_lshl_add_u64 v[238:239], s[4:5], 0, v[132:133]
	global_load_lds_dwordx4 v[236:237], off
	s_mov_b32 m0, s36
	s_nop 0
	global_load_lds_dwordx4 v[238:239], off
	s_waitcnt vmcnt(8)
	s_waitcnt lgkmcnt(0)
	s_barrier
; #define PG8_STAGE(bufoff, gbase, voff) do { _Pragma("unroll") for (int _i = 0; _i < 2; ++_i) \
;         __builtin_amdgcn_global_load_lds((const unsigned*)((const char*)(gbase) + (voff)[_i]), (LAS unsigned*)(lds + (bufoff) + ldsw + _i * 8192), 16, 0, 0); } while (0)
; #define PG8_LDA(dst, b, h) do { _Pragma("unroll") for (int m = 0; m < 4; ++m) _Pragma("unroll") for (int k = 0; k < 2; ++k) dst[m][k] = *(const LAS bf16x8*)(lds + PG8_SA(b, h) + aoff + m * 2048 + k * 1024); } while (0)
; #define PG8_LDB(dst, b, h) do { _Pragma("unroll") for (int n = 0; n < 2; ++n) _Pragma("unroll") for (int k = 0; k < 2; ++k) dst[n][k] = *(const LAS bf16x8*)(lds + PG8_SB(b, h) + boff + n * 2048 + k * 1024); } while (0)
; #define PG8_MMA(ai, bj, At, Bt) do { __builtin_amdgcn_s_setprio(1); _Pragma("unroll") for (int m = 0; m < 4; ++m) _Pragma("unroll") for (int n = 0; n < 2; ++n) _Pragma("unroll") for (int k = 0; k < 2; ++k) \
;         acc[ai][bj][m][n] = __builtin_amdgcn_mfma_f32_16x16x32_bf16(Bt[n][k], At[m][k], acc[ai][bj][m][n], 0, 0, 0); __builtin_amdgcn_s_setprio(0); } while (0)
; #define PG8_WAIT_V(n) asm volatile("s_waitcnt vmcnt(" #n ")" ::: "memory")
; #define PG8_WAIT_L(n) asm volatile("s_waitcnt lgkmcnt(" #n ")" ::: "memory")
; #define PG8_BAR __builtin_amdgcn_s_barrier()
; #define PG8_SCHED __builtin_amdgcn_sched_barrier(0)
;     ...
;             PG8_WAIT_V(8); PG8_WAIT_L(0); PG8_BAR; PG8_MMA(1, 0, At, B0); PG8_MMA(1, 1, At, B1); PG8_BAR; PG8_SCHED;
;             PG8_LDB(B0, 1, 0); PG8_LDB(B1, 1, 1); PG8_SCHED; PG8_LDA(At, 1, 0); PG8_STAGE(PG8_SA(0, 1), a2 + hstepA, voffA);
;             PG8_WAIT_V(8); PG8_WAIT_L(0); PG8_BAR; PG8_MMA(0, 0, At, B0); PG8_MMA(0, 1, At, B1); PG8_BAR; PG8_SCHED;
	s_setprio 1
	s_waitcnt lgkmcnt(0)
	v_mfma_f32_16x16x32_bf16 v[60:63], v[158:161], v[190:193], v[60:63]
	v_mfma_f32_16x16x32_bf16 v[56:59], v[166:169], v[190:193], v[56:59]
	v_mfma_f32_16x16x32_bf16 v[44:47], v[158:161], v[198:201], v[44:47]
	v_mfma_f32_16x16x32_bf16 v[40:43], v[166:169], v[198:201], v[40:43]
	v_mfma_f32_16x16x32_bf16 v[28:31], v[158:161], v[206:209], v[28:31]
	v_mfma_f32_16x16x32_bf16 v[24:27], v[166:169], v[206:209], v[24:27]
	v_mfma_f32_16x16x32_bf16 v[12:15], v[158:161], v[214:217], v[12:15]
	v_mfma_f32_16x16x32_bf16 v[8:11], v[166:169], v[214:217], v[8:11]
	v_mfma_f32_16x16x32_bf16 v[60:63], v[162:165], v[194:197], v[60:63]
	v_mfma_f32_16x16x32_bf16 v[56:59], v[170:173], v[194:197], v[56:59]
	v_mfma_f32_16x16x32_bf16 v[44:47], v[162:165], v[202:205], v[44:47]
	v_mfma_f32_16x16x32_bf16 v[40:43], v[170:173], v[202:205], v[40:43]
	v_mfma_f32_16x16x32_bf16 v[28:31], v[162:165], v[210:213], v[28:31]
	v_mfma_f32_16x16x32_bf16 v[24:27], v[170:173], v[210:213], v[24:27]
	v_mfma_f32_16x16x32_bf16 v[12:15], v[162:165], v[228:231], v[12:15]
	v_mfma_f32_16x16x32_bf16 v[8:11], v[170:173], v[228:231], v[8:11]
	v_mfma_f32_16x16x32_bf16 v[52:55], v[174:177], v[190:193], v[52:55]
	v_mfma_f32_16x16x32_bf16 v[48:51], v[182:185], v[190:193], v[48:51]
	v_mfma_f32_16x16x32_bf16 v[36:39], v[174:177], v[198:201], v[36:39]
	v_mfma_f32_16x16x32_bf16 v[32:35], v[182:185], v[198:201], v[32:35]
	v_mfma_f32_16x16x32_bf16 v[20:23], v[174:177], v[206:209], v[20:23]
	v_mfma_f32_16x16x32_bf16 v[16:19], v[182:185], v[206:209], v[16:19]
	v_mfma_f32_16x16x32_bf16 v[4:7], v[174:177], v[214:217], v[4:7]
	v_mfma_f32_16x16x32_bf16 v[0:3], v[182:185], v[214:217], v[0:3]
	v_mfma_f32_16x16x32_bf16 v[52:55], v[178:181], v[194:197], v[52:55]
	v_mfma_f32_16x16x32_bf16 v[48:51], v[186:189], v[194:197], v[48:51]
	v_mfma_f32_16x16x32_bf16 v[36:39], v[178:181], v[202:205], v[36:39]
	v_mfma_f32_16x16x32_bf16 v[32:35], v[186:189], v[202:205], v[32:35]
	v_mfma_f32_16x16x32_bf16 v[20:23], v[178:181], v[210:213], v[20:23]
	v_mfma_f32_16x16x32_bf16 v[16:19], v[186:189], v[210:213], v[16:19]
	v_mfma_f32_16x16x32_bf16 v[4:7], v[178:181], v[228:231], v[4:7]
	v_mfma_f32_16x16x32_bf16 v[0:3], v[186:189], v[228:231], v[0:3]
	s_setprio 0
	s_barrier
	s_add_i32 s51, 0, 0x18000
	v_add_u32_e32 v152, s51, v143
	s_add_i32 s52, 0, 0x1c000
	ds_read_b128 v[158:161], v152
	ds_read_b128 v[162:165], v152 offset:1024
	ds_read_b128 v[166:169], v152 offset:2048
	ds_read_b128 v[170:173], v152 offset:3072
	v_add_u32_e32 v152, s52, v143
	ds_read_b128 v[174:177], v152
	ds_read_b128 v[178:181], v152 offset:1024
	ds_read_b128 v[182:185], v152 offset:2048
	ds_read_b128 v[186:189], v152 offset:3072
	s_add_u32 s0, s4, 0xe0000
	s_addc_u32 s1, s5, 0
	s_mov_b32 m0, s37
	v_lshl_add_u64 v[240:241], s[0:1], 0, v[128:129]
	ds_read_b128 v[190:193], v156 offset:32768
	ds_read_b128 v[194:197], v156 offset:33792
	ds_read_b128 v[198:201], v156 offset:34816
	ds_read_b128 v[202:205], v156 offset:35840
	ds_read_b128 v[206:209], v156 offset:36864
	ds_read_b128 v[210:213], v156 offset:37888
	ds_read_b128 v[214:217], v156 offset:38912
	ds_read_b128 v[228:231], v156 offset:39936
	global_load_lds_dwordx4 v[240:241], off
	v_lshl_add_u64 v[240:241], s[0:1], 0, v[132:133]
	s_mov_b32 m0, s38
	s_nop 0
	global_load_lds_dwordx4 v[240:241], off
	s_waitcnt vmcnt(8)
	s_waitcnt lgkmcnt(0)
	s_barrier
	s_setprio 1
	s_waitcnt lgkmcnt(0)
	v_mfma_f32_16x16x32_bf16 v[124:127], v[158:161], v[190:193], v[124:127]
	v_mfma_f32_16x16x32_bf16 v[120:123], v[166:169], v[190:193], v[120:123]
	v_mfma_f32_16x16x32_bf16 v[108:111], v[158:161], v[198:201], v[108:111]
	v_mfma_f32_16x16x32_bf16 v[104:107], v[166:169], v[198:201], v[104:107]
	v_mfma_f32_16x16x32_bf16 v[92:95], v[158:161], v[206:209], v[92:95]
	v_mfma_f32_16x16x32_bf16 v[88:91], v[166:169], v[206:209], v[88:91]
	v_mfma_f32_16x16x32_bf16 v[76:79], v[158:161], v[214:217], v[76:79]
	v_mfma_f32_16x16x32_bf16 v[72:75], v[166:169], v[214:217], v[72:75]
	v_mfma_f32_16x16x32_bf16 v[124:127], v[162:165], v[194:197], v[124:127]
	v_mfma_f32_16x16x32_bf16 v[120:123], v[170:173], v[194:197], v[120:123]
	v_mfma_f32_16x16x32_bf16 v[108:111], v[162:165], v[202:205], v[108:111]
	v_mfma_f32_16x16x32_bf16 v[104:107], v[170:173], v[202:205], v[104:107]
	v_mfma_f32_16x16x32_bf16 v[92:95], v[162:165], v[210:213], v[92:95]
	v_mfma_f32_16x16x32_bf16 v[88:91], v[170:173], v[210:213], v[88:91]
	v_mfma_f32_16x16x32_bf16 v[76:79], v[162:165], v[228:231], v[76:79]
	v_mfma_f32_16x16x32_bf16 v[72:75], v[170:173], v[228:231], v[72:75]
	v_mfma_f32_16x16x32_bf16 v[116:119], v[174:177], v[190:193], v[116:119]
	v_mfma_f32_16x16x32_bf16 v[112:115], v[182:185], v[190:193], v[112:115]
	v_mfma_f32_16x16x32_bf16 v[100:103], v[174:177], v[198:201], v[100:103]
	v_mfma_f32_16x16x32_bf16 v[96:99], v[182:185], v[198:201], v[96:99]
	v_mfma_f32_16x16x32_bf16 v[84:87], v[174:177], v[206:209], v[84:87]
	v_mfma_f32_16x16x32_bf16 v[80:83], v[182:185], v[206:209], v[80:83]
	v_mfma_f32_16x16x32_bf16 v[68:71], v[174:177], v[214:217], v[68:71]
	v_mfma_f32_16x16x32_bf16 v[64:67], v[182:185], v[214:217], v[64:67]
	v_mfma_f32_16x16x32_bf16 v[116:119], v[178:181], v[194:197], v[116:119]
	v_mfma_f32_16x16x32_bf16 v[112:115], v[186:189], v[194:197], v[112:115]
	v_mfma_f32_16x16x32_bf16 v[100:103], v[178:181], v[202:205], v[100:103]
	v_mfma_f32_16x16x32_bf16 v[96:99], v[186:189], v[202:205], v[96:99]
	v_mfma_f32_16x16x32_bf16 v[84:87], v[178:181], v[210:213], v[84:87]
	v_mfma_f32_16x16x32_bf16 v[80:83], v[186:189], v[210:213], v[80:83]
	v_mfma_f32_16x16x32_bf16 v[68:71], v[178:181], v[228:231], v[68:71]
	v_mfma_f32_16x16x32_bf16 v[64:67], v[186:189], v[228:231], v[64:67]
	s_setprio 0
	s_barrier
; #define PG8_STAGE(bufoff, gbase, voff) do { _Pragma("unroll") for (int _i = 0; _i < 2; ++_i) \
;         __builtin_amdgcn_global_load_lds((const unsigned*)((const char*)(gbase) + (voff)[_i]), (LAS unsigned*)(lds + (bufoff) + ldsw + _i * 8192), 16, 0, 0); } while (0)
; #define PG8_LDA(dst, b, h) do { _Pragma("unroll") for (int m = 0; m < 4; ++m) _Pragma("unroll") for (int k = 0; k < 2; ++k) dst[m][k] = *(const LAS bf16x8*)(lds + PG8_SA(b, h) + aoff + m * 2048 + k * 1024); } while (0)
; #define PG8_MMA(ai, bj, At, Bt) do { __builtin_amdgcn_s_setprio(1); _Pragma("unroll") for (int m = 0; m < 4; ++m) _Pragma("unroll") for (int n = 0; n < 2; ++n) _Pragma("unroll") for (int k = 0; k < 2; ++k) \
;         acc[ai][bj][m][n] = __builtin_amdgcn_mfma_f32_16x16x32_bf16(Bt[n][k], At[m][k], acc[ai][bj][m][n], 0, 0, 0); __builtin_amdgcn_s_setprio(0); } while (0)
; #define PG8_WAIT_V(n) asm volatile("s_waitcnt vmcnt(" #n ")" ::: "memory")
; #define PG8_WAIT_L(n) asm volatile("s_waitcnt lgkmcnt(" #n ")" ::: "memory")
; #define PG8_BAR __builtin_amdgcn_s_barrier()
; #define PG8_SCHED __builtin_amdgcn_sched_barrier(0)
;     ...
;         for (int t = 0; t < nt; t += 2) {
;             const bool last = (t == nt - 2);
;             const char* a1 = cA + (size_t)(t + 1) * kstep;
;             const char* a2 = last ? nA : cA + (size_t)(t + 2) * kstep; const char* b2 = last ? nB : cB + (size_t)(t + 2) * kstep;
;     ...
;             PG8_LDA(At, 1, 1); PG8_STAGE(PG8_SB(1, 0), b3, voffB); PG8_STAGE(PG8_SB(1, 1), b3 + hstepB, voffB); PG8_STAGE(PG8_SA(1, 0), a3, voffA);
;             PG8_WAIT_V(8); PG8_WAIT_L(0); PG8_BAR; PG8_MMA(1, 0, At, B0); PG8_MMA(1, 1, At, B1); PG8_BAR; PG8_SCHED;
	s_add_i32 s0, s51, s31
	v_lshl_add_u64 v[140:141], v[140:141], 0, s[56:57]
	s_mov_b32 m0, s0
	ds_read_b128 v[190:193], v156 offset:49152
	ds_read_b128 v[194:197], v156 offset:50176
	ds_read_b128 v[198:201], v156 offset:51200
	ds_read_b128 v[202:205], v156 offset:52224
	ds_read_b128 v[206:209], v156 offset:53248
	ds_read_b128 v[210:213], v156 offset:54272
	ds_read_b128 v[214:217], v156 offset:55296
	ds_read_b128 v[228:231], v156 offset:56320
	global_load_lds_dwordx4 v[140:141], off
	v_lshl_add_u64 v[140:141], v[218:219], 0, s[56:57]
	s_add_i32 m0, s0, 0x2000
	s_add_i32 s0, s52, s31
	global_load_lds_dwordx4 v[140:141], off
	v_lshl_add_u64 v[140:141], v[232:233], 0, s[56:57]
	s_mov_b32 m0, s0
	s_nop 0
	global_load_lds_dwordx4 v[140:141], off
	v_lshl_add_u64 v[140:141], v[234:235], 0, s[56:57]
	s_add_i32 m0, s0, 0x2000
	s_nop 0
	global_load_lds_dwordx4 v[140:141], off
	v_lshl_add_u64 v[140:141], v[236:237], 0, s[56:57]
	s_mov_b32 m0, s39
	s_nop 0
	global_load_lds_dwordx4 v[140:141], off
	v_lshl_add_u64 v[140:141], v[238:239], 0, s[56:57]
	s_mov_b32 m0, s40
	s_nop 0
	global_load_lds_dwordx4 v[140:141], off
	s_waitcnt vmcnt(8)
	s_waitcnt lgkmcnt(0)
	s_barrier
	s_setprio 1
	s_waitcnt lgkmcnt(0)
	v_mfma_f32_16x16x32_bf16 v[60:63], v[158:161], v[190:193], v[60:63]
	v_mfma_f32_16x16x32_bf16 v[56:59], v[166:169], v[190:193], v[56:59]
	v_mfma_f32_16x16x32_bf16 v[44:47], v[158:161], v[198:201], v[44:47]
	v_mfma_f32_16x16x32_bf16 v[40:43], v[166:169], v[198:201], v[40:43]
	v_mfma_f32_16x16x32_bf16 v[28:31], v[158:161], v[206:209], v[28:31]
	v_mfma_f32_16x16x32_bf16 v[24:27], v[166:169], v[206:209], v[24:27]
	v_mfma_f32_16x16x32_bf16 v[12:15], v[158:161], v[214:217], v[12:15]
	v_mfma_f32_16x16x32_bf16 v[8:11], v[166:169], v[214:217], v[8:11]
	v_mfma_f32_16x16x32_bf16 v[60:63], v[162:165], v[194:197], v[60:63]
	v_mfma_f32_16x16x32_bf16 v[56:59], v[170:173], v[194:197], v[56:59]
	v_mfma_f32_16x16x32_bf16 v[44:47], v[162:165], v[202:205], v[44:47]
	v_mfma_f32_16x16x32_bf16 v[40:43], v[170:173], v[202:205], v[40:43]
	v_mfma_f32_16x16x32_bf16 v[28:31], v[162:165], v[210:213], v[28:31]
	v_mfma_f32_16x16x32_bf16 v[24:27], v[170:173], v[210:213], v[24:27]
	v_mfma_f32_16x16x32_bf16 v[12:15], v[162:165], v[228:231], v[12:15]
	v_mfma_f32_16x16x32_bf16 v[8:11], v[170:173], v[228:231], v[8:11]
	v_mfma_f32_16x16x32_bf16 v[52:55], v[174:177], v[190:193], v[52:55]
	v_mfma_f32_16x16x32_bf16 v[48:51], v[182:185], v[190:193], v[48:51]
	v_mfma_f32_16x16x32_bf16 v[36:39], v[174:177], v[198:201], v[36:39]
	v_mfma_f32_16x16x32_bf16 v[32:35], v[182:185], v[198:201], v[32:35]
	v_mfma_f32_16x16x32_bf16 v[20:23], v[174:177], v[206:209], v[20:23]
	v_mfma_f32_16x16x32_bf16 v[16:19], v[182:185], v[206:209], v[16:19]
	v_mfma_f32_16x16x32_bf16 v[4:7], v[174:177], v[214:217], v[4:7]
	v_mfma_f32_16x16x32_bf16 v[0:3], v[182:185], v[214:217], v[0:3]
	v_mfma_f32_16x16x32_bf16 v[52:55], v[178:181], v[194:197], v[52:55]
	v_mfma_f32_16x16x32_bf16 v[48:51], v[186:189], v[194:197], v[48:51]
	v_mfma_f32_16x16x32_bf16 v[36:39], v[178:181], v[202:205], v[36:39]
	v_mfma_f32_16x16x32_bf16 v[32:35], v[186:189], v[202:205], v[32:35]
	v_mfma_f32_16x16x32_bf16 v[20:23], v[178:181], v[210:213], v[20:23]
	v_mfma_f32_16x16x32_bf16 v[16:19], v[186:189], v[210:213], v[16:19]
	v_mfma_f32_16x16x32_bf16 v[4:7], v[178:181], v[228:231], v[4:7]
	v_mfma_f32_16x16x32_bf16 v[0:3], v[186:189], v[228:231], v[0:3]
	s_setprio 0
	s_barrier
	s_add_u32 s48, s48, 0x100
	s_addc_u32 s49, s49, 0
	s_cmp_ge_i32 s50, s6
	s_mov_b64 s[0:1], s[2:3]
	s_mov_b32 s4, s50
	s_cbranch_scc0 .LBB0_314

; #define PG8_STAGE(bufoff, gbase, voff) do { _Pragma("unroll") for (int _i = 0; _i < 2; ++_i) \
;         __builtin_amdgcn_global_load_lds((const unsigned*)((const char*)(gbase) + (voff)[_i]), (LAS unsigned*)(lds + (bufoff) + ldsw + _i * 8192), 16, 0, 0); } while (0)
; #define PG8_LDA(dst, b, h) do { _Pragma("unroll") for (int m = 0; m < 4; ++m) _Pragma("unroll") for (int k = 0; k < 2; ++k) dst[m][k] = *(const LAS bf16x8*)(lds + PG8_SA(b, h) + aoff + m * 2048 + k * 1024); } while (0)
; #define PG8_LDB(dst, b, h) do { _Pragma("unroll") for (int n = 0; n < 2; ++n) _Pragma("unroll") for (int k = 0; k < 2; ++k) dst[n][k] = *(const LAS bf16x8*)(lds + PG8_SB(b, h) + boff + n * 2048 + k * 1024); } while (0)
; #define PG8_MMA(ai, bj, At, Bt) do { __builtin_amdgcn_s_setprio(1); _Pragma("unroll") for (int m = 0; m < 4; ++m) _Pragma("unroll") for (int n = 0; n < 2; ++n) _Pragma("unroll") for (int k = 0; k < 2; ++k) \
;         acc[ai][bj][m][n] = __builtin_amdgcn_mfma_f32_16x16x32_bf16(Bt[n][k], At[m][k], acc[ai][bj][m][n], 0, 0, 0); __builtin_amdgcn_s_setprio(0); } while (0)
; #define PG8_WAIT_V(n) asm volatile("s_waitcnt vmcnt(" #n ")" ::: "memory")
; #define PG8_WAIT_L(n) asm volatile("s_waitcnt lgkmcnt(" #n ")" ::: "memory")
; #define PG8_BAR __builtin_amdgcn_s_barrier()
; #define PG8_SCHED __builtin_amdgcn_sched_barrier(0)
;     ...
;             const bool last = (t == nt - 2);
;             const char* a1 = cA + (size_t)(t + 1) * kstep;
;             const char* a2 = last ? nA : cA + (size_t)(t + 2) * kstep; const char* b2 = last ? nB : cB + (size_t)(t + 2) * kstep;
;             const char* a3 = a2 + kstep; const char* b3 = b2 + kstep;
;             if constexpr (SP2) {
;             PG8_LDB(B0, 0, 0); PG8_LDB(B1, 0, 1); PG8_SCHED; PG8_LDA(At, 0, 0); PG8_STAGE(PG8_SA(1, 1), a1 + hstepA, voffA);
;             PG8_WAIT_V(8); PG8_WAIT_L(0); PG8_BAR; PG8_MMA(0, 0, At, B0); PG8_MMA(0, 1, At, B1); PG8_BAR; PG8_SCHED;
;             PG8_LDA(At, 0, 1); PG8_STAGE(PG8_SB(0, 0), b2, voffB); PG8_STAGE(PG8_SB(0, 1), b2 + hstepB, voffB); PG8_STAGE(PG8_SA(0, 0), a2, voffA);
;             PG8_WAIT_V(8); PG8_WAIT_L(0); PG8_BAR; PG8_MMA(1, 0, At, B0); PG8_MMA(1, 1, At, B1); PG8_BAR; PG8_SCHED;
.LBB0_345:
	s_add_i32 s53, s26, 2
	s_add_u32 s54, s12, 0xfffc0080
	s_addc_u32 s27, s13, -1
	s_add_i32 s56, 0, 0x10000
	s_cmp_eq_u32 s46, s26
	s_cselect_b32 s27, s17, s27
	s_cselect_b32 s26, s52, s54
	v_add_u32_e32 v152, s56, v143
	s_cselect_b32 s55, s19, s29
	s_cselect_b32 s54, s18, s28
	s_add_i32 s57, 0, 0x14000
	ds_read_b128 v[158:161], v152
	ds_read_b128 v[162:165], v152 offset:1024
	ds_read_b128 v[166:169], v152 offset:2048
	ds_read_b128 v[170:173], v152 offset:3072
	v_add_u32_e32 v152, s57, v143
	ds_read_b128 v[174:177], v152
	ds_read_b128 v[178:181], v152 offset:1024
	ds_read_b128 v[182:185], v152 offset:2048
	ds_read_b128 v[186:189], v152 offset:3072
	v_lshl_add_u64 v[218:219], s[12:13], 0, v[138:139]
	s_add_i32 m0, s25, 0xc000
	ds_read_b128 v[190:193], v157
	ds_read_b128 v[194:197], v157 offset:1024
	ds_read_b128 v[198:201], v157 offset:2048
	ds_read_b128 v[202:205], v157 offset:3072
	ds_read_b128 v[206:209], v157 offset:4096
	ds_read_b128 v[210:213], v157 offset:5120
	ds_read_b128 v[214:217], v157 offset:6144
	ds_read_b128 v[228:231], v157 offset:7168
	global_load_lds_dwordx4 v[218:219], off
	v_lshl_add_u64 v[218:219], s[12:13], 0, v[140:141]
	s_add_i32 m0, s25, 0xe000
	s_nop 0
	global_load_lds_dwordx4 v[218:219], off
	s_waitcnt vmcnt(8)
	s_waitcnt lgkmcnt(0)
	s_barrier
	s_setprio 1
	s_waitcnt lgkmcnt(0)
	v_mfma_f32_16x16x32_bf16 v[124:127], v[158:161], v[190:193], v[124:127]
	v_mfma_f32_16x16x32_bf16 v[120:123], v[166:169], v[190:193], v[120:123]
	v_mfma_f32_16x16x32_bf16 v[108:111], v[158:161], v[198:201], v[108:111]
	v_mfma_f32_16x16x32_bf16 v[104:107], v[166:169], v[198:201], v[104:107]
	v_mfma_f32_16x16x32_bf16 v[92:95], v[158:161], v[206:209], v[92:95]
	v_mfma_f32_16x16x32_bf16 v[88:91], v[166:169], v[206:209], v[88:91]
	v_mfma_f32_16x16x32_bf16 v[76:79], v[158:161], v[214:217], v[76:79]
	v_mfma_f32_16x16x32_bf16 v[72:75], v[166:169], v[214:217], v[72:75]
	v_mfma_f32_16x16x32_bf16 v[124:127], v[162:165], v[194:197], v[124:127]
	v_mfma_f32_16x16x32_bf16 v[120:123], v[170:173], v[194:197], v[120:123]
	v_mfma_f32_16x16x32_bf16 v[108:111], v[162:165], v[202:205], v[108:111]
	v_mfma_f32_16x16x32_bf16 v[104:107], v[170:173], v[202:205], v[104:107]
	v_mfma_f32_16x16x32_bf16 v[92:95], v[162:165], v[210:213], v[92:95]
	v_mfma_f32_16x16x32_bf16 v[88:91], v[170:173], v[210:213], v[88:91]
	v_mfma_f32_16x16x32_bf16 v[76:79], v[162:165], v[228:231], v[76:79]
	v_mfma_f32_16x16x32_bf16 v[72:75], v[170:173], v[228:231], v[72:75]
	v_mfma_f32_16x16x32_bf16 v[116:119], v[174:177], v[190:193], v[116:119]
	v_mfma_f32_16x16x32_bf16 v[112:115], v[182:185], v[190:193], v[112:115]
	v_mfma_f32_16x16x32_bf16 v[100:103], v[174:177], v[198:201], v[100:103]
	v_mfma_f32_16x16x32_bf16 v[96:99], v[182:185], v[198:201], v[96:99]
	v_mfma_f32_16x16x32_bf16 v[84:87], v[174:177], v[206:209], v[84:87]
	v_mfma_f32_16x16x32_bf16 v[80:83], v[182:185], v[206:209], v[80:83]
	v_mfma_f32_16x16x32_bf16 v[68:71], v[174:177], v[214:217], v[68:71]
	v_mfma_f32_16x16x32_bf16 v[64:67], v[182:185], v[214:217], v[64:67]
	v_mfma_f32_16x16x32_bf16 v[116:119], v[178:181], v[194:197], v[116:119]
	v_mfma_f32_16x16x32_bf16 v[112:115], v[186:189], v[194:197], v[112:115]
	v_mfma_f32_16x16x32_bf16 v[100:103], v[178:181], v[202:205], v[100:103]
	v_mfma_f32_16x16x32_bf16 v[96:99], v[186:189], v[202:205], v[96:99]
	v_mfma_f32_16x16x32_bf16 v[84:87], v[178:181], v[210:213], v[84:87]
	v_mfma_f32_16x16x32_bf16 v[80:83], v[186:189], v[210:213], v[80:83]
	v_mfma_f32_16x16x32_bf16 v[68:71], v[178:181], v[228:231], v[68:71]
	v_mfma_f32_16x16x32_bf16 v[64:67], v[186:189], v[228:231], v[64:67]
	s_setprio 0
	s_barrier
	s_add_i32 s56, s56, s38
	v_lshl_add_u64 v[218:219], s[54:55], 0, v[130:131]
	s_mov_b32 m0, s56
	ds_read_b128 v[190:193], v157 offset:16384
	ds_read_b128 v[194:197], v157 offset:17408
	ds_read_b128 v[198:201], v157 offset:18432
	ds_read_b128 v[202:205], v157 offset:19456
	ds_read_b128 v[206:209], v157 offset:20480
	ds_read_b128 v[210:213], v157 offset:21504
	ds_read_b128 v[214:217], v157 offset:22528
	ds_read_b128 v[228:231], v157 offset:23552
	global_load_lds_dwordx4 v[218:219], off
	s_add_i32 m0, s56, 0x2000
	v_lshl_add_u64 v[232:233], s[54:55], 0, v[134:135]
	s_add_u32 s54, s54, s0
	s_addc_u32 s55, s55, s1
	s_add_i32 s56, s57, s38
	global_load_lds_dwordx4 v[232:233], off
	v_lshl_add_u64 v[234:235], s[54:55], 0, v[130:131]
	s_mov_b32 m0, s56
	v_lshl_add_u64 v[236:237], s[54:55], 0, v[134:135]
	global_load_lds_dwordx4 v[234:235], off
	s_add_i32 m0, s56, 0x2000
	v_lshl_add_u64 v[238:239], s[26:27], 0, v[128:129]
	global_load_lds_dwordx4 v[236:237], off
	s_mov_b32 m0, s25
	v_lshl_add_u64 v[240:241], s[26:27], 0, v[132:133]
	global_load_lds_dwordx4 v[238:239], off
	s_mov_b32 m0, s39
	s_nop 0
	global_load_lds_dwordx4 v[240:241], off
	s_waitcnt vmcnt(8)
	s_waitcnt lgkmcnt(0)
	s_barrier
; #define PG8_STAGE(bufoff, gbase, voff) do { _Pragma("unroll") for (int _i = 0; _i < 2; ++_i) \
;         __builtin_amdgcn_global_load_lds((const unsigned*)((const char*)(gbase) + (voff)[_i]), (LAS unsigned*)(lds + (bufoff) + ldsw + _i * 8192), 16, 0, 0); } while (0)
; #define PG8_LDA(dst, b, h) do { _Pragma("unroll") for (int m = 0; m < 4; ++m) _Pragma("unroll") for (int k = 0; k < 2; ++k) dst[m][k] = *(const LAS bf16x8*)(lds + PG8_SA(b, h) + aoff + m * 2048 + k * 1024); } while (0)
; #define PG8_LDB(dst, b, h) do { _Pragma("unroll") for (int n = 0; n < 2; ++n) _Pragma("unroll") for (int k = 0; k < 2; ++k) dst[n][k] = *(const LAS bf16x8*)(lds + PG8_SB(b, h) + boff + n * 2048 + k * 1024); } while (0)
; #define PG8_MMA(ai, bj, At, Bt) do { __builtin_amdgcn_s_setprio(1); _Pragma("unroll") for (int m = 0; m < 4; ++m) _Pragma("unroll") for (int n = 0; n < 2; ++n) _Pragma("unroll") for (int k = 0; k < 2; ++k) \
;         acc[ai][bj][m][n] = __builtin_amdgcn_mfma_f32_16x16x32_bf16(Bt[n][k], At[m][k], acc[ai][bj][m][n], 0, 0, 0); __builtin_amdgcn_s_setprio(0); } while (0)
; #define PG8_WAIT_V(n) asm volatile("s_waitcnt vmcnt(" #n ")" ::: "memory")
; #define PG8_WAIT_L(n) asm volatile("s_waitcnt lgkmcnt(" #n ")" ::: "memory")
; #define PG8_BAR __builtin_amdgcn_s_barrier()
; #define PG8_SCHED __builtin_amdgcn_sched_barrier(0)
;     ...
;             PG8_WAIT_V(8); PG8_WAIT_L(0); PG8_BAR; PG8_MMA(1, 0, At, B0); PG8_MMA(1, 1, At, B1); PG8_BAR; PG8_SCHED;
;             PG8_LDB(B0, 1, 0); PG8_LDB(B1, 1, 1); PG8_SCHED; PG8_LDA(At, 1, 0); PG8_STAGE(PG8_SA(0, 1), a2 + hstepA, voffA);
;             PG8_WAIT_V(8); PG8_WAIT_L(0); PG8_BAR; PG8_MMA(0, 0, At, B0); PG8_MMA(0, 1, At, B1); PG8_BAR; PG8_SCHED;
	s_setprio 1
	s_waitcnt lgkmcnt(0)
	v_mfma_f32_16x16x32_bf16 v[60:63], v[158:161], v[190:193], v[60:63]
	v_mfma_f32_16x16x32_bf16 v[56:59], v[166:169], v[190:193], v[56:59]
	v_mfma_f32_16x16x32_bf16 v[44:47], v[158:161], v[198:201], v[44:47]
	v_mfma_f32_16x16x32_bf16 v[40:43], v[166:169], v[198:201], v[40:43]
	v_mfma_f32_16x16x32_bf16 v[28:31], v[158:161], v[206:209], v[28:31]
	v_mfma_f32_16x16x32_bf16 v[24:27], v[166:169], v[206:209], v[24:27]
	v_mfma_f32_16x16x32_bf16 v[12:15], v[158:161], v[214:217], v[12:15]
	v_mfma_f32_16x16x32_bf16 v[8:11], v[166:169], v[214:217], v[8:11]
	v_mfma_f32_16x16x32_bf16 v[60:63], v[162:165], v[194:197], v[60:63]
	v_mfma_f32_16x16x32_bf16 v[56:59], v[170:173], v[194:197], v[56:59]
	v_mfma_f32_16x16x32_bf16 v[44:47], v[162:165], v[202:205], v[44:47]
	v_mfma_f32_16x16x32_bf16 v[40:43], v[170:173], v[202:205], v[40:43]
	v_mfma_f32_16x16x32_bf16 v[28:31], v[162:165], v[210:213], v[28:31]
	v_mfma_f32_16x16x32_bf16 v[24:27], v[170:173], v[210:213], v[24:27]
	v_mfma_f32_16x16x32_bf16 v[12:15], v[162:165], v[228:231], v[12:15]
	v_mfma_f32_16x16x32_bf16 v[8:11], v[170:173], v[228:231], v[8:11]
	v_mfma_f32_16x16x32_bf16 v[52:55], v[174:177], v[190:193], v[52:55]
	v_mfma_f32_16x16x32_bf16 v[48:51], v[182:185], v[190:193], v[48:51]
	v_mfma_f32_16x16x32_bf16 v[36:39], v[174:177], v[198:201], v[36:39]
	v_mfma_f32_16x16x32_bf16 v[32:35], v[182:185], v[198:201], v[32:35]
	v_mfma_f32_16x16x32_bf16 v[20:23], v[174:177], v[206:209], v[20:23]
	v_mfma_f32_16x16x32_bf16 v[16:19], v[182:185], v[206:209], v[16:19]
	v_mfma_f32_16x16x32_bf16 v[4:7], v[174:177], v[214:217], v[4:7]
	v_mfma_f32_16x16x32_bf16 v[0:3], v[182:185], v[214:217], v[0:3]
	v_mfma_f32_16x16x32_bf16 v[52:55], v[178:181], v[194:197], v[52:55]
	v_mfma_f32_16x16x32_bf16 v[48:51], v[186:189], v[194:197], v[48:51]
	v_mfma_f32_16x16x32_bf16 v[36:39], v[178:181], v[202:205], v[36:39]
	v_mfma_f32_16x16x32_bf16 v[32:35], v[186:189], v[202:205], v[32:35]
	v_mfma_f32_16x16x32_bf16 v[20:23], v[178:181], v[210:213], v[20:23]
	v_mfma_f32_16x16x32_bf16 v[16:19], v[186:189], v[210:213], v[16:19]
	v_mfma_f32_16x16x32_bf16 v[4:7], v[178:181], v[228:231], v[4:7]
	v_mfma_f32_16x16x32_bf16 v[0:3], v[186:189], v[228:231], v[0:3]
	s_setprio 0
	s_barrier
	s_add_i32 s54, 0, 0x18000
	v_add_u32_e32 v152, s54, v143
	s_add_i32 s55, 0, 0x1c000
	ds_read_b128 v[158:161], v152
	ds_read_b128 v[162:165], v152 offset:1024
	ds_read_b128 v[166:169], v152 offset:2048
	ds_read_b128 v[170:173], v152 offset:3072
	v_add_u32_e32 v152, s55, v143
	ds_read_b128 v[174:177], v152
	ds_read_b128 v[178:181], v152 offset:1024
	ds_read_b128 v[182:185], v152 offset:2048
	ds_read_b128 v[186:189], v152 offset:3072
	s_add_u32 s26, s26, 0x40000
	s_addc_u32 s27, s27, 0
	s_mov_b32 m0, s40
	v_lshl_add_u64 v[242:243], s[26:27], 0, v[128:129]
	ds_read_b128 v[190:193], v157 offset:32768
	ds_read_b128 v[194:197], v157 offset:33792
	ds_read_b128 v[198:201], v157 offset:34816
	ds_read_b128 v[202:205], v157 offset:35840
	ds_read_b128 v[206:209], v157 offset:36864
	ds_read_b128 v[210:213], v157 offset:37888
	ds_read_b128 v[214:217], v157 offset:38912
	ds_read_b128 v[228:231], v157 offset:39936
	global_load_lds_dwordx4 v[242:243], off
	v_lshl_add_u64 v[242:243], s[26:27], 0, v[132:133]
	s_mov_b32 m0, s41
	s_nop 0
	global_load_lds_dwordx4 v[242:243], off
	s_waitcnt vmcnt(8)
	s_waitcnt lgkmcnt(0)
	s_barrier
	s_setprio 1
	s_waitcnt lgkmcnt(0)
	v_mfma_f32_16x16x32_bf16 v[124:127], v[158:161], v[190:193], v[124:127]
	v_mfma_f32_16x16x32_bf16 v[120:123], v[166:169], v[190:193], v[120:123]
	v_mfma_f32_16x16x32_bf16 v[108:111], v[158:161], v[198:201], v[108:111]
	v_mfma_f32_16x16x32_bf16 v[104:107], v[166:169], v[198:201], v[104:107]
	v_mfma_f32_16x16x32_bf16 v[92:95], v[158:161], v[206:209], v[92:95]
	v_mfma_f32_16x16x32_bf16 v[88:91], v[166:169], v[206:209], v[88:91]
	v_mfma_f32_16x16x32_bf16 v[76:79], v[158:161], v[214:217], v[76:79]
	v_mfma_f32_16x16x32_bf16 v[72:75], v[166:169], v[214:217], v[72:75]
	v_mfma_f32_16x16x32_bf16 v[124:127], v[162:165], v[194:197], v[124:127]
	v_mfma_f32_16x16x32_bf16 v[120:123], v[170:173], v[194:197], v[120:123]
	v_mfma_f32_16x16x32_bf16 v[108:111], v[162:165], v[202:205], v[108:111]
	v_mfma_f32_16x16x32_bf16 v[104:107], v[170:173], v[202:205], v[104:107]
	v_mfma_f32_16x16x32_bf16 v[92:95], v[162:165], v[210:213], v[92:95]
	v_mfma_f32_16x16x32_bf16 v[88:91], v[170:173], v[210:213], v[88:91]
	v_mfma_f32_16x16x32_bf16 v[76:79], v[162:165], v[228:231], v[76:79]
	v_mfma_f32_16x16x32_bf16 v[72:75], v[170:173], v[228:231], v[72:75]
	v_mfma_f32_16x16x32_bf16 v[116:119], v[174:177], v[190:193], v[116:119]
	v_mfma_f32_16x16x32_bf16 v[112:115], v[182:185], v[190:193], v[112:115]
	v_mfma_f32_16x16x32_bf16 v[100:103], v[174:177], v[198:201], v[100:103]
	v_mfma_f32_16x16x32_bf16 v[96:99], v[182:185], v[198:201], v[96:99]
	v_mfma_f32_16x16x32_bf16 v[84:87], v[174:177], v[206:209], v[84:87]
	v_mfma_f32_16x16x32_bf16 v[80:83], v[182:185], v[206:209], v[80:83]
	v_mfma_f32_16x16x32_bf16 v[68:71], v[174:177], v[214:217], v[68:71]
	v_mfma_f32_16x16x32_bf16 v[64:67], v[182:185], v[214:217], v[64:67]
	v_mfma_f32_16x16x32_bf16 v[116:119], v[178:181], v[194:197], v[116:119]
	v_mfma_f32_16x16x32_bf16 v[112:115], v[186:189], v[194:197], v[112:115]
	v_mfma_f32_16x16x32_bf16 v[100:103], v[178:181], v[202:205], v[100:103]
	v_mfma_f32_16x16x32_bf16 v[96:99], v[186:189], v[202:205], v[96:99]
	v_mfma_f32_16x16x32_bf16 v[84:87], v[178:181], v[210:213], v[84:87]
	v_mfma_f32_16x16x32_bf16 v[80:83], v[186:189], v[210:213], v[80:83]
	v_mfma_f32_16x16x32_bf16 v[68:71], v[178:181], v[228:231], v[68:71]
	v_mfma_f32_16x16x32_bf16 v[64:67], v[186:189], v[228:231], v[64:67]
	s_setprio 0
	s_barrier
; #define PG8_STAGE(bufoff, gbase, voff) do { _Pragma("unroll") for (int _i = 0; _i < 2; ++_i) \
;         __builtin_amdgcn_global_load_lds((const unsigned*)((const char*)(gbase) + (voff)[_i]), (LAS unsigned*)(lds + (bufoff) + ldsw + _i * 8192), 16, 0, 0); } while (0)
; #define PG8_LDA(dst, b, h) do { _Pragma("unroll") for (int m = 0; m < 4; ++m) _Pragma("unroll") for (int k = 0; k < 2; ++k) dst[m][k] = *(const LAS bf16x8*)(lds + PG8_SA(b, h) + aoff + m * 2048 + k * 1024); } while (0)
; #define PG8_MMA(ai, bj, At, Bt) do { __builtin_amdgcn_s_setprio(1); _Pragma("unroll") for (int m = 0; m < 4; ++m) _Pragma("unroll") for (int n = 0; n < 2; ++n) _Pragma("unroll") for (int k = 0; k < 2; ++k) \
;         acc[ai][bj][m][n] = __builtin_amdgcn_mfma_f32_16x16x32_bf16(Bt[n][k], At[m][k], acc[ai][bj][m][n], 0, 0, 0); __builtin_amdgcn_s_setprio(0); } while (0)
; #define PG8_WAIT_V(n) asm volatile("s_waitcnt vmcnt(" #n ")" ::: "memory")
; #define PG8_WAIT_L(n) asm volatile("s_waitcnt lgkmcnt(" #n ")" ::: "memory")
; #define PG8_BAR __builtin_amdgcn_s_barrier()
; #define PG8_SCHED __builtin_amdgcn_sched_barrier(0)
;     ...
;         for (int t = 0; t < nt; t += 2) {
;             const bool last = (t == nt - 2);
;             const char* a1 = cA + (size_t)(t + 1) * kstep;
;             const char* a2 = last ? nA : cA + (size_t)(t + 2) * kstep; const char* b2 = last ? nB : cB + (size_t)(t + 2) * kstep;
;     ...
;             PG8_LDA(At, 1, 1); PG8_STAGE(PG8_SB(1, 0), b3, voffB); PG8_STAGE(PG8_SB(1, 1), b3 + hstepB, voffB); PG8_STAGE(PG8_SA(1, 0), a3, voffA);
;             PG8_WAIT_V(8); PG8_WAIT_L(0); PG8_BAR; PG8_MMA(1, 0, At, B0); PG8_MMA(1, 1, At, B1); PG8_BAR; PG8_SCHED;
	s_add_i32 s26, s54, s38
	v_lshl_add_u64 v[218:219], v[218:219], 0, s[58:59]
	s_mov_b32 m0, s26
	ds_read_b128 v[190:193], v157 offset:49152
	ds_read_b128 v[194:197], v157 offset:50176
	ds_read_b128 v[198:201], v157 offset:51200
	ds_read_b128 v[202:205], v157 offset:52224
	ds_read_b128 v[206:209], v157 offset:53248
	ds_read_b128 v[210:213], v157 offset:54272
	ds_read_b128 v[214:217], v157 offset:55296
	ds_read_b128 v[228:231], v157 offset:56320
	global_load_lds_dwordx4 v[218:219], off
	v_lshl_add_u64 v[218:219], v[232:233], 0, s[58:59]
	s_add_i32 m0, s26, 0x2000
	s_add_i32 s26, s55, s38
	global_load_lds_dwordx4 v[218:219], off
	v_lshl_add_u64 v[218:219], v[234:235], 0, s[58:59]
	s_mov_b32 m0, s26
	s_nop 0
	global_load_lds_dwordx4 v[218:219], off
	v_lshl_add_u64 v[218:219], v[236:237], 0, s[58:59]
	s_add_i32 m0, s26, 0x2000
	s_nop 0
	global_load_lds_dwordx4 v[218:219], off
	v_lshl_add_u64 v[218:219], v[238:239], 0, s[58:59]
	s_mov_b32 m0, s42
	s_nop 0
	global_load_lds_dwordx4 v[218:219], off
	v_lshl_add_u64 v[218:219], v[240:241], 0, s[58:59]
	s_mov_b32 m0, s43
	s_nop 0
	global_load_lds_dwordx4 v[218:219], off
	s_waitcnt vmcnt(8)
	s_waitcnt lgkmcnt(0)
	s_barrier
	s_setprio 1
	s_waitcnt lgkmcnt(0)
	v_mfma_f32_16x16x32_bf16 v[60:63], v[158:161], v[190:193], v[60:63]
	v_mfma_f32_16x16x32_bf16 v[56:59], v[166:169], v[190:193], v[56:59]
	v_mfma_f32_16x16x32_bf16 v[44:47], v[158:161], v[198:201], v[44:47]
	v_mfma_f32_16x16x32_bf16 v[40:43], v[166:169], v[198:201], v[40:43]
	v_mfma_f32_16x16x32_bf16 v[28:31], v[158:161], v[206:209], v[28:31]
	v_mfma_f32_16x16x32_bf16 v[24:27], v[166:169], v[206:209], v[24:27]
	v_mfma_f32_16x16x32_bf16 v[12:15], v[158:161], v[214:217], v[12:15]
	v_mfma_f32_16x16x32_bf16 v[8:11], v[166:169], v[214:217], v[8:11]
	v_mfma_f32_16x16x32_bf16 v[60:63], v[162:165], v[194:197], v[60:63]
	v_mfma_f32_16x16x32_bf16 v[56:59], v[170:173], v[194:197], v[56:59]
	v_mfma_f32_16x16x32_bf16 v[44:47], v[162:165], v[202:205], v[44:47]
	v_mfma_f32_16x16x32_bf16 v[40:43], v[170:173], v[202:205], v[40:43]
	v_mfma_f32_16x16x32_bf16 v[28:31], v[162:165], v[210:213], v[28:31]
	v_mfma_f32_16x16x32_bf16 v[24:27], v[170:173], v[210:213], v[24:27]
	v_mfma_f32_16x16x32_bf16 v[12:15], v[162:165], v[228:231], v[12:15]
	v_mfma_f32_16x16x32_bf16 v[8:11], v[170:173], v[228:231], v[8:11]
	v_mfma_f32_16x16x32_bf16 v[52:55], v[174:177], v[190:193], v[52:55]
	v_mfma_f32_16x16x32_bf16 v[48:51], v[182:185], v[190:193], v[48:51]
	v_mfma_f32_16x16x32_bf16 v[36:39], v[174:177], v[198:201], v[36:39]
	v_mfma_f32_16x16x32_bf16 v[32:35], v[182:185], v[198:201], v[32:35]
	v_mfma_f32_16x16x32_bf16 v[20:23], v[174:177], v[206:209], v[20:23]
	v_mfma_f32_16x16x32_bf16 v[16:19], v[182:185], v[206:209], v[16:19]
	v_mfma_f32_16x16x32_bf16 v[4:7], v[174:177], v[214:217], v[4:7]
	v_mfma_f32_16x16x32_bf16 v[0:3], v[182:185], v[214:217], v[0:3]
	v_mfma_f32_16x16x32_bf16 v[52:55], v[178:181], v[194:197], v[52:55]
	v_mfma_f32_16x16x32_bf16 v[48:51], v[186:189], v[194:197], v[48:51]
	v_mfma_f32_16x16x32_bf16 v[36:39], v[178:181], v[202:205], v[36:39]
	v_mfma_f32_16x16x32_bf16 v[32:35], v[186:189], v[202:205], v[32:35]
	v_mfma_f32_16x16x32_bf16 v[20:23], v[178:181], v[210:213], v[20:23]
	v_mfma_f32_16x16x32_bf16 v[16:19], v[186:189], v[210:213], v[16:19]
	v_mfma_f32_16x16x32_bf16 v[4:7], v[178:181], v[228:231], v[4:7]
	v_mfma_f32_16x16x32_bf16 v[0:3], v[186:189], v[228:231], v[0:3]
	s_setprio 0
	s_barrier
	s_add_u32 s12, s12, 0x100
	s_addc_u32 s13, s13, 0
	s_add_u32 s28, s28, 0x100
	s_addc_u32 s29, s29, 0
	s_cmp_ge_i32 s53, s44
	s_mov_b32 s26, s53
	s_cbranch_scc0 .LBB0_345

; #define PG8_STAGE(bufoff, gbase, voff) do { _Pragma("unroll") for (int _i = 0; _i < 2; ++_i) \
;         __builtin_amdgcn_global_load_lds((const unsigned*)((const char*)(gbase) + (voff)[_i]), (LAS unsigned*)(lds + (bufoff) + ldsw + _i * 8192), 16, 0, 0); } while (0)
; #define PG8_LDA(dst, b, h) do { _Pragma("unroll") for (int m = 0; m < 4; ++m) _Pragma("unroll") for (int k = 0; k < 2; ++k) dst[m][k] = *(const LAS bf16x8*)(lds + PG8_SA(b, h) + aoff + m * 2048 + k * 1024); } while (0)
; #define PG8_LDB(dst, b, h) do { _Pragma("unroll") for (int n = 0; n < 2; ++n) _Pragma("unroll") for (int k = 0; k < 2; ++k) dst[n][k] = *(const LAS bf16x8*)(lds + PG8_SB(b, h) + boff + n * 2048 + k * 1024); } while (0)
; #define PG8_MMA(ai, bj, At, Bt) do { __builtin_amdgcn_s_setprio(1); _Pragma("unroll") for (int m = 0; m < 4; ++m) _Pragma("unroll") for (int n = 0; n < 2; ++n) _Pragma("unroll") for (int k = 0; k < 2; ++k) \
;         acc[ai][bj][m][n] = __builtin_amdgcn_mfma_f32_16x16x32_bf16(Bt[n][k], At[m][k], acc[ai][bj][m][n], 0, 0, 0); __builtin_amdgcn_s_setprio(0); } while (0)
; #define PG8_WAIT_V(n) asm volatile("s_waitcnt vmcnt(" #n ")" ::: "memory")
; #define PG8_WAIT_L(n) asm volatile("s_waitcnt lgkmcnt(" #n ")" ::: "memory")
; #define PG8_BAR __builtin_amdgcn_s_barrier()
; #define PG8_SCHED __builtin_amdgcn_sched_barrier(0)
;     ...
;             const bool last = (t == nt - 2);
;             const char* a1 = cA + (size_t)(t + 1) * kstep;
;             const char* a2 = last ? nA : cA + (size_t)(t + 2) * kstep; const char* b2 = last ? nB : cB + (size_t)(t + 2) * kstep;
;             const char* a3 = a2 + kstep; const char* b3 = b2 + kstep;
;             if constexpr (SP2) {
;             PG8_LDB(B0, 0, 0); PG8_LDB(B1, 0, 1); PG8_SCHED; PG8_LDA(At, 0, 0); PG8_STAGE(PG8_SA(1, 1), a1 + hstepA, voffA);
;             PG8_WAIT_V(8); PG8_WAIT_L(0); PG8_BAR; PG8_MMA(0, 0, At, B0); PG8_MMA(0, 1, At, B1); PG8_BAR; PG8_SCHED;
;             PG8_LDA(At, 0, 1); PG8_STAGE(PG8_SB(0, 0), b2, voffB); PG8_STAGE(PG8_SB(0, 1), b2 + hstepB, voffB); PG8_STAGE(PG8_SA(0, 0), a2, voffA);
;             PG8_WAIT_V(8); PG8_WAIT_L(0); PG8_BAR; PG8_MMA(1, 0, At, B0); PG8_MMA(1, 1, At, B1); PG8_BAR; PG8_SCHED;
.LBB0_553:
	s_add_i32 s52, s26, 2
	s_add_u32 s53, s12, 0xfffc0080
	s_addc_u32 s27, s13, -1
	s_add_i32 s56, 0, 0x10000
	s_cmp_eq_u32 s45, s26
	s_cselect_b32 s27, s21, s27
	s_cselect_b32 s26, s51, s53
	v_add_u32_e32 v146, s56, v161
	s_cselect_b32 s55, s23, s29
	s_cselect_b32 s54, s22, s28
	s_add_i32 s53, 0, 0x14000
	ds_read_b128 v[164:167], v146
	ds_read_b128 v[168:171], v146 offset:1024
	ds_read_b128 v[172:175], v146 offset:2048
	ds_read_b128 v[176:179], v146 offset:3072
	v_add_u32_e32 v146, s53, v161
	ds_read_b128 v[180:183], v146
	ds_read_b128 v[184:187], v146 offset:1024
	ds_read_b128 v[188:191], v146 offset:2048
	ds_read_b128 v[192:195], v146 offset:3072
	v_lshl_add_u64 v[158:159], s[12:13], 0, v[142:143]
	s_add_i32 m0, s36, 0xc000
	ds_read_b128 v[196:199], v163
	ds_read_b128 v[200:203], v163 offset:1024
	ds_read_b128 v[204:207], v163 offset:2048
	ds_read_b128 v[208:211], v163 offset:3072
	ds_read_b128 v[212:215], v163 offset:4096
	ds_read_b128 v[216:219], v163 offset:5120
	ds_read_b128 v[228:231], v163 offset:6144
	ds_read_b128 v[232:235], v163 offset:7168
	global_load_lds_dwordx4 v[158:159], off
	v_lshl_add_u64 v[158:159], s[12:13], 0, v[156:157]
	s_add_i32 m0, s36, 0xe000
	s_nop 0
	global_load_lds_dwordx4 v[158:159], off
	s_waitcnt vmcnt(8)
	s_waitcnt lgkmcnt(0)
	s_barrier
	s_setprio 1
	s_waitcnt lgkmcnt(0)
	v_mfma_f32_16x16x32_bf16 v[124:127], v[164:167], v[196:199], v[124:127]
	v_mfma_f32_16x16x32_bf16 v[120:123], v[172:175], v[196:199], v[120:123]
	v_mfma_f32_16x16x32_bf16 v[108:111], v[164:167], v[204:207], v[108:111]
	v_mfma_f32_16x16x32_bf16 v[104:107], v[172:175], v[204:207], v[104:107]
	v_mfma_f32_16x16x32_bf16 v[92:95], v[164:167], v[212:215], v[92:95]
	v_mfma_f32_16x16x32_bf16 v[88:91], v[172:175], v[212:215], v[88:91]
	v_mfma_f32_16x16x32_bf16 v[76:79], v[164:167], v[228:231], v[76:79]
	v_mfma_f32_16x16x32_bf16 v[72:75], v[172:175], v[228:231], v[72:75]
	v_mfma_f32_16x16x32_bf16 v[124:127], v[168:171], v[200:203], v[124:127]
	v_mfma_f32_16x16x32_bf16 v[120:123], v[176:179], v[200:203], v[120:123]
	v_mfma_f32_16x16x32_bf16 v[108:111], v[168:171], v[208:211], v[108:111]
	v_mfma_f32_16x16x32_bf16 v[104:107], v[176:179], v[208:211], v[104:107]
	v_mfma_f32_16x16x32_bf16 v[92:95], v[168:171], v[216:219], v[92:95]
	v_mfma_f32_16x16x32_bf16 v[88:91], v[176:179], v[216:219], v[88:91]
	v_mfma_f32_16x16x32_bf16 v[76:79], v[168:171], v[232:235], v[76:79]
	v_mfma_f32_16x16x32_bf16 v[72:75], v[176:179], v[232:235], v[72:75]
	v_mfma_f32_16x16x32_bf16 v[116:119], v[180:183], v[196:199], v[116:119]
	v_mfma_f32_16x16x32_bf16 v[112:115], v[188:191], v[196:199], v[112:115]
	v_mfma_f32_16x16x32_bf16 v[100:103], v[180:183], v[204:207], v[100:103]
	v_mfma_f32_16x16x32_bf16 v[96:99], v[188:191], v[204:207], v[96:99]
	v_mfma_f32_16x16x32_bf16 v[84:87], v[180:183], v[212:215], v[84:87]
	v_mfma_f32_16x16x32_bf16 v[80:83], v[188:191], v[212:215], v[80:83]
	v_mfma_f32_16x16x32_bf16 v[68:71], v[180:183], v[228:231], v[68:71]
	v_mfma_f32_16x16x32_bf16 v[64:67], v[188:191], v[228:231], v[64:67]
	v_mfma_f32_16x16x32_bf16 v[116:119], v[184:187], v[200:203], v[116:119]
	v_mfma_f32_16x16x32_bf16 v[112:115], v[192:195], v[200:203], v[112:115]
	v_mfma_f32_16x16x32_bf16 v[100:103], v[184:187], v[208:211], v[100:103]
	v_mfma_f32_16x16x32_bf16 v[96:99], v[192:195], v[208:211], v[96:99]
	v_mfma_f32_16x16x32_bf16 v[84:87], v[184:187], v[216:219], v[84:87]
	v_mfma_f32_16x16x32_bf16 v[80:83], v[192:195], v[216:219], v[80:83]
	v_mfma_f32_16x16x32_bf16 v[68:71], v[184:187], v[232:235], v[68:71]
	v_mfma_f32_16x16x32_bf16 v[64:67], v[192:195], v[232:235], v[64:67]
	s_setprio 0
	s_barrier
	s_add_i32 s56, s56, s35
	v_lshl_add_u64 v[158:159], s[54:55], 0, v[130:131]
	s_mov_b32 m0, s56
	ds_read_b128 v[196:199], v163 offset:16384
	ds_read_b128 v[200:203], v163 offset:17408
	ds_read_b128 v[204:207], v163 offset:18432
	ds_read_b128 v[208:211], v163 offset:19456
	ds_read_b128 v[212:215], v163 offset:20480
	ds_read_b128 v[216:219], v163 offset:21504
	ds_read_b128 v[228:231], v163 offset:22528
	ds_read_b128 v[232:235], v163 offset:23552
	global_load_lds_dwordx4 v[158:159], off
	s_add_i32 m0, s56, 0x2000
	v_lshl_add_u64 v[236:237], s[54:55], 0, v[134:135]
	s_add_u32 s54, s54, s0
	s_addc_u32 s55, s55, s1
	s_add_i32 s53, s53, s35
	global_load_lds_dwordx4 v[236:237], off
	v_lshl_add_u64 v[238:239], s[54:55], 0, v[130:131]
	s_mov_b32 m0, s53
	v_lshl_add_u64 v[240:241], s[54:55], 0, v[134:135]
	global_load_lds_dwordx4 v[238:239], off
	s_add_i32 m0, s53, 0x2000
	v_lshl_add_u64 v[242:243], s[26:27], 0, v[128:129]
	global_load_lds_dwordx4 v[240:241], off
	s_mov_b32 m0, s36
	v_lshl_add_u64 v[244:245], s[26:27], 0, v[132:133]
	global_load_lds_dwordx4 v[242:243], off
	s_mov_b32 m0, s37
	s_nop 0
	global_load_lds_dwordx4 v[244:245], off
	s_waitcnt vmcnt(8)
	s_waitcnt lgkmcnt(0)
	s_barrier
; #define PG8_STAGE(bufoff, gbase, voff) do { _Pragma("unroll") for (int _i = 0; _i < 2; ++_i) \
;         __builtin_amdgcn_global_load_lds((const unsigned*)((const char*)(gbase) + (voff)[_i]), (LAS unsigned*)(lds + (bufoff) + ldsw + _i * 8192), 16, 0, 0); } while (0)
; #define PG8_LDA(dst, b, h) do { _Pragma("unroll") for (int m = 0; m < 4; ++m) _Pragma("unroll") for (int k = 0; k < 2; ++k) dst[m][k] = *(const LAS bf16x8*)(lds + PG8_SA(b, h) + aoff + m * 2048 + k * 1024); } while (0)
; #define PG8_LDB(dst, b, h) do { _Pragma("unroll") for (int n = 0; n < 2; ++n) _Pragma("unroll") for (int k = 0; k < 2; ++k) dst[n][k] = *(const LAS bf16x8*)(lds + PG8_SB(b, h) + boff + n * 2048 + k * 1024); } while (0)
; #define PG8_MMA(ai, bj, At, Bt) do { __builtin_amdgcn_s_setprio(1); _Pragma("unroll") for (int m = 0; m < 4; ++m) _Pragma("unroll") for (int n = 0; n < 2; ++n) _Pragma("unroll") for (int k = 0; k < 2; ++k) \
;         acc[ai][bj][m][n] = __builtin_amdgcn_mfma_f32_16x16x32_bf16(Bt[n][k], At[m][k], acc[ai][bj][m][n], 0, 0, 0); __builtin_amdgcn_s_setprio(0); } while (0)
; #define PG8_WAIT_V(n) asm volatile("s_waitcnt vmcnt(" #n ")" ::: "memory")
; #define PG8_WAIT_L(n) asm volatile("s_waitcnt lgkmcnt(" #n ")" ::: "memory")
; #define PG8_BAR __builtin_amdgcn_s_barrier()
; #define PG8_SCHED __builtin_amdgcn_sched_barrier(0)
;     ...
;             PG8_WAIT_V(8); PG8_WAIT_L(0); PG8_BAR; PG8_MMA(1, 0, At, B0); PG8_MMA(1, 1, At, B1); PG8_BAR; PG8_SCHED;
;             PG8_LDB(B0, 1, 0); PG8_LDB(B1, 1, 1); PG8_SCHED; PG8_LDA(At, 1, 0); PG8_STAGE(PG8_SA(0, 1), a2 + hstepA, voffA);
;             PG8_WAIT_V(8); PG8_WAIT_L(0); PG8_BAR; PG8_MMA(0, 0, At, B0); PG8_MMA(0, 1, At, B1); PG8_BAR; PG8_SCHED;
	s_setprio 1
	s_waitcnt lgkmcnt(0)
	v_mfma_f32_16x16x32_bf16 v[60:63], v[164:167], v[196:199], v[60:63]
	v_mfma_f32_16x16x32_bf16 v[56:59], v[172:175], v[196:199], v[56:59]
	v_mfma_f32_16x16x32_bf16 v[44:47], v[164:167], v[204:207], v[44:47]
	v_mfma_f32_16x16x32_bf16 v[40:43], v[172:175], v[204:207], v[40:43]
	v_mfma_f32_16x16x32_bf16 v[28:31], v[164:167], v[212:215], v[28:31]
	v_mfma_f32_16x16x32_bf16 v[24:27], v[172:175], v[212:215], v[24:27]
	v_mfma_f32_16x16x32_bf16 v[12:15], v[164:167], v[228:231], v[12:15]
	v_mfma_f32_16x16x32_bf16 v[8:11], v[172:175], v[228:231], v[8:11]
	v_mfma_f32_16x16x32_bf16 v[60:63], v[168:171], v[200:203], v[60:63]
	v_mfma_f32_16x16x32_bf16 v[56:59], v[176:179], v[200:203], v[56:59]
	v_mfma_f32_16x16x32_bf16 v[44:47], v[168:171], v[208:211], v[44:47]
	v_mfma_f32_16x16x32_bf16 v[40:43], v[176:179], v[208:211], v[40:43]
	v_mfma_f32_16x16x32_bf16 v[28:31], v[168:171], v[216:219], v[28:31]
	v_mfma_f32_16x16x32_bf16 v[24:27], v[176:179], v[216:219], v[24:27]
	v_mfma_f32_16x16x32_bf16 v[12:15], v[168:171], v[232:235], v[12:15]
	v_mfma_f32_16x16x32_bf16 v[8:11], v[176:179], v[232:235], v[8:11]
	v_mfma_f32_16x16x32_bf16 v[52:55], v[180:183], v[196:199], v[52:55]
	v_mfma_f32_16x16x32_bf16 v[48:51], v[188:191], v[196:199], v[48:51]
	v_mfma_f32_16x16x32_bf16 v[36:39], v[180:183], v[204:207], v[36:39]
	v_mfma_f32_16x16x32_bf16 v[32:35], v[188:191], v[204:207], v[32:35]
	v_mfma_f32_16x16x32_bf16 v[20:23], v[180:183], v[212:215], v[20:23]
	v_mfma_f32_16x16x32_bf16 v[16:19], v[188:191], v[212:215], v[16:19]
	v_mfma_f32_16x16x32_bf16 v[4:7], v[180:183], v[228:231], v[4:7]
	v_mfma_f32_16x16x32_bf16 v[0:3], v[188:191], v[228:231], v[0:3]
	v_mfma_f32_16x16x32_bf16 v[52:55], v[184:187], v[200:203], v[52:55]
	v_mfma_f32_16x16x32_bf16 v[48:51], v[192:195], v[200:203], v[48:51]
	v_mfma_f32_16x16x32_bf16 v[36:39], v[184:187], v[208:211], v[36:39]
	v_mfma_f32_16x16x32_bf16 v[32:35], v[192:195], v[208:211], v[32:35]
	v_mfma_f32_16x16x32_bf16 v[20:23], v[184:187], v[216:219], v[20:23]
	v_mfma_f32_16x16x32_bf16 v[16:19], v[192:195], v[216:219], v[16:19]
	v_mfma_f32_16x16x32_bf16 v[4:7], v[184:187], v[232:235], v[4:7]
	v_mfma_f32_16x16x32_bf16 v[0:3], v[192:195], v[232:235], v[0:3]
	s_setprio 0
	s_barrier
	s_add_i32 s53, 0, 0x18000
	v_add_u32_e32 v146, s53, v161
	s_add_i32 s54, 0, 0x1c000
	ds_read_b128 v[164:167], v146
	ds_read_b128 v[168:171], v146 offset:1024
	ds_read_b128 v[172:175], v146 offset:2048
	ds_read_b128 v[176:179], v146 offset:3072
	v_add_u32_e32 v146, s54, v161
	ds_read_b128 v[180:183], v146
	ds_read_b128 v[184:187], v146 offset:1024
	ds_read_b128 v[188:191], v146 offset:2048
	ds_read_b128 v[192:195], v146 offset:3072
	s_add_u32 s26, s26, 0x40000
	s_addc_u32 s27, s27, 0
	s_mov_b32 m0, s38
	v_lshl_add_u64 v[246:247], s[26:27], 0, v[128:129]
	ds_read_b128 v[196:199], v163 offset:32768
	ds_read_b128 v[200:203], v163 offset:33792
	ds_read_b128 v[204:207], v163 offset:34816
	ds_read_b128 v[208:211], v163 offset:35840
	ds_read_b128 v[212:215], v163 offset:36864
	ds_read_b128 v[216:219], v163 offset:37888
	ds_read_b128 v[228:231], v163 offset:38912
	ds_read_b128 v[232:235], v163 offset:39936
	global_load_lds_dwordx4 v[246:247], off
	v_lshl_add_u64 v[246:247], s[26:27], 0, v[132:133]
	s_mov_b32 m0, s39
	s_nop 0
	global_load_lds_dwordx4 v[246:247], off
	s_waitcnt vmcnt(8)
	s_waitcnt lgkmcnt(0)
	s_barrier
	s_setprio 1
	s_waitcnt lgkmcnt(0)
	v_mfma_f32_16x16x32_bf16 v[124:127], v[164:167], v[196:199], v[124:127]
	v_mfma_f32_16x16x32_bf16 v[120:123], v[172:175], v[196:199], v[120:123]
	v_mfma_f32_16x16x32_bf16 v[108:111], v[164:167], v[204:207], v[108:111]
	v_mfma_f32_16x16x32_bf16 v[104:107], v[172:175], v[204:207], v[104:107]
	v_mfma_f32_16x16x32_bf16 v[92:95], v[164:167], v[212:215], v[92:95]
	v_mfma_f32_16x16x32_bf16 v[88:91], v[172:175], v[212:215], v[88:91]
	v_mfma_f32_16x16x32_bf16 v[76:79], v[164:167], v[228:231], v[76:79]
	v_mfma_f32_16x16x32_bf16 v[72:75], v[172:175], v[228:231], v[72:75]
	v_mfma_f32_16x16x32_bf16 v[124:127], v[168:171], v[200:203], v[124:127]
	v_mfma_f32_16x16x32_bf16 v[120:123], v[176:179], v[200:203], v[120:123]
	v_mfma_f32_16x16x32_bf16 v[108:111], v[168:171], v[208:211], v[108:111]
	v_mfma_f32_16x16x32_bf16 v[104:107], v[176:179], v[208:211], v[104:107]
	v_mfma_f32_16x16x32_bf16 v[92:95], v[168:171], v[216:219], v[92:95]
	v_mfma_f32_16x16x32_bf16 v[88:91], v[176:179], v[216:219], v[88:91]
	v_mfma_f32_16x16x32_bf16 v[76:79], v[168:171], v[232:235], v[76:79]
	v_mfma_f32_16x16x32_bf16 v[72:75], v[176:179], v[232:235], v[72:75]
	v_mfma_f32_16x16x32_bf16 v[116:119], v[180:183], v[196:199], v[116:119]
	v_mfma_f32_16x16x32_bf16 v[112:115], v[188:191], v[196:199], v[112:115]
	v_mfma_f32_16x16x32_bf16 v[100:103], v[180:183], v[204:207], v[100:103]
	v_mfma_f32_16x16x32_bf16 v[96:99], v[188:191], v[204:207], v[96:99]
	v_mfma_f32_16x16x32_bf16 v[84:87], v[180:183], v[212:215], v[84:87]
	v_mfma_f32_16x16x32_bf16 v[80:83], v[188:191], v[212:215], v[80:83]
	v_mfma_f32_16x16x32_bf16 v[68:71], v[180:183], v[228:231], v[68:71]
	v_mfma_f32_16x16x32_bf16 v[64:67], v[188:191], v[228:231], v[64:67]
	v_mfma_f32_16x16x32_bf16 v[116:119], v[184:187], v[200:203], v[116:119]
	v_mfma_f32_16x16x32_bf16 v[112:115], v[192:195], v[200:203], v[112:115]
	v_mfma_f32_16x16x32_bf16 v[100:103], v[184:187], v[208:211], v[100:103]
	v_mfma_f32_16x16x32_bf16 v[96:99], v[192:195], v[208:211], v[96:99]
	v_mfma_f32_16x16x32_bf16 v[84:87], v[184:187], v[216:219], v[84:87]
	v_mfma_f32_16x16x32_bf16 v[80:83], v[192:195], v[216:219], v[80:83]
	v_mfma_f32_16x16x32_bf16 v[68:71], v[184:187], v[232:235], v[68:71]
	v_mfma_f32_16x16x32_bf16 v[64:67], v[192:195], v[232:235], v[64:67]
	s_setprio 0
	s_barrier
; #define PG8_STAGE(bufoff, gbase, voff) do { _Pragma("unroll") for (int _i = 0; _i < 2; ++_i) \
;         __builtin_amdgcn_global_load_lds((const unsigned*)((const char*)(gbase) + (voff)[_i]), (LAS unsigned*)(lds + (bufoff) + ldsw + _i * 8192), 16, 0, 0); } while (0)
; #define PG8_LDA(dst, b, h) do { _Pragma("unroll") for (int m = 0; m < 4; ++m) _Pragma("unroll") for (int k = 0; k < 2; ++k) dst[m][k] = *(const LAS bf16x8*)(lds + PG8_SA(b, h) + aoff + m * 2048 + k * 1024); } while (0)
; #define PG8_MMA(ai, bj, At, Bt) do { __builtin_amdgcn_s_setprio(1); _Pragma("unroll") for (int m = 0; m < 4; ++m) _Pragma("unroll") for (int n = 0; n < 2; ++n) _Pragma("unroll") for (int k = 0; k < 2; ++k) \
;         acc[ai][bj][m][n] = __builtin_amdgcn_mfma_f32_16x16x32_bf16(Bt[n][k], At[m][k], acc[ai][bj][m][n], 0, 0, 0); __builtin_amdgcn_s_setprio(0); } while (0)
; #define PG8_WAIT_V(n) asm volatile("s_waitcnt vmcnt(" #n ")" ::: "memory")
; #define PG8_WAIT_L(n) asm volatile("s_waitcnt lgkmcnt(" #n ")" ::: "memory")
; #define PG8_BAR __builtin_amdgcn_s_barrier()
; #define PG8_SCHED __builtin_amdgcn_sched_barrier(0)
;     ...
;         for (int t = 0; t < nt; t += 2) {
;             const bool last = (t == nt - 2);
;             const char* a1 = cA + (size_t)(t + 1) * kstep;
;             const char* a2 = last ? nA : cA + (size_t)(t + 2) * kstep; const char* b2 = last ? nB : cB + (size_t)(t + 2) * kstep;
;     ...
;             PG8_LDA(At, 1, 1); PG8_STAGE(PG8_SB(1, 0), b3, voffB); PG8_STAGE(PG8_SB(1, 1), b3 + hstepB, voffB); PG8_STAGE(PG8_SA(1, 0), a3, voffA);
;             PG8_WAIT_V(8); PG8_WAIT_L(0); PG8_BAR; PG8_MMA(1, 0, At, B0); PG8_MMA(1, 1, At, B1); PG8_BAR; PG8_SCHED;
	s_add_i32 s26, s53, s35
	v_lshl_add_u64 v[158:159], v[158:159], 0, s[58:59]
	s_mov_b32 m0, s26
	ds_read_b128 v[196:199], v163 offset:49152
	ds_read_b128 v[200:203], v163 offset:50176
	ds_read_b128 v[204:207], v163 offset:51200
	ds_read_b128 v[208:211], v163 offset:52224
	ds_read_b128 v[212:215], v163 offset:53248
	ds_read_b128 v[216:219], v163 offset:54272
	ds_read_b128 v[228:231], v163 offset:55296
	ds_read_b128 v[232:235], v163 offset:56320
	global_load_lds_dwordx4 v[158:159], off
	v_lshl_add_u64 v[158:159], v[236:237], 0, s[58:59]
	s_add_i32 m0, s26, 0x2000
	s_add_i32 s26, s54, s35
	global_load_lds_dwordx4 v[158:159], off
	v_lshl_add_u64 v[158:159], v[238:239], 0, s[58:59]
	s_mov_b32 m0, s26
	s_nop 0
	global_load_lds_dwordx4 v[158:159], off
	v_lshl_add_u64 v[158:159], v[240:241], 0, s[58:59]
	s_add_i32 m0, s26, 0x2000
	s_nop 0
	global_load_lds_dwordx4 v[158:159], off
	v_lshl_add_u64 v[158:159], v[242:243], 0, s[58:59]
	s_mov_b32 m0, s40
	s_nop 0
	global_load_lds_dwordx4 v[158:159], off
	v_lshl_add_u64 v[158:159], v[244:245], 0, s[58:59]
	s_mov_b32 m0, s41
	s_nop 0
	global_load_lds_dwordx4 v[158:159], off
	s_waitcnt vmcnt(8)
	s_waitcnt lgkmcnt(0)
	s_barrier
	s_setprio 1
	s_waitcnt lgkmcnt(0)
	v_mfma_f32_16x16x32_bf16 v[60:63], v[164:167], v[196:199], v[60:63]
	v_mfma_f32_16x16x32_bf16 v[56:59], v[172:175], v[196:199], v[56:59]
	v_mfma_f32_16x16x32_bf16 v[44:47], v[164:167], v[204:207], v[44:47]
	v_mfma_f32_16x16x32_bf16 v[40:43], v[172:175], v[204:207], v[40:43]
	v_mfma_f32_16x16x32_bf16 v[28:31], v[164:167], v[212:215], v[28:31]
	v_mfma_f32_16x16x32_bf16 v[24:27], v[172:175], v[212:215], v[24:27]
	v_mfma_f32_16x16x32_bf16 v[12:15], v[164:167], v[228:231], v[12:15]
	v_mfma_f32_16x16x32_bf16 v[8:11], v[172:175], v[228:231], v[8:11]
	v_mfma_f32_16x16x32_bf16 v[60:63], v[168:171], v[200:203], v[60:63]
	v_mfma_f32_16x16x32_bf16 v[56:59], v[176:179], v[200:203], v[56:59]
	v_mfma_f32_16x16x32_bf16 v[44:47], v[168:171], v[208:211], v[44:47]
	v_mfma_f32_16x16x32_bf16 v[40:43], v[176:179], v[208:211], v[40:43]
	v_mfma_f32_16x16x32_bf16 v[28:31], v[168:171], v[216:219], v[28:31]
	v_mfma_f32_16x16x32_bf16 v[24:27], v[176:179], v[216:219], v[24:27]
	v_mfma_f32_16x16x32_bf16 v[12:15], v[168:171], v[232:235], v[12:15]
	v_mfma_f32_16x16x32_bf16 v[8:11], v[176:179], v[232:235], v[8:11]
	v_mfma_f32_16x16x32_bf16 v[52:55], v[180:183], v[196:199], v[52:55]
	v_mfma_f32_16x16x32_bf16 v[48:51], v[188:191], v[196:199], v[48:51]
	v_mfma_f32_16x16x32_bf16 v[36:39], v[180:183], v[204:207], v[36:39]
	v_mfma_f32_16x16x32_bf16 v[32:35], v[188:191], v[204:207], v[32:35]
	v_mfma_f32_16x16x32_bf16 v[20:23], v[180:183], v[212:215], v[20:23]
	v_mfma_f32_16x16x32_bf16 v[16:19], v[188:191], v[212:215], v[16:19]
	v_mfma_f32_16x16x32_bf16 v[4:7], v[180:183], v[228:231], v[4:7]
	v_mfma_f32_16x16x32_bf16 v[0:3], v[188:191], v[228:231], v[0:3]
	v_mfma_f32_16x16x32_bf16 v[52:55], v[184:187], v[200:203], v[52:55]
	v_mfma_f32_16x16x32_bf16 v[48:51], v[192:195], v[200:203], v[48:51]
	v_mfma_f32_16x16x32_bf16 v[36:39], v[184:187], v[208:211], v[36:39]
	v_mfma_f32_16x16x32_bf16 v[32:35], v[192:195], v[208:211], v[32:35]
	v_mfma_f32_16x16x32_bf16 v[20:23], v[184:187], v[216:219], v[20:23]
	v_mfma_f32_16x16x32_bf16 v[16:19], v[192:195], v[216:219], v[16:19]
	v_mfma_f32_16x16x32_bf16 v[4:7], v[184:187], v[232:235], v[4:7]
	v_mfma_f32_16x16x32_bf16 v[0:3], v[192:195], v[232:235], v[0:3]
	s_setprio 0
	s_barrier
	s_add_u32 s12, s12, 0x100
	s_addc_u32 s13, s13, 0
	s_add_u32 s28, s28, 0x100
	s_addc_u32 s29, s29, 0
	s_cmp_ge_i32 s52, s42
	s_mov_b32 s26, s52
	s_cbranch_scc0 .LBB0_553
